# backedge-salu-in-mfma-shadow
# speedup vs baseline: 1.0102x; 1.0102x over previous
; #define PG8_STAGE(bufoff, gbase, voff) do { _Pragma("unroll") for (int _i = 0; _i < 2; ++_i) \
;         __builtin_amdgcn_global_load_lds((const unsigned*)((const char*)(gbase) + (voff)[_i]), (LAS unsigned*)(lds + (bufoff) + ldsw + _i * 8192), 16, 0, 0); } while (0)
; #define PG8_LDA(dst, b, h) do { _Pragma("unroll") for (int m = 0; m < 4; ++m) _Pragma("unroll") for (int k = 0; k < 2; ++k) dst[m][k] = *(const LAS bf16x8*)(lds + PG8_SA(b, h) + aoff + m * 2048 + k * 1024); } while (0)
; #define PG8_LDB(dst, b, h) do { _Pragma("unroll") for (int n = 0; n < 2; ++n) _Pragma("unroll") for (int k = 0; k < 2; ++k) dst[n][k] = *(const LAS bf16x8*)(lds + PG8_SB(b, h) + boff + n * 2048 + k * 1024); } while (0)
; #define PG8_MMA(ai, bj, At, Bt) do { __builtin_amdgcn_s_setprio(1); _Pragma("unroll") for (int m = 0; m < 4; ++m) _Pragma("unroll") for (int n = 0; n < 2; ++n) _Pragma("unroll") for (int k = 0; k < 2; ++k) \
;         acc[ai][bj][m][n] = __builtin_amdgcn_mfma_f32_16x16x32_bf16(Bt[n][k], At[m][k], acc[ai][bj][m][n], 0, 0, 0); __builtin_amdgcn_s_setprio(0); } while (0)
; #define PG8_WAIT_V(n) asm volatile("s_waitcnt vmcnt(" #n ")" ::: "memory")
; #define PG8_WAIT_L(n) asm volatile("s_waitcnt lgkmcnt(" #n ")" ::: "memory")
; template <class Epi, class Sched, bool ATILE = false>
; __device__ __forceinline__ void gemm_phase(LAS unsigned char* lds, const Gemm g, const Sched& S, const Epi& E) {
;     ...
;         for (int t = 0; t < nt; t += 2) {
;             const bool last = (t == nt - 2);
;             const char* a1 = cA + (size_t)(t + 1) * kstepA;
;             const char* a2 = last ? nA : cA + (size_t)(t + 2) * kstepA; const char* b2 = last ? nB : cB + (size_t)(t + 2) * kstep;
;             const char* a3 = a2 + kstepA; const char* b3 = b2 + kstep;
;             PG8_LDB(B0, 0, 0); PG8_SCHED; PG8_LDA(At, 0, 0); PG8_STAGE(PG8_SA(1, 1), a1 + hstepA, voffA);
;             PG8_WAIT_L(8); PG8_BAR; PG8_WAIT_L(0); PG8_MMA(0, 0, At, B0); PG8_BAR; PG8_SCHED;
;             PG8_LDB(B1, 0, 1); PG8_STAGE(PG8_SB(0, 0), b2, voffB);
;             PG8_BAR; PG8_WAIT_L(0); PG8_MMA(0, 1, At, B1); PG8_BAR;
;             PG8_LDA(At, 0, 1); PG8_STAGE(PG8_SA(0, 0), a2, voffA);
;             PG8_BAR; PG8_WAIT_L(0); PG8_MMA(1, 0, At, B0); PG8_BAR; PG8_SCHED;
;             PG8_STAGE(PG8_SB(0, 1), b2 + hstepB, voffB);
;             PG8_WAIT_V(6); PG8_BAR; PG8_MMA(1, 1, At, B1); PG8_BAR;
.LBB0_625:
	ds_read_b128 v[182:185], v139
	ds_read_b128 v[186:189], v139 offset:1024
	ds_read_b128 v[190:193], v139 offset:2048
	ds_read_b128 v[194:197], v139 offset:3072
	s_add_i32 s62, s28, 2
	s_add_u32 s29, s26, 0xfff80080
	s_addc_u32 s30, s27, -1
	s_cmp_eq_u32 s59, s28
	s_cselect_b32 s28, s58, s60
	s_cselect_b32 s31, s13, s30
	s_cselect_b32 s30, s56, s29
	s_cselect_b32 s29, s57, s61
	s_add_i32 m0, s35, 0xc000
	ds_read_b128 v[198:201], v163
	ds_read_b128 v[202:205], v163 offset:1024
	ds_read_b128 v[206:209], v163 offset:2048
	ds_read_b128 v[210:213], v163 offset:3072
	ds_read_b128 v[214:217], v163 offset:4096
	ds_read_b128 v[218:221], v163 offset:5120
	ds_read_b128 v[222:225], v163 offset:6144
	ds_read_b128 v[226:229], v163 offset:7168
	global_load_lds_dwordx4 v172, s[26:27]
	s_add_i32 m0, s35, 0xe000
	s_nop 0
	global_load_lds_dwordx4 v174, s[26:27]
	s_waitcnt lgkmcnt(8)
	s_setprio 1
	s_barrier
	s_waitcnt lgkmcnt(0)
	v_mfma_f32_16x16x32_bf16 v[120:123], v[182:185], v[198:201], v[120:123]
	v_mfma_f32_16x16x32_bf16 v[112:115], v[190:193], v[198:201], v[112:115]
	v_mfma_f32_16x16x32_bf16 v[104:107], v[182:185], v[206:209], v[104:107]
	v_mfma_f32_16x16x32_bf16 v[96:99], v[190:193], v[206:209], v[96:99]
	v_mfma_f32_16x16x32_bf16 v[88:91], v[182:185], v[214:217], v[88:91]
	v_mfma_f32_16x16x32_bf16 v[80:83], v[190:193], v[214:217], v[80:83]
	v_mfma_f32_16x16x32_bf16 v[72:75], v[182:185], v[222:225], v[72:75]
	v_mfma_f32_16x16x32_bf16 v[64:67], v[190:193], v[222:225], v[64:67]
	v_mfma_f32_16x16x32_bf16 v[120:123], v[186:189], v[202:205], v[120:123]
	v_mfma_f32_16x16x32_bf16 v[112:115], v[194:197], v[202:205], v[112:115]
	v_mfma_f32_16x16x32_bf16 v[104:107], v[186:189], v[210:213], v[104:107]
	v_mfma_f32_16x16x32_bf16 v[96:99], v[194:197], v[210:213], v[96:99]
	v_mfma_f32_16x16x32_bf16 v[88:91], v[186:189], v[218:221], v[88:91]
	v_mfma_f32_16x16x32_bf16 v[80:83], v[194:197], v[218:221], v[80:83]
	v_mfma_f32_16x16x32_bf16 v[72:75], v[186:189], v[226:229], v[72:75]
	v_mfma_f32_16x16x32_bf16 v[64:67], v[194:197], v[226:229], v[64:67]
	s_barrier
	s_setprio 0
	s_add_i32 s63, s53, s34
	s_add_u32 s98, s28, s0
	s_addc_u32 s99, s29, s1
	s_mov_b32 m0, s63
	ds_read_b128 v[230:233], v167
	ds_read_b128 v[234:237], v167 offset:1024
	ds_read_b128 v[238:241], v167 offset:2048
	ds_read_b128 v[242:245], v167 offset:3072
	global_load_lds_dwordx4 v130, s[28:29]
	s_add_i32 m0, s63, 0x2000
	s_nop 0
	global_load_lds_dwordx4 v134, s[28:29]
	s_setprio 1
	s_barrier
	s_waitcnt lgkmcnt(0)
	v_mfma_f32_16x16x32_bf16 v[124:127], v[230:233], v[198:201], v[124:127]
	v_mfma_f32_16x16x32_bf16 v[116:119], v[238:241], v[198:201], v[116:119]
	v_mfma_f32_16x16x32_bf16 v[108:111], v[230:233], v[206:209], v[108:111]
	v_mfma_f32_16x16x32_bf16 v[100:103], v[238:241], v[206:209], v[100:103]
	v_mfma_f32_16x16x32_bf16 v[92:95], v[230:233], v[214:217], v[92:95]
	v_mfma_f32_16x16x32_bf16 v[84:87], v[238:241], v[214:217], v[84:87]
	v_mfma_f32_16x16x32_bf16 v[76:79], v[230:233], v[222:225], v[76:79]
	v_mfma_f32_16x16x32_bf16 v[68:71], v[238:241], v[222:225], v[68:71]
	v_mfma_f32_16x16x32_bf16 v[124:127], v[234:237], v[202:205], v[124:127]
	v_mfma_f32_16x16x32_bf16 v[116:119], v[242:245], v[202:205], v[116:119]
	v_mfma_f32_16x16x32_bf16 v[108:111], v[234:237], v[210:213], v[108:111]
	v_mfma_f32_16x16x32_bf16 v[100:103], v[242:245], v[210:213], v[100:103]
	v_mfma_f32_16x16x32_bf16 v[92:95], v[234:237], v[218:221], v[92:95]
	v_mfma_f32_16x16x32_bf16 v[84:87], v[242:245], v[218:221], v[84:87]
	v_mfma_f32_16x16x32_bf16 v[76:79], v[234:237], v[226:229], v[76:79]
	v_mfma_f32_16x16x32_bf16 v[68:71], v[242:245], v[226:229], v[68:71]
	s_barrier
	s_setprio 0
	s_mov_b32 m0, s35
	s_add_u32 s100, s30, s0
	s_addc_u32 s101, s31, s1
	ds_read_b128 v[198:201], v163 offset:16384
	ds_read_b128 v[202:205], v163 offset:17408
	ds_read_b128 v[206:209], v163 offset:18432
	ds_read_b128 v[210:213], v163 offset:19456
	ds_read_b128 v[214:217], v163 offset:20480
	ds_read_b128 v[218:221], v163 offset:21504
	ds_read_b128 v[222:225], v163 offset:22528
	ds_read_b128 v[226:229], v163 offset:23552
	global_load_lds_dwordx4 v128, s[30:31]
	s_mov_b32 m0, s36
	s_nop 0
	global_load_lds_dwordx4 v132, s[30:31]
	s_setprio 1
	s_barrier
	s_waitcnt lgkmcnt(0)
	v_mfma_f32_16x16x32_bf16 v[56:59], v[182:185], v[198:201], v[56:59]
	v_mfma_f32_16x16x32_bf16 v[48:51], v[190:193], v[198:201], v[48:51]
	v_mfma_f32_16x16x32_bf16 v[40:43], v[182:185], v[206:209], v[40:43]
	v_mfma_f32_16x16x32_bf16 v[32:35], v[190:193], v[206:209], v[32:35]
	v_mfma_f32_16x16x32_bf16 v[24:27], v[182:185], v[214:217], v[24:27]
	v_mfma_f32_16x16x32_bf16 v[16:19], v[190:193], v[214:217], v[16:19]
	v_mfma_f32_16x16x32_bf16 v[8:11], v[182:185], v[222:225], v[8:11]
	v_mfma_f32_16x16x32_bf16 v[4:7], v[190:193], v[222:225], v[4:7]
	v_mfma_f32_16x16x32_bf16 v[56:59], v[186:189], v[202:205], v[56:59]
	v_mfma_f32_16x16x32_bf16 v[48:51], v[194:197], v[202:205], v[48:51]
	v_mfma_f32_16x16x32_bf16 v[40:43], v[186:189], v[210:213], v[40:43]
	v_mfma_f32_16x16x32_bf16 v[32:35], v[194:197], v[210:213], v[32:35]
	v_mfma_f32_16x16x32_bf16 v[24:27], v[186:189], v[218:221], v[24:27]
	v_mfma_f32_16x16x32_bf16 v[16:19], v[194:197], v[218:221], v[16:19]
	v_mfma_f32_16x16x32_bf16 v[8:11], v[186:189], v[226:229], v[8:11]
	v_mfma_f32_16x16x32_bf16 v[4:7], v[194:197], v[226:229], v[4:7]
	s_barrier
	s_setprio 0
	s_add_u32 s64, s28, 0x80000
	s_addc_u32 s65, s29, 0
	s_add_i32 s63, s54, s34
	s_mov_b32 m0, s63
	s_nop 0
	global_load_lds_dwordx4 v130, s[64:65]
	s_add_i32 m0, s63, 0x2000
	s_nop 0
	global_load_lds_dwordx4 v134, s[64:65]
	s_waitcnt vmcnt(6)
	s_setprio 1
	s_barrier
; #define PG8_STAGE(bufoff, gbase, voff) do { _Pragma("unroll") for (int _i = 0; _i < 2; ++_i) \
;         __builtin_amdgcn_global_load_lds((const unsigned*)((const char*)(gbase) + (voff)[_i]), (LAS unsigned*)(lds + (bufoff) + ldsw + _i * 8192), 16, 0, 0); } while (0)
; #define PG8_LDA(dst, b, h) do { _Pragma("unroll") for (int m = 0; m < 4; ++m) _Pragma("unroll") for (int k = 0; k < 2; ++k) dst[m][k] = *(const LAS bf16x8*)(lds + PG8_SA(b, h) + aoff + m * 2048 + k * 1024); } while (0)
; #define PG8_LDB(dst, b, h) do { _Pragma("unroll") for (int n = 0; n < 2; ++n) _Pragma("unroll") for (int k = 0; k < 2; ++k) dst[n][k] = *(const LAS bf16x8*)(lds + PG8_SB(b, h) + boff + n * 2048 + k * 1024); } while (0)
; #define PG8_MMA(ai, bj, At, Bt) do { __builtin_amdgcn_s_setprio(1); _Pragma("unroll") for (int m = 0; m < 4; ++m) _Pragma("unroll") for (int n = 0; n < 2; ++n) _Pragma("unroll") for (int k = 0; k < 2; ++k) \
;         acc[ai][bj][m][n] = __builtin_amdgcn_mfma_f32_16x16x32_bf16(Bt[n][k], At[m][k], acc[ai][bj][m][n], 0, 0, 0); __builtin_amdgcn_s_setprio(0); } while (0)
; #define PG8_WAIT_V(n) asm volatile("s_waitcnt vmcnt(" #n ")" ::: "memory")
; #define PG8_WAIT_L(n) asm volatile("s_waitcnt lgkmcnt(" #n ")" ::: "memory")
; #define PG8_BAR __builtin_amdgcn_s_barrier()
; #define PG8_SCHED __builtin_amdgcn_sched_barrier(0)
; template <class Epi, class Sched, bool ATILE = false>
; __device__ __forceinline__ void gemm_phase(LAS unsigned char* lds, const Gemm g, const Sched& S, const Epi& E) {
;     ...
;             PG8_WAIT_V(6); PG8_BAR; PG8_MMA(1, 1, At, B1); PG8_BAR;
;             PG8_LDB(B0, 1, 0); PG8_SCHED; PG8_LDA(At, 1, 0); PG8_STAGE(PG8_SA(0, 1), a2 + hstepA, voffA);
;             PG8_WAIT_L(8); PG8_BAR; PG8_WAIT_L(0); PG8_MMA(0, 0, At, B0); PG8_BAR; PG8_SCHED;
;             PG8_LDB(B1, 1, 1); PG8_STAGE(PG8_SB(1, 0), b3, voffB);
;             PG8_BAR; PG8_WAIT_L(0); PG8_MMA(0, 1, At, B1); PG8_BAR;
	v_mfma_f32_16x16x32_bf16 v[60:63], v[230:233], v[198:201], v[60:63]
	v_mfma_f32_16x16x32_bf16 v[52:55], v[238:241], v[198:201], v[52:55]
	v_mfma_f32_16x16x32_bf16 v[44:47], v[230:233], v[206:209], v[44:47]
	v_mfma_f32_16x16x32_bf16 v[36:39], v[238:241], v[206:209], v[36:39]
	v_mfma_f32_16x16x32_bf16 v[28:31], v[230:233], v[214:217], v[28:31]
	v_mfma_f32_16x16x32_bf16 v[20:23], v[238:241], v[214:217], v[20:23]
	v_mfma_f32_16x16x32_bf16 v[12:15], v[230:233], v[222:225], v[12:15]
	v_mfma_f32_16x16x32_bf16 v[0:3], v[238:241], v[222:225], v[0:3]
	v_mfma_f32_16x16x32_bf16 v[60:63], v[234:237], v[202:205], v[60:63]
	v_mfma_f32_16x16x32_bf16 v[52:55], v[242:245], v[202:205], v[52:55]
	v_mfma_f32_16x16x32_bf16 v[44:47], v[234:237], v[210:213], v[44:47]
	v_mfma_f32_16x16x32_bf16 v[36:39], v[242:245], v[210:213], v[36:39]
	v_mfma_f32_16x16x32_bf16 v[28:31], v[234:237], v[218:221], v[28:31]
	v_mfma_f32_16x16x32_bf16 v[20:23], v[242:245], v[218:221], v[20:23]
	v_mfma_f32_16x16x32_bf16 v[12:15], v[234:237], v[226:229], v[12:15]
	v_mfma_f32_16x16x32_bf16 v[0:3], v[242:245], v[226:229], v[0:3]
	s_barrier
	s_setprio 0
	s_add_i32 s63, 0, 0x18000
	v_add_u32_e32 v176, s63, v161
	ds_read_b128 v[182:185], v176
	ds_read_b128 v[186:189], v176 offset:1024
	ds_read_b128 v[190:193], v176 offset:2048
	ds_read_b128 v[194:197], v176 offset:3072
	s_add_u32 s30, s30, 0x80000
	s_addc_u32 s31, s31, 0
	s_mov_b32 m0, s37
	ds_read_b128 v[198:201], v163 offset:32768
	ds_read_b128 v[202:205], v163 offset:33792
	ds_read_b128 v[206:209], v163 offset:34816
	ds_read_b128 v[210:213], v163 offset:35840
	ds_read_b128 v[214:217], v163 offset:36864
	ds_read_b128 v[218:221], v163 offset:37888
	ds_read_b128 v[222:225], v163 offset:38912
	ds_read_b128 v[226:229], v163 offset:39936
	global_load_lds_dwordx4 v128, s[30:31]
	s_mov_b32 m0, s38
	s_nop 0
	global_load_lds_dwordx4 v132, s[30:31]
	s_waitcnt lgkmcnt(8)
	s_setprio 1
	s_barrier
	s_waitcnt lgkmcnt(0)
	v_mfma_f32_16x16x32_bf16 v[120:123], v[182:185], v[198:201], v[120:123]
	v_mfma_f32_16x16x32_bf16 v[112:115], v[190:193], v[198:201], v[112:115]
	v_mfma_f32_16x16x32_bf16 v[104:107], v[182:185], v[206:209], v[104:107]
	v_mfma_f32_16x16x32_bf16 v[96:99], v[190:193], v[206:209], v[96:99]
	v_mfma_f32_16x16x32_bf16 v[88:91], v[182:185], v[214:217], v[88:91]
	v_mfma_f32_16x16x32_bf16 v[80:83], v[190:193], v[214:217], v[80:83]
	v_mfma_f32_16x16x32_bf16 v[72:75], v[182:185], v[222:225], v[72:75]
	v_mfma_f32_16x16x32_bf16 v[64:67], v[190:193], v[222:225], v[64:67]
	v_mfma_f32_16x16x32_bf16 v[120:123], v[186:189], v[202:205], v[120:123]
	v_mfma_f32_16x16x32_bf16 v[112:115], v[194:197], v[202:205], v[112:115]
	v_mfma_f32_16x16x32_bf16 v[104:107], v[186:189], v[210:213], v[104:107]
	v_mfma_f32_16x16x32_bf16 v[96:99], v[194:197], v[210:213], v[96:99]
	v_mfma_f32_16x16x32_bf16 v[88:91], v[186:189], v[218:221], v[88:91]
	v_mfma_f32_16x16x32_bf16 v[80:83], v[194:197], v[218:221], v[80:83]
	v_mfma_f32_16x16x32_bf16 v[72:75], v[186:189], v[226:229], v[72:75]
	v_mfma_f32_16x16x32_bf16 v[64:67], v[194:197], v[226:229], v[64:67]
	s_barrier
	s_setprio 0
	s_add_i32 s30, 0, 0x1c000
	s_add_i32 s31, s63, s34
	v_add_u32_e32 v176, s30, v161
	s_mov_b32 m0, s31
	ds_read_b128 v[230:233], v176
	ds_read_b128 v[234:237], v176 offset:1024
	ds_read_b128 v[238:241], v176 offset:2048
	ds_read_b128 v[242:245], v176 offset:3072
	global_load_lds_dwordx4 v130, s[98:99]
	s_add_i32 m0, s31, 0x2000
	s_nop 0
	global_load_lds_dwordx4 v134, s[98:99]
	s_setprio 1
	s_barrier
; #define PG8_STAGE(bufoff, gbase, voff) do { _Pragma("unroll") for (int _i = 0; _i < 2; ++_i) \
;         __builtin_amdgcn_global_load_lds((const unsigned*)((const char*)(gbase) + (voff)[_i]), (LAS unsigned*)(lds + (bufoff) + ldsw + _i * 8192), 16, 0, 0); } while (0)
; #define PG8_LDA(dst, b, h) do { _Pragma("unroll") for (int m = 0; m < 4; ++m) _Pragma("unroll") for (int k = 0; k < 2; ++k) dst[m][k] = *(const LAS bf16x8*)(lds + PG8_SA(b, h) + aoff + m * 2048 + k * 1024); } while (0)
; #define PG8_MMA(ai, bj, At, Bt) do { __builtin_amdgcn_s_setprio(1); _Pragma("unroll") for (int m = 0; m < 4; ++m) _Pragma("unroll") for (int n = 0; n < 2; ++n) _Pragma("unroll") for (int k = 0; k < 2; ++k) \
;         acc[ai][bj][m][n] = __builtin_amdgcn_mfma_f32_16x16x32_bf16(Bt[n][k], At[m][k], acc[ai][bj][m][n], 0, 0, 0); __builtin_amdgcn_s_setprio(0); } while (0)
; #define PG8_WAIT_V(n) asm volatile("s_waitcnt vmcnt(" #n ")" ::: "memory")
; #define PG8_WAIT_L(n) asm volatile("s_waitcnt lgkmcnt(" #n ")" ::: "memory")
; #define PG8_BAR __builtin_amdgcn_s_barrier()
; #define PG8_SCHED __builtin_amdgcn_sched_barrier(0)
; template <class Epi, class Sched, bool ATILE = false>
; __device__ __forceinline__ void gemm_phase(LAS unsigned char* lds, const Gemm g, const Sched& S, const Epi& E) {
;     ...
;             PG8_BAR; PG8_WAIT_L(0); PG8_MMA(0, 1, At, B1); PG8_BAR;
;             PG8_LDA(At, 1, 1); PG8_STAGE(PG8_SA(1, 0), a3, voffA);
;             PG8_BAR; PG8_WAIT_L(0); PG8_MMA(1, 0, At, B0); PG8_BAR; PG8_SCHED;
;             PG8_STAGE(PG8_SB(1, 1), b3 + hstepB, voffB);
;             PG8_WAIT_V(6); PG8_BAR; PG8_MMA(1, 1, At, B1); PG8_BAR;
;         }
	s_waitcnt lgkmcnt(0)
	v_mfma_f32_16x16x32_bf16 v[124:127], v[230:233], v[198:201], v[124:127]
	v_mfma_f32_16x16x32_bf16 v[116:119], v[238:241], v[198:201], v[116:119]
	v_mfma_f32_16x16x32_bf16 v[108:111], v[230:233], v[206:209], v[108:111]
	v_mfma_f32_16x16x32_bf16 v[100:103], v[238:241], v[206:209], v[100:103]
	v_mfma_f32_16x16x32_bf16 v[92:95], v[230:233], v[214:217], v[92:95]
	v_mfma_f32_16x16x32_bf16 v[84:87], v[238:241], v[214:217], v[84:87]
	v_mfma_f32_16x16x32_bf16 v[76:79], v[230:233], v[222:225], v[76:79]
	v_mfma_f32_16x16x32_bf16 v[68:71], v[238:241], v[222:225], v[68:71]
	v_mfma_f32_16x16x32_bf16 v[124:127], v[234:237], v[202:205], v[124:127]
	v_mfma_f32_16x16x32_bf16 v[116:119], v[242:245], v[202:205], v[116:119]
	v_mfma_f32_16x16x32_bf16 v[108:111], v[234:237], v[210:213], v[108:111]
	v_mfma_f32_16x16x32_bf16 v[100:103], v[242:245], v[210:213], v[100:103]
	v_mfma_f32_16x16x32_bf16 v[92:95], v[234:237], v[218:221], v[92:95]
	v_mfma_f32_16x16x32_bf16 v[84:87], v[242:245], v[218:221], v[84:87]
	v_mfma_f32_16x16x32_bf16 v[76:79], v[234:237], v[226:229], v[76:79]
	v_mfma_f32_16x16x32_bf16 v[68:71], v[242:245], v[226:229], v[68:71]
	s_barrier
	s_setprio 0
	s_mov_b32 m0, s41
	ds_read_b128 v[198:201], v163 offset:49152
	ds_read_b128 v[202:205], v163 offset:50176
	ds_read_b128 v[206:209], v163 offset:51200
	ds_read_b128 v[210:213], v163 offset:52224
	ds_read_b128 v[214:217], v163 offset:53248
	ds_read_b128 v[218:221], v163 offset:54272
	ds_read_b128 v[222:225], v163 offset:55296
	ds_read_b128 v[226:229], v163 offset:56320
	global_load_lds_dwordx4 v128, s[100:101]
	s_mov_b32 m0, s42
	s_nop 0
	global_load_lds_dwordx4 v132, s[100:101]
	s_setprio 1
	s_barrier
	s_waitcnt lgkmcnt(0)
	v_mfma_f32_16x16x32_bf16 v[56:59], v[182:185], v[198:201], v[56:59]
	v_mfma_f32_16x16x32_bf16 v[48:51], v[190:193], v[198:201], v[48:51]
	v_mfma_f32_16x16x32_bf16 v[40:43], v[182:185], v[206:209], v[40:43]
	v_mfma_f32_16x16x32_bf16 v[32:35], v[190:193], v[206:209], v[32:35]
	v_mfma_f32_16x16x32_bf16 v[24:27], v[182:185], v[214:217], v[24:27]
	v_mfma_f32_16x16x32_bf16 v[16:19], v[190:193], v[214:217], v[16:19]
	v_mfma_f32_16x16x32_bf16 v[8:11], v[182:185], v[222:225], v[8:11]
	v_mfma_f32_16x16x32_bf16 v[4:7], v[190:193], v[222:225], v[4:7]
	v_mfma_f32_16x16x32_bf16 v[56:59], v[186:189], v[202:205], v[56:59]
	v_mfma_f32_16x16x32_bf16 v[48:51], v[194:197], v[202:205], v[48:51]
	v_mfma_f32_16x16x32_bf16 v[40:43], v[186:189], v[210:213], v[40:43]
	v_mfma_f32_16x16x32_bf16 v[32:35], v[194:197], v[210:213], v[32:35]
	v_mfma_f32_16x16x32_bf16 v[24:27], v[186:189], v[218:221], v[24:27]
	v_mfma_f32_16x16x32_bf16 v[16:19], v[194:197], v[218:221], v[16:19]
	v_mfma_f32_16x16x32_bf16 v[8:11], v[186:189], v[226:229], v[8:11]
	v_mfma_f32_16x16x32_bf16 v[4:7], v[194:197], v[226:229], v[4:7]
	s_barrier
	s_setprio 0
	s_add_u32 s28, s28, 0x80080
	s_addc_u32 s29, s29, 0
	s_add_i32 s30, s30, s34
	s_mov_b32 m0, s30
	s_nop 0
	global_load_lds_dwordx4 v130, s[28:29]
	s_add_i32 m0, s30, 0x2000
	s_nop 0
	global_load_lds_dwordx4 v134, s[28:29]
	s_waitcnt vmcnt(6)
	s_setprio 1
	s_barrier
	v_mfma_f32_16x16x32_bf16 v[60:63], v[230:233], v[198:201], v[60:63]
	v_mfma_f32_16x16x32_bf16 v[52:55], v[238:241], v[198:201], v[52:55]
	v_mfma_f32_16x16x32_bf16 v[44:47], v[230:233], v[206:209], v[44:47]
	v_mfma_f32_16x16x32_bf16 v[36:39], v[238:241], v[206:209], v[36:39]
	v_mfma_f32_16x16x32_bf16 v[28:31], v[230:233], v[214:217], v[28:31]
	v_mfma_f32_16x16x32_bf16 v[20:23], v[238:241], v[214:217], v[20:23]
	v_mfma_f32_16x16x32_bf16 v[12:15], v[230:233], v[222:225], v[12:15]
	s_add_u32 s26, s26, 0x100
	v_mfma_f32_16x16x32_bf16 v[0:3], v[238:241], v[222:225], v[0:3]
	s_addc_u32 s27, s27, 0
	v_mfma_f32_16x16x32_bf16 v[60:63], v[234:237], v[202:205], v[60:63]
	s_add_u32 s60, s60, 0x100
	v_mfma_f32_16x16x32_bf16 v[52:55], v[242:245], v[202:205], v[52:55]
	s_addc_u32 s61, s61, 0
	v_mfma_f32_16x16x32_bf16 v[44:47], v[234:237], v[210:213], v[44:47]
	s_cmp_ge_i32 s62, s11
	v_mfma_f32_16x16x32_bf16 v[36:39], v[242:245], v[210:213], v[36:39]
	s_mov_b32 s28, s62
	v_mfma_f32_16x16x32_bf16 v[28:31], v[234:237], v[218:221], v[28:31]
	v_mfma_f32_16x16x32_bf16 v[20:23], v[242:245], v[218:221], v[20:23]
	v_mfma_f32_16x16x32_bf16 v[12:15], v[234:237], v[226:229], v[12:15]
	v_mfma_f32_16x16x32_bf16 v[0:3], v[242:245], v[226:229], v[0:3]
	s_barrier
	s_setprio 0
	s_cbranch_scc0 .LBB0_625
	s_nop 5
	s_branch .LBB0_616

; #define PG8_STAGE(bufoff, gbase, voff) do { _Pragma("unroll") for (int _i = 0; _i < 2; ++_i) \
;         __builtin_amdgcn_global_load_lds((const unsigned*)((const char*)(gbase) + (voff)[_i]), (LAS unsigned*)(lds + (bufoff) + ldsw + _i * 8192), 16, 0, 0); } while (0)
; #define PG8_LDA(dst, b, h) do { _Pragma("unroll") for (int m = 0; m < 4; ++m) _Pragma("unroll") for (int k = 0; k < 2; ++k) dst[m][k] = *(const LAS bf16x8*)(lds + PG8_SA(b, h) + aoff + m * 2048 + k * 1024); } while (0)
; #define PG8_LDB(dst, b, h) do { _Pragma("unroll") for (int n = 0; n < 2; ++n) _Pragma("unroll") for (int k = 0; k < 2; ++k) dst[n][k] = *(const LAS bf16x8*)(lds + PG8_SB(b, h) + boff + n * 2048 + k * 1024); } while (0)
; #define PG8_MMA(ai, bj, At, Bt) do { __builtin_amdgcn_s_setprio(1); _Pragma("unroll") for (int m = 0; m < 4; ++m) _Pragma("unroll") for (int n = 0; n < 2; ++n) _Pragma("unroll") for (int k = 0; k < 2; ++k) \
;         acc[ai][bj][m][n] = __builtin_amdgcn_mfma_f32_16x16x32_bf16(Bt[n][k], At[m][k], acc[ai][bj][m][n], 0, 0, 0); __builtin_amdgcn_s_setprio(0); } while (0)
; #define PG8_WAIT_V(n) asm volatile("s_waitcnt vmcnt(" #n ")" ::: "memory")
; #define PG8_WAIT_L(n) asm volatile("s_waitcnt lgkmcnt(" #n ")" ::: "memory")
; template <class Epi, class Sched, bool ATILE = false>
; __device__ __forceinline__ void gemm_phase(LAS unsigned char* lds, const Gemm g, const Sched& S, const Epi& E) {
;     ...
;         for (int t = 0; t < nt; t += 2) {
;             const bool last = (t == nt - 2);
;             const char* a1 = cA + (size_t)(t + 1) * kstepA;
;             const char* a2 = last ? nA : cA + (size_t)(t + 2) * kstepA; const char* b2 = last ? nB : cB + (size_t)(t + 2) * kstep;
;             const char* a3 = a2 + kstepA; const char* b3 = b2 + kstep;
;             PG8_LDB(B0, 0, 0); PG8_SCHED; PG8_LDA(At, 0, 0); PG8_STAGE(PG8_SA(1, 1), a1 + hstepA, voffA);
;             PG8_WAIT_L(8); PG8_BAR; PG8_WAIT_L(0); PG8_MMA(0, 0, At, B0); PG8_BAR; PG8_SCHED;
;             PG8_LDB(B1, 0, 1); PG8_STAGE(PG8_SB(0, 0), b2, voffB);
;             PG8_BAR; PG8_WAIT_L(0); PG8_MMA(0, 1, At, B1); PG8_BAR;
;             PG8_LDA(At, 0, 1); PG8_STAGE(PG8_SA(0, 0), a2, voffA);
;             PG8_BAR; PG8_WAIT_L(0); PG8_MMA(1, 0, At, B0); PG8_BAR; PG8_SCHED;
;             PG8_STAGE(PG8_SB(0, 1), b2 + hstepB, voffB);
;             PG8_WAIT_V(6); PG8_BAR; PG8_MMA(1, 1, At, B1); PG8_BAR;
.LBB0_739:
	ds_read_b128 v[20:23], v165
	ds_read_b128 v[28:31], v165 offset:1024
	ds_read_b128 v[136:139], v165 offset:2048
	ds_read_b128 v[140:143], v165 offset:3072
	s_add_i32 s62, s26, 2
	s_add_u32 s27, s24, 0x4000
	s_addc_u32 s28, s25, 0
	s_cmp_eq_u32 s11, s26
	s_cselect_b32 s30, s20, s27
	s_cselect_b32 s31, s21, s28
	s_cselect_b32 s26, s22, s60
	s_cselect_b32 s27, s23, s61
	s_add_u32 s28, s30, 0x8000
	s_addc_u32 s29, s31, 0
	s_add_i32 m0, s34, 0xc000
	ds_read_b128 v[144:147], v167
	ds_read_b128 v[148:151], v167 offset:1024
	ds_read_b128 v[200:203], v167 offset:2048
	ds_read_b128 v[204:207], v167 offset:3072
	ds_read_b128 v[208:211], v167 offset:4096
	ds_read_b128 v[212:215], v167 offset:5120
	ds_read_b128 v[220:223], v167 offset:6144
	ds_read_b128 v[224:227], v167 offset:7168
	global_load_lds_dwordx4 v194, s[24:25]
	s_add_i32 m0, s34, 0xe000
	s_nop 0
	global_load_lds_dwordx4 v196, s[24:25]
	s_waitcnt lgkmcnt(8)
	s_setprio 1
	s_barrier
	s_waitcnt lgkmcnt(0)
	v_mfma_f32_16x16x32_bf16 v[0:3], v[20:23], v[144:147], v[0:3]
	v_mfma_f32_16x16x32_bf16 v[4:7], v[136:139], v[144:147], v[4:7]
	v_mfma_f32_16x16x32_bf16 v[44:47], v[20:23], v[200:203], v[44:47]
	v_mfma_f32_16x16x32_bf16 v[36:39], v[136:139], v[200:203], v[36:39]
	v_mfma_f32_16x16x32_bf16 v[52:55], v[20:23], v[208:211], v[52:55]
	v_mfma_f32_16x16x32_bf16 v[48:51], v[136:139], v[208:211], v[48:51]
	v_mfma_f32_16x16x32_bf16 v[92:95], v[20:23], v[220:223], v[92:95]
	v_mfma_f32_16x16x32_bf16 v[84:87], v[136:139], v[220:223], v[84:87]
	v_mfma_f32_16x16x32_bf16 v[0:3], v[28:31], v[148:151], v[0:3]
	v_mfma_f32_16x16x32_bf16 v[4:7], v[140:143], v[148:151], v[4:7]
	v_mfma_f32_16x16x32_bf16 v[44:47], v[28:31], v[204:207], v[44:47]
	v_mfma_f32_16x16x32_bf16 v[36:39], v[140:143], v[204:207], v[36:39]
	v_mfma_f32_16x16x32_bf16 v[52:55], v[28:31], v[212:215], v[52:55]
	v_mfma_f32_16x16x32_bf16 v[48:51], v[140:143], v[212:215], v[48:51]
	v_mfma_f32_16x16x32_bf16 v[92:95], v[28:31], v[224:227], v[92:95]
	v_mfma_f32_16x16x32_bf16 v[84:87], v[140:143], v[224:227], v[84:87]
	s_barrier
	s_setprio 0
	s_add_i32 s63, s52, s33
	s_add_u32 s98, s26, s6
	s_addc_u32 s99, s27, s7
	s_mov_b32 m0, s63
	ds_read_b128 v[228:231], v177
	ds_read_b128 v[232:235], v177 offset:1024
	ds_read_b128 v[236:239], v177 offset:2048
	ds_read_b128 v[240:243], v177 offset:3072
	global_load_lds_dwordx4 v170, s[26:27]
	s_add_i32 m0, s63, 0x2000
	s_nop 0
	global_load_lds_dwordx4 v174, s[26:27]
	s_setprio 1
	s_barrier
	s_waitcnt lgkmcnt(0)
	v_mfma_f32_16x16x32_bf16 v[12:15], v[228:231], v[144:147], v[12:15]
	v_mfma_f32_16x16x32_bf16 v[8:11], v[236:239], v[144:147], v[8:11]
	v_mfma_f32_16x16x32_bf16 v[24:27], v[228:231], v[200:203], v[24:27]
	v_mfma_f32_16x16x32_bf16 v[16:19], v[236:239], v[200:203], v[16:19]
	v_mfma_f32_16x16x32_bf16 v[40:43], v[228:231], v[208:211], v[40:43]
	v_mfma_f32_16x16x32_bf16 v[32:35], v[236:239], v[208:211], v[32:35]
	v_mfma_f32_16x16x32_bf16 v[56:59], v[228:231], v[220:223], v[56:59]
	v_mfma_f32_16x16x32_bf16 v[60:63], v[236:239], v[220:223], v[60:63]
	v_mfma_f32_16x16x32_bf16 v[12:15], v[232:235], v[148:151], v[12:15]
	v_mfma_f32_16x16x32_bf16 v[8:11], v[240:243], v[148:151], v[8:11]
	v_mfma_f32_16x16x32_bf16 v[24:27], v[232:235], v[204:207], v[24:27]
	v_mfma_f32_16x16x32_bf16 v[16:19], v[240:243], v[204:207], v[16:19]
	v_mfma_f32_16x16x32_bf16 v[40:43], v[232:235], v[212:215], v[40:43]
	v_mfma_f32_16x16x32_bf16 v[32:35], v[240:243], v[212:215], v[32:35]
	v_mfma_f32_16x16x32_bf16 v[56:59], v[232:235], v[224:227], v[56:59]
	v_mfma_f32_16x16x32_bf16 v[60:63], v[240:243], v[224:227], v[60:63]
	s_barrier
	s_setprio 0
	s_mov_b32 m0, s34
	ds_read_b128 v[144:147], v167 offset:16384
	ds_read_b128 v[148:151], v167 offset:17408
	ds_read_b128 v[200:203], v167 offset:18432
	ds_read_b128 v[204:207], v167 offset:19456
	ds_read_b128 v[208:211], v167 offset:20480
	ds_read_b128 v[212:215], v167 offset:21504
	ds_read_b128 v[220:223], v167 offset:22528
	ds_read_b128 v[224:227], v167 offset:23552
	global_load_lds_dwordx4 v168, s[30:31]
	s_mov_b32 m0, s35
	s_nop 0
	global_load_lds_dwordx4 v172, s[30:31]
	s_setprio 1
	s_barrier
	s_waitcnt lgkmcnt(0)
	v_mfma_f32_16x16x32_bf16 v[64:67], v[20:23], v[144:147], v[64:67]
	v_mfma_f32_16x16x32_bf16 v[68:71], v[136:139], v[144:147], v[68:71]
	v_mfma_f32_16x16x32_bf16 v[108:111], v[20:23], v[200:203], v[108:111]
	v_mfma_f32_16x16x32_bf16 v[100:103], v[136:139], v[200:203], v[100:103]
	v_mfma_f32_16x16x32_bf16 v[116:119], v[20:23], v[208:211], v[116:119]
	v_mfma_f32_16x16x32_bf16 v[112:115], v[136:139], v[208:211], v[112:115]
	v_mfma_f32_16x16x32_bf16 v[20:23], v[20:23], v[220:223], v[132:135]
	v_mfma_f32_16x16x32_bf16 v[64:67], v[28:31], v[148:151], v[64:67]
	v_mfma_f32_16x16x32_bf16 v[68:71], v[140:143], v[148:151], v[68:71]
	v_mfma_f32_16x16x32_bf16 v[108:111], v[28:31], v[204:207], v[108:111]
	v_mfma_f32_16x16x32_bf16 v[100:103], v[140:143], v[204:207], v[100:103]
	v_mfma_f32_16x16x32_bf16 v[116:119], v[28:31], v[212:215], v[116:119]
	v_mfma_f32_16x16x32_bf16 v[112:115], v[140:143], v[212:215], v[112:115]
	v_mfma_f32_16x16x32_bf16 v[20:23], v[28:31], v[224:227], v[20:23]
	v_mfma_f32_16x16x32_bf16 v[28:31], v[136:139], v[220:223], v[128:131]
	v_mfma_f32_16x16x32_bf16 v[28:31], v[140:143], v[224:227], v[28:31]
	s_barrier
	s_setprio 0
	s_add_u32 s64, s26, 0x158000
	s_addc_u32 s65, s27, 0
	s_add_i32 s63, s53, s33
	s_mov_b32 m0, s63
	s_nop 0
	global_load_lds_dwordx4 v170, s[64:65]
	s_add_i32 m0, s63, 0x2000
	s_nop 0
	global_load_lds_dwordx4 v174, s[64:65]
	s_waitcnt vmcnt(6)
	s_setprio 1
	s_barrier
; #define PG8_STAGE(bufoff, gbase, voff) do { _Pragma("unroll") for (int _i = 0; _i < 2; ++_i) \
;         __builtin_amdgcn_global_load_lds((const unsigned*)((const char*)(gbase) + (voff)[_i]), (LAS unsigned*)(lds + (bufoff) + ldsw + _i * 8192), 16, 0, 0); } while (0)
; #define PG8_LDA(dst, b, h) do { _Pragma("unroll") for (int m = 0; m < 4; ++m) _Pragma("unroll") for (int k = 0; k < 2; ++k) dst[m][k] = *(const LAS bf16x8*)(lds + PG8_SA(b, h) + aoff + m * 2048 + k * 1024); } while (0)
; #define PG8_LDB(dst, b, h) do { _Pragma("unroll") for (int n = 0; n < 2; ++n) _Pragma("unroll") for (int k = 0; k < 2; ++k) dst[n][k] = *(const LAS bf16x8*)(lds + PG8_SB(b, h) + boff + n * 2048 + k * 1024); } while (0)
; #define PG8_MMA(ai, bj, At, Bt) do { __builtin_amdgcn_s_setprio(1); _Pragma("unroll") for (int m = 0; m < 4; ++m) _Pragma("unroll") for (int n = 0; n < 2; ++n) _Pragma("unroll") for (int k = 0; k < 2; ++k) \
;         acc[ai][bj][m][n] = __builtin_amdgcn_mfma_f32_16x16x32_bf16(Bt[n][k], At[m][k], acc[ai][bj][m][n], 0, 0, 0); __builtin_amdgcn_s_setprio(0); } while (0)
; #define PG8_WAIT_V(n) asm volatile("s_waitcnt vmcnt(" #n ")" ::: "memory")
; #define PG8_WAIT_L(n) asm volatile("s_waitcnt lgkmcnt(" #n ")" ::: "memory")
; #define PG8_BAR __builtin_amdgcn_s_barrier()
; #define PG8_SCHED __builtin_amdgcn_sched_barrier(0)
; template <class Epi, class Sched, bool ATILE = false>
; __device__ __forceinline__ void gemm_phase(LAS unsigned char* lds, const Gemm g, const Sched& S, const Epi& E) {
;     ...
;             PG8_WAIT_V(6); PG8_BAR; PG8_MMA(1, 1, At, B1); PG8_BAR;
;             PG8_LDB(B0, 1, 0); PG8_SCHED; PG8_LDA(At, 1, 0); PG8_STAGE(PG8_SA(0, 1), a2 + hstepA, voffA);
;             PG8_WAIT_L(8); PG8_BAR; PG8_WAIT_L(0); PG8_MMA(0, 0, At, B0); PG8_BAR; PG8_SCHED;
;             PG8_LDB(B1, 1, 1); PG8_STAGE(PG8_SB(1, 0), b3, voffB);
;             PG8_BAR; PG8_WAIT_L(0); PG8_MMA(0, 1, At, B1); PG8_BAR;
;             PG8_LDA(At, 1, 1); PG8_STAGE(PG8_SA(1, 0), a3, voffA);
;             PG8_BAR; PG8_WAIT_L(0); PG8_MMA(1, 0, At, B0); PG8_BAR; PG8_SCHED;
	v_mfma_f32_16x16x32_bf16 v[76:79], v[228:231], v[144:147], v[76:79]
	v_mfma_f32_16x16x32_bf16 v[72:75], v[236:239], v[144:147], v[72:75]
	v_mfma_f32_16x16x32_bf16 v[88:91], v[228:231], v[200:203], v[88:91]
	v_mfma_f32_16x16x32_bf16 v[80:83], v[236:239], v[200:203], v[80:83]
	v_mfma_f32_16x16x32_bf16 v[104:107], v[228:231], v[208:211], v[104:107]
	v_mfma_f32_16x16x32_bf16 v[96:99], v[236:239], v[208:211], v[96:99]
	v_mfma_f32_16x16x32_bf16 v[120:123], v[228:231], v[220:223], v[120:123]
	v_mfma_f32_16x16x32_bf16 v[124:127], v[236:239], v[220:223], v[124:127]
	v_mfma_f32_16x16x32_bf16 v[76:79], v[232:235], v[148:151], v[76:79]
	v_mfma_f32_16x16x32_bf16 v[72:75], v[240:243], v[148:151], v[72:75]
	v_mfma_f32_16x16x32_bf16 v[88:91], v[232:235], v[204:207], v[88:91]
	v_mfma_f32_16x16x32_bf16 v[80:83], v[240:243], v[204:207], v[80:83]
	v_mfma_f32_16x16x32_bf16 v[104:107], v[232:235], v[212:215], v[104:107]
	v_mfma_f32_16x16x32_bf16 v[96:99], v[240:243], v[212:215], v[96:99]
	v_mfma_f32_16x16x32_bf16 v[120:123], v[232:235], v[224:227], v[120:123]
	v_mfma_f32_16x16x32_bf16 v[124:127], v[240:243], v[224:227], v[124:127]
	s_barrier
	s_setprio 0
	s_add_i32 s63, 0, 0x18000
	v_add_u32_e32 v140, s63, v161
	ds_read_b128 v[128:131], v140
	ds_read_b128 v[132:135], v140 offset:1024
	ds_read_b128 v[136:139], v140 offset:2048
	ds_read_b128 v[140:143], v140 offset:3072
	s_add_u32 s30, s30, 0x4000
	s_addc_u32 s31, s31, 0
	s_mov_b32 m0, s36
	ds_read_b128 v[144:147], v167 offset:32768
	ds_read_b128 v[148:151], v167 offset:33792
	ds_read_b128 v[200:203], v167 offset:34816
	ds_read_b128 v[204:207], v167 offset:35840
	ds_read_b128 v[208:211], v167 offset:36864
	ds_read_b128 v[212:215], v167 offset:37888
	ds_read_b128 v[220:223], v167 offset:38912
	ds_read_b128 v[224:227], v167 offset:39936
	global_load_lds_dwordx4 v168, s[30:31]
	s_mov_b32 m0, s37
	s_nop 0
	global_load_lds_dwordx4 v172, s[30:31]
	s_waitcnt lgkmcnt(8)
	s_setprio 1
	s_barrier
	s_waitcnt lgkmcnt(0)
	v_mfma_f32_16x16x32_bf16 v[0:3], v[128:131], v[144:147], v[0:3]
	v_mfma_f32_16x16x32_bf16 v[4:7], v[136:139], v[144:147], v[4:7]
	v_mfma_f32_16x16x32_bf16 v[44:47], v[128:131], v[200:203], v[44:47]
	v_mfma_f32_16x16x32_bf16 v[36:39], v[136:139], v[200:203], v[36:39]
	v_mfma_f32_16x16x32_bf16 v[52:55], v[128:131], v[208:211], v[52:55]
	v_mfma_f32_16x16x32_bf16 v[48:51], v[136:139], v[208:211], v[48:51]
	v_mfma_f32_16x16x32_bf16 v[92:95], v[128:131], v[220:223], v[92:95]
	v_mfma_f32_16x16x32_bf16 v[84:87], v[136:139], v[220:223], v[84:87]
	v_mfma_f32_16x16x32_bf16 v[0:3], v[132:135], v[148:151], v[0:3]
	v_mfma_f32_16x16x32_bf16 v[4:7], v[140:143], v[148:151], v[4:7]
	v_mfma_f32_16x16x32_bf16 v[44:47], v[132:135], v[204:207], v[44:47]
	v_mfma_f32_16x16x32_bf16 v[36:39], v[140:143], v[204:207], v[36:39]
	v_mfma_f32_16x16x32_bf16 v[52:55], v[132:135], v[212:215], v[52:55]
	v_mfma_f32_16x16x32_bf16 v[48:51], v[140:143], v[212:215], v[48:51]
	v_mfma_f32_16x16x32_bf16 v[92:95], v[132:135], v[224:227], v[92:95]
	v_mfma_f32_16x16x32_bf16 v[84:87], v[140:143], v[224:227], v[84:87]
	s_barrier
	s_setprio 0
	s_add_i32 s30, 0, 0x1c000
	s_add_i32 s31, s63, s33
	v_add_u32_e32 v219, s30, v161
	s_mov_b32 m0, s31
	ds_read_b128 v[228:231], v219
	ds_read_b128 v[232:235], v219 offset:1024
	ds_read_b128 v[236:239], v219 offset:2048
	ds_read_b128 v[240:243], v219 offset:3072
	global_load_lds_dwordx4 v170, s[98:99]
	s_add_i32 m0, s31, 0x2000
	s_nop 0
	global_load_lds_dwordx4 v174, s[98:99]
	s_setprio 1
	s_barrier
	s_waitcnt lgkmcnt(0)
	v_mfma_f32_16x16x32_bf16 v[12:15], v[228:231], v[144:147], v[12:15]
	v_mfma_f32_16x16x32_bf16 v[8:11], v[236:239], v[144:147], v[8:11]
	v_mfma_f32_16x16x32_bf16 v[24:27], v[228:231], v[200:203], v[24:27]
	v_mfma_f32_16x16x32_bf16 v[16:19], v[236:239], v[200:203], v[16:19]
	v_mfma_f32_16x16x32_bf16 v[40:43], v[228:231], v[208:211], v[40:43]
	v_mfma_f32_16x16x32_bf16 v[32:35], v[236:239], v[208:211], v[32:35]
	v_mfma_f32_16x16x32_bf16 v[56:59], v[228:231], v[220:223], v[56:59]
	v_mfma_f32_16x16x32_bf16 v[60:63], v[236:239], v[220:223], v[60:63]
	v_mfma_f32_16x16x32_bf16 v[12:15], v[232:235], v[148:151], v[12:15]
	v_mfma_f32_16x16x32_bf16 v[8:11], v[240:243], v[148:151], v[8:11]
	v_mfma_f32_16x16x32_bf16 v[24:27], v[232:235], v[204:207], v[24:27]
	v_mfma_f32_16x16x32_bf16 v[16:19], v[240:243], v[204:207], v[16:19]
	v_mfma_f32_16x16x32_bf16 v[40:43], v[232:235], v[212:215], v[40:43]
	v_mfma_f32_16x16x32_bf16 v[32:35], v[240:243], v[212:215], v[32:35]
	v_mfma_f32_16x16x32_bf16 v[56:59], v[232:235], v[224:227], v[56:59]
	v_mfma_f32_16x16x32_bf16 v[60:63], v[240:243], v[224:227], v[60:63]
	s_barrier
	s_setprio 0
	s_mov_b32 m0, s39
	ds_read_b128 v[144:147], v167 offset:49152
	ds_read_b128 v[148:151], v167 offset:50176
	ds_read_b128 v[200:203], v167 offset:51200
	ds_read_b128 v[204:207], v167 offset:52224
	ds_read_b128 v[208:211], v167 offset:53248
	ds_read_b128 v[212:215], v167 offset:54272
	ds_read_b128 v[220:223], v167 offset:55296
	ds_read_b128 v[224:227], v167 offset:56320
	global_load_lds_dwordx4 v168, s[28:29]
	s_mov_b32 m0, s40
	s_nop 0
	global_load_lds_dwordx4 v172, s[28:29]
	s_setprio 1
	s_barrier
; #define PG8_STAGE(bufoff, gbase, voff) do { _Pragma("unroll") for (int _i = 0; _i < 2; ++_i) \
;         __builtin_amdgcn_global_load_lds((const unsigned*)((const char*)(gbase) + (voff)[_i]), (LAS unsigned*)(lds + (bufoff) + ldsw + _i * 8192), 16, 0, 0); } while (0)
; #define PG8_MMA(ai, bj, At, Bt) do { __builtin_amdgcn_s_setprio(1); _Pragma("unroll") for (int m = 0; m < 4; ++m) _Pragma("unroll") for (int n = 0; n < 2; ++n) _Pragma("unroll") for (int k = 0; k < 2; ++k) \
;         acc[ai][bj][m][n] = __builtin_amdgcn_mfma_f32_16x16x32_bf16(Bt[n][k], At[m][k], acc[ai][bj][m][n], 0, 0, 0); __builtin_amdgcn_s_setprio(0); } while (0)
; #define PG8_WAIT_V(n) asm volatile("s_waitcnt vmcnt(" #n ")" ::: "memory")
; #define PG8_WAIT_L(n) asm volatile("s_waitcnt lgkmcnt(" #n ")" ::: "memory")
; #define PG8_BAR __builtin_amdgcn_s_barrier()
; #define PG8_SCHED __builtin_amdgcn_sched_barrier(0)
; template <class Epi, class Sched, bool ATILE = false>
; __device__ __forceinline__ void gemm_phase(LAS unsigned char* lds, const Gemm g, const Sched& S, const Epi& E) {
;     ...
;             PG8_BAR; PG8_WAIT_L(0); PG8_MMA(1, 0, At, B0); PG8_BAR; PG8_SCHED;
;             PG8_STAGE(PG8_SB(1, 1), b3 + hstepB, voffB);
;             PG8_WAIT_V(6); PG8_BAR; PG8_MMA(1, 1, At, B1); PG8_BAR;
;         }
;         E(acc, cur, wr, wc, fr, fq);
	s_waitcnt lgkmcnt(0)
	v_mfma_f32_16x16x32_bf16 v[64:67], v[128:131], v[144:147], v[64:67]
	v_mfma_f32_16x16x32_bf16 v[108:111], v[128:131], v[200:203], v[108:111]
	v_mfma_f32_16x16x32_bf16 v[116:119], v[128:131], v[208:211], v[116:119]
	v_mfma_f32_16x16x32_bf16 v[20:23], v[128:131], v[220:223], v[20:23]
	v_mfma_f32_16x16x32_bf16 v[64:67], v[132:135], v[148:151], v[64:67]
	v_mfma_f32_16x16x32_bf16 v[68:71], v[136:139], v[144:147], v[68:71]
	v_mfma_f32_16x16x32_bf16 v[108:111], v[132:135], v[204:207], v[108:111]
	v_mfma_f32_16x16x32_bf16 v[100:103], v[136:139], v[200:203], v[100:103]
	v_mfma_f32_16x16x32_bf16 v[116:119], v[132:135], v[212:215], v[116:119]
	v_mfma_f32_16x16x32_bf16 v[112:115], v[136:139], v[208:211], v[112:115]
	v_mfma_f32_16x16x32_bf16 v[132:135], v[132:135], v[224:227], v[20:23]
	v_mfma_f32_16x16x32_bf16 v[20:23], v[136:139], v[220:223], v[28:31]
	v_mfma_f32_16x16x32_bf16 v[68:71], v[140:143], v[148:151], v[68:71]
	v_mfma_f32_16x16x32_bf16 v[100:103], v[140:143], v[204:207], v[100:103]
	v_mfma_f32_16x16x32_bf16 v[112:115], v[140:143], v[212:215], v[112:115]
	v_mfma_f32_16x16x32_bf16 v[128:131], v[140:143], v[224:227], v[20:23]
	s_barrier
	s_setprio 0
	s_add_u32 s26, s26, 0x158080
	s_addc_u32 s27, s27, 0
	s_add_i32 s28, s30, s33
	s_mov_b32 m0, s28
	s_nop 0
	global_load_lds_dwordx4 v170, s[26:27]
	s_add_i32 m0, s28, 0x2000
	s_nop 0
	global_load_lds_dwordx4 v174, s[26:27]
	s_waitcnt vmcnt(6)
	s_setprio 1
	s_barrier
	v_mfma_f32_16x16x32_bf16 v[20:23], v[228:231], v[144:147], v[76:79]
	v_mfma_f32_16x16x32_bf16 v[76:79], v[232:235], v[148:151], v[20:23]
	v_mfma_f32_16x16x32_bf16 v[20:23], v[236:239], v[144:147], v[72:75]
	v_mfma_f32_16x16x32_bf16 v[72:75], v[240:243], v[148:151], v[20:23]
	v_mfma_f32_16x16x32_bf16 v[20:23], v[228:231], v[200:203], v[88:91]
	v_mfma_f32_16x16x32_bf16 v[88:91], v[232:235], v[204:207], v[20:23]
	v_mfma_f32_16x16x32_bf16 v[20:23], v[236:239], v[200:203], v[80:83]
	s_add_u32 s60, s60, 0x100
	v_mfma_f32_16x16x32_bf16 v[80:83], v[240:243], v[204:207], v[20:23]
	s_addc_u32 s61, s61, 0
	v_mfma_f32_16x16x32_bf16 v[20:23], v[228:231], v[208:211], v[104:107]
	s_add_u32 s24, s24, 0x10000
	v_mfma_f32_16x16x32_bf16 v[104:107], v[232:235], v[212:215], v[20:23]
	s_addc_u32 s25, s25, 0
	v_mfma_f32_16x16x32_bf16 v[20:23], v[236:239], v[208:211], v[96:99]
	s_cmp_ge_i32 s62, s59
	v_mfma_f32_16x16x32_bf16 v[96:99], v[240:243], v[212:215], v[20:23]
	s_mov_b32 s26, s62
	v_mfma_f32_16x16x32_bf16 v[20:23], v[228:231], v[220:223], v[120:123]
	v_mfma_f32_16x16x32_bf16 v[120:123], v[232:235], v[224:227], v[20:23]
	v_mfma_f32_16x16x32_bf16 v[20:23], v[236:239], v[220:223], v[124:127]
	v_mfma_f32_16x16x32_bf16 v[124:127], v[240:243], v[224:227], v[20:23]
	s_barrier
	s_setprio 0
	s_cbranch_scc0 .LBB0_739
	s_nop 5
	v_pk_mul_f32 v[2:3], v[2:3], 0.5 op_sel_hi:[1,0]
	v_pk_mul_f32 v[0:1], v[0:1], 0.5 op_sel_hi:[1,0]
	v_pk_mul_f32 v[6:7], v[6:7], 0.5 op_sel_hi:[1,0]
	v_pk_mul_f32 v[4:5], v[4:5], 0.5 op_sel_hi:[1,0]
	v_pk_mul_f32 v[22:23], v[14:15], 0.5 op_sel_hi:[1,0]
	v_pk_mul_f32 v[20:21], v[12:13], 0.5 op_sel_hi:[1,0]
	v_pk_mul_f32 v[30:31], v[10:11], 0.5 op_sel_hi:[1,0]
	v_pk_mul_f32 v[28:29], v[8:9], 0.5 op_sel_hi:[1,0]
	v_pk_mul_f32 v[10:11], v[46:47], 0.5 op_sel_hi:[1,0]
	v_pk_mul_f32 v[8:9], v[44:45], 0.5 op_sel_hi:[1,0]
	v_pk_mul_f32 v[14:15], v[38:39], 0.5 op_sel_hi:[1,0]
	v_pk_mul_f32 v[12:13], v[36:37], 0.5 op_sel_hi:[1,0]
	v_pk_mul_f32 v[38:39], v[26:27], 0.5 op_sel_hi:[1,0]
	v_pk_mul_f32 v[36:37], v[24:25], 0.5 op_sel_hi:[1,0]
	v_pk_mul_f32 v[46:47], v[18:19], 0.5 op_sel_hi:[1,0]
	v_pk_mul_f32 v[44:45], v[16:17], 0.5 op_sel_hi:[1,0]
	v_pk_mul_f32 v[18:19], v[54:55], 0.5 op_sel_hi:[1,0]
	v_pk_mul_f32 v[16:17], v[52:53], 0.5 op_sel_hi:[1,0]
	v_pk_mul_f32 v[26:27], v[50:51], 0.5 op_sel_hi:[1,0]
	v_pk_mul_f32 v[24:25], v[48:49], 0.5 op_sel_hi:[1,0]
	v_pk_mul_f32 v[50:51], v[42:43], 0.5 op_sel_hi:[1,0]
	v_pk_mul_f32 v[48:49], v[40:41], 0.5 op_sel_hi:[1,0]
	v_pk_mul_f32 v[54:55], v[34:35], 0.5 op_sel_hi:[1,0]
	v_pk_mul_f32 v[52:53], v[32:33], 0.5 op_sel_hi:[1,0]
	v_pk_mul_f32 v[34:35], v[94:95], 0.5 op_sel_hi:[1,0]
	v_pk_mul_f32 v[32:33], v[92:93], 0.5 op_sel_hi:[1,0]
	v_pk_mul_f32 v[42:43], v[86:87], 0.5 op_sel_hi:[1,0]
	v_pk_mul_f32 v[40:41], v[84:85], 0.5 op_sel_hi:[1,0]
	v_pk_mul_f32 v[58:59], v[58:59], 0.5 op_sel_hi:[1,0]
	v_pk_mul_f32 v[56:57], v[56:57], 0.5 op_sel_hi:[1,0]
	v_pk_mul_f32 v[62:63], v[62:63], 0.5 op_sel_hi:[1,0]
	v_pk_mul_f32 v[60:61], v[60:61], 0.5 op_sel_hi:[1,0]
	v_pk_mul_f32 v[66:67], v[66:67], 0.5 op_sel_hi:[1,0]
	v_pk_mul_f32 v[64:65], v[64:65], 0.5 op_sel_hi:[1,0]
	v_pk_mul_f32 v[70:71], v[70:71], 0.5 op_sel_hi:[1,0]
	v_pk_mul_f32 v[68:69], v[68:69], 0.5 op_sel_hi:[1,0]
	v_pk_mul_f32 v[86:87], v[78:79], 0.5 op_sel_hi:[1,0]
	v_pk_mul_f32 v[84:85], v[76:77], 0.5 op_sel_hi:[1,0]
	v_pk_mul_f32 v[94:95], v[74:75], 0.5 op_sel_hi:[1,0]
	v_pk_mul_f32 v[92:93], v[72:73], 0.5 op_sel_hi:[1,0]
	v_pk_mul_f32 v[74:75], v[110:111], 0.5 op_sel_hi:[1,0]
	v_pk_mul_f32 v[72:73], v[108:109], 0.5 op_sel_hi:[1,0]
	v_pk_mul_f32 v[78:79], v[102:103], 0.5 op_sel_hi:[1,0]
	v_pk_mul_f32 v[76:77], v[100:101], 0.5 op_sel_hi:[1,0]
	v_pk_mul_f32 v[102:103], v[90:91], 0.5 op_sel_hi:[1,0]
	v_pk_mul_f32 v[100:101], v[88:89], 0.5 op_sel_hi:[1,0]
	v_pk_mul_f32 v[110:111], v[82:83], 0.5 op_sel_hi:[1,0]
	v_pk_mul_f32 v[108:109], v[80:81], 0.5 op_sel_hi:[1,0]
	v_pk_mul_f32 v[82:83], v[118:119], 0.5 op_sel_hi:[1,0]
	v_pk_mul_f32 v[80:81], v[116:117], 0.5 op_sel_hi:[1,0]
	v_pk_mul_f32 v[90:91], v[114:115], 0.5 op_sel_hi:[1,0]
	v_pk_mul_f32 v[88:89], v[112:113], 0.5 op_sel_hi:[1,0]
	v_pk_mul_f32 v[114:115], v[106:107], 0.5 op_sel_hi:[1,0]
	v_pk_mul_f32 v[112:113], v[104:105], 0.5 op_sel_hi:[1,0]
	v_pk_mul_f32 v[118:119], v[98:99], 0.5 op_sel_hi:[1,0]
	v_pk_mul_f32 v[116:117], v[96:97], 0.5 op_sel_hi:[1,0]
	v_pk_mul_f32 v[98:99], v[134:135], 0.5 op_sel_hi:[1,0]
	v_pk_mul_f32 v[96:97], v[132:133], 0.5 op_sel_hi:[1,0]
	v_pk_mul_f32 v[106:107], v[130:131], 0.5 op_sel_hi:[1,0]
	v_pk_mul_f32 v[104:105], v[128:129], 0.5 op_sel_hi:[1,0]
	v_pk_mul_f32 v[122:123], v[122:123], 0.5 op_sel_hi:[1,0]
	v_pk_mul_f32 v[120:121], v[120:121], 0.5 op_sel_hi:[1,0]
	v_pk_mul_f32 v[126:127], v[126:127], 0.5 op_sel_hi:[1,0]
	v_pk_mul_f32 v[124:125], v[124:125], 0.5 op_sel_hi:[1,0]
	s_branch .LBB0_744

; #define PG8_STAGE(bufoff, gbase, voff) do { _Pragma("unroll") for (int _i = 0; _i < 2; ++_i) \
;         __builtin_amdgcn_global_load_lds((const unsigned*)((const char*)(gbase) + (voff)[_i]), (LAS unsigned*)(lds + (bufoff) + ldsw + _i * 8192), 16, 0, 0); } while (0)
; #define PG8_LDA(dst, b, h) do { _Pragma("unroll") for (int m = 0; m < 4; ++m) _Pragma("unroll") for (int k = 0; k < 2; ++k) dst[m][k] = *(const LAS bf16x8*)(lds + PG8_SA(b, h) + aoff + m * 2048 + k * 1024); } while (0)
; #define PG8_LDB(dst, b, h) do { _Pragma("unroll") for (int n = 0; n < 2; ++n) _Pragma("unroll") for (int k = 0; k < 2; ++k) dst[n][k] = *(const LAS bf16x8*)(lds + PG8_SB(b, h) + boff + n * 2048 + k * 1024); } while (0)
; #define PG8_MMA(ai, bj, At, Bt) do { __builtin_amdgcn_s_setprio(1); _Pragma("unroll") for (int m = 0; m < 4; ++m) _Pragma("unroll") for (int n = 0; n < 2; ++n) _Pragma("unroll") for (int k = 0; k < 2; ++k) \
;         acc[ai][bj][m][n] = __builtin_amdgcn_mfma_f32_16x16x32_bf16(Bt[n][k], At[m][k], acc[ai][bj][m][n], 0, 0, 0); __builtin_amdgcn_s_setprio(0); } while (0)
; #define PG8_WAIT_V(n) asm volatile("s_waitcnt vmcnt(" #n ")" ::: "memory")
; #define PG8_WAIT_L(n) asm volatile("s_waitcnt lgkmcnt(" #n ")" ::: "memory")
; template <class Epi, class Sched, bool ATILE = false>
; __device__ __forceinline__ void gemm_phase(LAS unsigned char* lds, const Gemm g, const Sched& S, const Epi& E) {
;     ...
;         for (int t = 0; t < nt; t += 2) {
;             const bool last = (t == nt - 2);
;             const char* a1 = cA + (size_t)(t + 1) * kstepA;
;             const char* a2 = last ? nA : cA + (size_t)(t + 2) * kstepA; const char* b2 = last ? nB : cB + (size_t)(t + 2) * kstep;
;             const char* a3 = a2 + kstepA; const char* b3 = b2 + kstep;
;             PG8_LDB(B0, 0, 0); PG8_SCHED; PG8_LDA(At, 0, 0); PG8_STAGE(PG8_SA(1, 1), a1 + hstepA, voffA);
;             PG8_WAIT_L(8); PG8_BAR; PG8_WAIT_L(0); PG8_MMA(0, 0, At, B0); PG8_BAR; PG8_SCHED;
;             PG8_LDB(B1, 0, 1); PG8_STAGE(PG8_SB(0, 0), b2, voffB);
;             PG8_BAR; PG8_WAIT_L(0); PG8_MMA(0, 1, At, B1); PG8_BAR;
;             PG8_LDA(At, 0, 1); PG8_STAGE(PG8_SA(0, 0), a2, voffA);
;             PG8_BAR; PG8_WAIT_L(0); PG8_MMA(1, 0, At, B0); PG8_BAR; PG8_SCHED;
;             PG8_STAGE(PG8_SB(0, 1), b2 + hstepB, voffB);
;             PG8_WAIT_V(6); PG8_BAR; PG8_MMA(1, 1, At, B1); PG8_BAR;
.LBB0_895:
	ds_read_b128 v[32:35], v165
	ds_read_b128 v[36:39], v165 offset:1024
	ds_read_b128 v[178:181], v165 offset:2048
	ds_read_b128 v[182:185], v165 offset:3072
	s_add_i32 s88, s73, 2
	s_add_u32 s84, s12, 0xfff80080
	s_addc_u32 s85, s13, -1
	s_cmp_eq_u32 s53, s73
	s_cselect_b32 s87, s11, s85
	s_cselect_b32 s86, s20, s84
	s_cselect_b32 s85, s41, s63
	s_cselect_b32 s84, s52, s62
	s_add_i32 m0, s35, 0xc000
	ds_read_b128 v[192:195], v167
	ds_read_b128 v[196:199], v167 offset:1024
	ds_read_b128 v[200:203], v167 offset:2048
	ds_read_b128 v[204:207], v167 offset:3072
	ds_read_b128 v[208:211], v167 offset:4096
	ds_read_b128 v[212:215], v167 offset:5120
	ds_read_b128 v[216:219], v167 offset:6144
	ds_read_b128 v[220:223], v167 offset:7168
	global_load_lds_dwordx4 v170, s[12:13]
	s_add_i32 m0, s35, 0xe000
	s_nop 0
	global_load_lds_dwordx4 v172, s[12:13]
	s_waitcnt lgkmcnt(8)
	s_setprio 1
	s_barrier
	s_waitcnt lgkmcnt(0)
	v_mfma_f32_16x16x32_bf16 v[132:135], v[32:35], v[192:195], v[132:135]
	v_mfma_f32_16x16x32_bf16 v[128:131], v[178:181], v[192:195], v[128:131]
	v_mfma_f32_16x16x32_bf16 v[116:119], v[32:35], v[200:203], v[116:119]
	v_mfma_f32_16x16x32_bf16 v[112:115], v[178:181], v[200:203], v[112:115]
	v_mfma_f32_16x16x32_bf16 v[100:103], v[32:35], v[208:211], v[100:103]
	v_mfma_f32_16x16x32_bf16 v[96:99], v[178:181], v[208:211], v[96:99]
	v_mfma_f32_16x16x32_bf16 v[84:87], v[32:35], v[216:219], v[84:87]
	v_mfma_f32_16x16x32_bf16 v[80:83], v[178:181], v[216:219], v[80:83]
	v_mfma_f32_16x16x32_bf16 v[132:135], v[36:39], v[196:199], v[132:135]
	v_mfma_f32_16x16x32_bf16 v[128:131], v[182:185], v[196:199], v[128:131]
	v_mfma_f32_16x16x32_bf16 v[116:119], v[36:39], v[204:207], v[116:119]
	v_mfma_f32_16x16x32_bf16 v[112:115], v[182:185], v[204:207], v[112:115]
	v_mfma_f32_16x16x32_bf16 v[100:103], v[36:39], v[212:215], v[100:103]
	v_mfma_f32_16x16x32_bf16 v[96:99], v[182:185], v[212:215], v[96:99]
	v_mfma_f32_16x16x32_bf16 v[84:87], v[36:39], v[220:223], v[84:87]
	v_mfma_f32_16x16x32_bf16 v[80:83], v[182:185], v[220:223], v[80:83]
	s_barrier
	s_setprio 0
	s_add_i32 s73, s43, s31
	s_add_u32 s98, s84, s22
	s_addc_u32 s99, s85, s23
	s_mov_b32 m0, s73
	ds_read_b128 v[224:227], v186
	ds_read_b128 v[228:231], v186 offset:1024
	ds_read_b128 v[232:235], v186 offset:2048
	ds_read_b128 v[236:239], v186 offset:3072
	global_load_lds_dwordx4 v138, s[84:85]
	s_add_i32 m0, s73, 0x2000
	s_nop 0
	global_load_lds_dwordx4 v142, s[84:85]
	s_setprio 1
	s_barrier
	s_waitcnt lgkmcnt(0)
	v_mfma_f32_16x16x32_bf16 v[124:127], v[224:227], v[192:195], v[124:127]
	v_mfma_f32_16x16x32_bf16 v[120:123], v[232:235], v[192:195], v[120:123]
	v_mfma_f32_16x16x32_bf16 v[108:111], v[224:227], v[200:203], v[108:111]
	v_mfma_f32_16x16x32_bf16 v[104:107], v[232:235], v[200:203], v[104:107]
	v_mfma_f32_16x16x32_bf16 v[92:95], v[224:227], v[208:211], v[92:95]
	v_mfma_f32_16x16x32_bf16 v[88:91], v[232:235], v[208:211], v[88:91]
	v_mfma_f32_16x16x32_bf16 v[76:79], v[224:227], v[216:219], v[76:79]
	v_mfma_f32_16x16x32_bf16 v[72:75], v[232:235], v[216:219], v[72:75]
	v_mfma_f32_16x16x32_bf16 v[124:127], v[228:231], v[196:199], v[124:127]
	v_mfma_f32_16x16x32_bf16 v[120:123], v[236:239], v[196:199], v[120:123]
	v_mfma_f32_16x16x32_bf16 v[108:111], v[228:231], v[204:207], v[108:111]
	v_mfma_f32_16x16x32_bf16 v[104:107], v[236:239], v[204:207], v[104:107]
	v_mfma_f32_16x16x32_bf16 v[92:95], v[228:231], v[212:215], v[92:95]
	v_mfma_f32_16x16x32_bf16 v[88:91], v[236:239], v[212:215], v[88:91]
	v_mfma_f32_16x16x32_bf16 v[76:79], v[228:231], v[220:223], v[76:79]
	v_mfma_f32_16x16x32_bf16 v[72:75], v[236:239], v[220:223], v[72:75]
	s_barrier
	s_setprio 0
	s_mov_b32 m0, s35
	s_add_u32 s100, s86, s22
	s_addc_u32 s101, s87, s23
	ds_read_b128 v[192:195], v167 offset:16384
	ds_read_b128 v[196:199], v167 offset:17408
	ds_read_b128 v[200:203], v167 offset:18432
	ds_read_b128 v[204:207], v167 offset:19456
	ds_read_b128 v[208:211], v167 offset:20480
	ds_read_b128 v[212:215], v167 offset:21504
	ds_read_b128 v[216:219], v167 offset:22528
	ds_read_b128 v[220:223], v167 offset:23552
	global_load_lds_dwordx4 v136, s[86:87]
	s_mov_b32 m0, s37
	s_nop 0
	global_load_lds_dwordx4 v140, s[86:87]
	s_setprio 1
	s_barrier
	s_waitcnt lgkmcnt(0)
	v_mfma_f32_16x16x32_bf16 v[68:71], v[32:35], v[192:195], v[68:71]
	v_mfma_f32_16x16x32_bf16 v[64:67], v[178:181], v[192:195], v[64:67]
	v_mfma_f32_16x16x32_bf16 v[52:55], v[32:35], v[200:203], v[52:55]
	v_mfma_f32_16x16x32_bf16 v[48:51], v[178:181], v[200:203], v[48:51]
	v_mfma_f32_16x16x32_bf16 v[28:31], v[32:35], v[208:211], v[28:31]
	v_mfma_f32_16x16x32_bf16 v[24:27], v[178:181], v[208:211], v[24:27]
	v_mfma_f32_16x16x32_bf16 v[12:15], v[32:35], v[216:219], v[12:15]
	v_mfma_f32_16x16x32_bf16 v[8:11], v[178:181], v[216:219], v[8:11]
	v_mfma_f32_16x16x32_bf16 v[68:71], v[36:39], v[196:199], v[68:71]
	v_mfma_f32_16x16x32_bf16 v[64:67], v[182:185], v[196:199], v[64:67]
	v_mfma_f32_16x16x32_bf16 v[52:55], v[36:39], v[204:207], v[52:55]
	v_mfma_f32_16x16x32_bf16 v[48:51], v[182:185], v[204:207], v[48:51]
	v_mfma_f32_16x16x32_bf16 v[28:31], v[36:39], v[212:215], v[28:31]
	v_mfma_f32_16x16x32_bf16 v[24:27], v[182:185], v[212:215], v[24:27]
	v_mfma_f32_16x16x32_bf16 v[12:15], v[36:39], v[220:223], v[12:15]
	v_mfma_f32_16x16x32_bf16 v[8:11], v[182:185], v[220:223], v[8:11]
	s_barrier
	s_setprio 0
	s_add_u32 vcc_lo, s84, 0x80000
	s_addc_u32 vcc_hi, s85, 0
	s_add_i32 s73, s56, s31
	v_lshl_add_u64 v[32:33], vcc, 0, v[138:139]
	s_mov_b32 m0, s73
	s_nop 0
	global_load_lds_dwordx4 v[32:33], off
	v_lshl_add_u64 v[32:33], vcc, 0, v[142:143]
	s_add_i32 m0, s73, 0x2000
	s_nop 0
	global_load_lds_dwordx4 v[32:33], off
	s_waitcnt vmcnt(6)
	s_setprio 1
	s_barrier
; #define PG8_STAGE(bufoff, gbase, voff) do { _Pragma("unroll") for (int _i = 0; _i < 2; ++_i) \
;         __builtin_amdgcn_global_load_lds((const unsigned*)((const char*)(gbase) + (voff)[_i]), (LAS unsigned*)(lds + (bufoff) + ldsw + _i * 8192), 16, 0, 0); } while (0)
; #define PG8_LDA(dst, b, h) do { _Pragma("unroll") for (int m = 0; m < 4; ++m) _Pragma("unroll") for (int k = 0; k < 2; ++k) dst[m][k] = *(const LAS bf16x8*)(lds + PG8_SA(b, h) + aoff + m * 2048 + k * 1024); } while (0)
; #define PG8_LDB(dst, b, h) do { _Pragma("unroll") for (int n = 0; n < 2; ++n) _Pragma("unroll") for (int k = 0; k < 2; ++k) dst[n][k] = *(const LAS bf16x8*)(lds + PG8_SB(b, h) + boff + n * 2048 + k * 1024); } while (0)
; #define PG8_MMA(ai, bj, At, Bt) do { __builtin_amdgcn_s_setprio(1); _Pragma("unroll") for (int m = 0; m < 4; ++m) _Pragma("unroll") for (int n = 0; n < 2; ++n) _Pragma("unroll") for (int k = 0; k < 2; ++k) \
;         acc[ai][bj][m][n] = __builtin_amdgcn_mfma_f32_16x16x32_bf16(Bt[n][k], At[m][k], acc[ai][bj][m][n], 0, 0, 0); __builtin_amdgcn_s_setprio(0); } while (0)
; #define PG8_WAIT_V(n) asm volatile("s_waitcnt vmcnt(" #n ")" ::: "memory")
; #define PG8_WAIT_L(n) asm volatile("s_waitcnt lgkmcnt(" #n ")" ::: "memory")
; #define PG8_BAR __builtin_amdgcn_s_barrier()
; #define PG8_SCHED __builtin_amdgcn_sched_barrier(0)
; template <class Epi, class Sched, bool ATILE = false>
; __device__ __forceinline__ void gemm_phase(LAS unsigned char* lds, const Gemm g, const Sched& S, const Epi& E) {
;     ...
;             PG8_WAIT_V(6); PG8_BAR; PG8_MMA(1, 1, At, B1); PG8_BAR;
;             PG8_LDB(B0, 1, 0); PG8_SCHED; PG8_LDA(At, 1, 0); PG8_STAGE(PG8_SA(0, 1), a2 + hstepA, voffA);
;             PG8_WAIT_L(8); PG8_BAR; PG8_WAIT_L(0); PG8_MMA(0, 0, At, B0); PG8_BAR; PG8_SCHED;
;             PG8_LDB(B1, 1, 1); PG8_STAGE(PG8_SB(1, 0), b3, voffB);
;             PG8_BAR; PG8_WAIT_L(0); PG8_MMA(0, 1, At, B1); PG8_BAR;
	v_mfma_f32_16x16x32_bf16 v[44:47], v[224:227], v[200:203], v[44:47]
	v_mfma_f32_16x16x32_bf16 v[40:43], v[232:235], v[200:203], v[40:43]
	v_mfma_f32_16x16x32_bf16 v[20:23], v[224:227], v[208:211], v[20:23]
	v_mfma_f32_16x16x32_bf16 v[16:19], v[232:235], v[208:211], v[16:19]
	v_mfma_f32_16x16x32_bf16 v[4:7], v[224:227], v[216:219], v[4:7]
	v_mfma_f32_16x16x32_bf16 v[0:3], v[232:235], v[216:219], v[0:3]
	v_mfma_f32_16x16x32_bf16 v[32:35], v[224:227], v[192:195], v[60:63]
	v_mfma_f32_16x16x32_bf16 v[36:39], v[232:235], v[192:195], v[56:59]
	v_mfma_f32_16x16x32_bf16 v[44:47], v[228:231], v[204:207], v[44:47]
	v_mfma_f32_16x16x32_bf16 v[40:43], v[236:239], v[204:207], v[40:43]
	v_mfma_f32_16x16x32_bf16 v[20:23], v[228:231], v[212:215], v[20:23]
	v_mfma_f32_16x16x32_bf16 v[16:19], v[236:239], v[212:215], v[16:19]
	v_mfma_f32_16x16x32_bf16 v[4:7], v[228:231], v[220:223], v[4:7]
	v_mfma_f32_16x16x32_bf16 v[0:3], v[236:239], v[220:223], v[0:3]
	v_mfma_f32_16x16x32_bf16 v[32:35], v[228:231], v[196:199], v[32:35]
	v_mfma_f32_16x16x32_bf16 v[36:39], v[236:239], v[196:199], v[36:39]
	s_barrier
	s_setprio 0
	s_add_i32 s73, 0, 0x18000
	v_add_u32_e32 v144, s73, v161
	ds_read_b128 v[56:59], v144
	ds_read_b128 v[60:63], v144 offset:1024
	ds_read_b128 v[178:181], v144 offset:2048
	ds_read_b128 v[182:185], v144 offset:3072
	s_add_u32 s86, s86, 0x80000
	s_addc_u32 s87, s87, 0
	s_mov_b32 m0, s39
	ds_read_b128 v[192:195], v167 offset:32768
	ds_read_b128 v[196:199], v167 offset:33792
	ds_read_b128 v[200:203], v167 offset:34816
	ds_read_b128 v[204:207], v167 offset:35840
	ds_read_b128 v[208:211], v167 offset:36864
	ds_read_b128 v[212:215], v167 offset:37888
	ds_read_b128 v[216:219], v167 offset:38912
	ds_read_b128 v[220:223], v167 offset:39936
	global_load_lds_dwordx4 v136, s[86:87]
	s_mov_b32 m0, s97
	s_nop 0
	global_load_lds_dwordx4 v140, s[86:87]
	s_waitcnt lgkmcnt(8)
	s_setprio 1
	s_barrier
	s_waitcnt lgkmcnt(0)
	v_mfma_f32_16x16x32_bf16 v[132:135], v[56:59], v[192:195], v[132:135]
	v_mfma_f32_16x16x32_bf16 v[128:131], v[178:181], v[192:195], v[128:131]
	v_mfma_f32_16x16x32_bf16 v[116:119], v[56:59], v[200:203], v[116:119]
	v_mfma_f32_16x16x32_bf16 v[112:115], v[178:181], v[200:203], v[112:115]
	v_mfma_f32_16x16x32_bf16 v[100:103], v[56:59], v[208:211], v[100:103]
	v_mfma_f32_16x16x32_bf16 v[96:99], v[178:181], v[208:211], v[96:99]
	v_mfma_f32_16x16x32_bf16 v[84:87], v[56:59], v[216:219], v[84:87]
	v_mfma_f32_16x16x32_bf16 v[80:83], v[178:181], v[216:219], v[80:83]
	v_mfma_f32_16x16x32_bf16 v[132:135], v[60:63], v[196:199], v[132:135]
	v_mfma_f32_16x16x32_bf16 v[128:131], v[182:185], v[196:199], v[128:131]
	v_mfma_f32_16x16x32_bf16 v[116:119], v[60:63], v[204:207], v[116:119]
	v_mfma_f32_16x16x32_bf16 v[112:115], v[182:185], v[204:207], v[112:115]
	v_mfma_f32_16x16x32_bf16 v[100:103], v[60:63], v[212:215], v[100:103]
	v_mfma_f32_16x16x32_bf16 v[96:99], v[182:185], v[212:215], v[96:99]
	v_mfma_f32_16x16x32_bf16 v[84:87], v[60:63], v[220:223], v[84:87]
	v_mfma_f32_16x16x32_bf16 v[80:83], v[182:185], v[220:223], v[80:83]
	s_barrier
	s_setprio 0
	s_add_i32 s86, 0, 0x1c000
	s_add_i32 s73, s73, s31
	v_add_u32_e32 v144, s86, v161
	s_mov_b32 m0, s73
	ds_read_b128 v[224:227], v144
	ds_read_b128 v[228:231], v144 offset:1024
	ds_read_b128 v[232:235], v144 offset:2048
	ds_read_b128 v[236:239], v144 offset:3072
	global_load_lds_dwordx4 v138, s[98:99]
	s_add_i32 m0, s73, 0x2000
	s_nop 0
	global_load_lds_dwordx4 v142, s[98:99]
	s_setprio 1
	s_barrier
; #define PG8_STAGE(bufoff, gbase, voff) do { _Pragma("unroll") for (int _i = 0; _i < 2; ++_i) \
;         __builtin_amdgcn_global_load_lds((const unsigned*)((const char*)(gbase) + (voff)[_i]), (LAS unsigned*)(lds + (bufoff) + ldsw + _i * 8192), 16, 0, 0); } while (0)
; #define PG8_LDA(dst, b, h) do { _Pragma("unroll") for (int m = 0; m < 4; ++m) _Pragma("unroll") for (int k = 0; k < 2; ++k) dst[m][k] = *(const LAS bf16x8*)(lds + PG8_SA(b, h) + aoff + m * 2048 + k * 1024); } while (0)
; #define PG8_MMA(ai, bj, At, Bt) do { __builtin_amdgcn_s_setprio(1); _Pragma("unroll") for (int m = 0; m < 4; ++m) _Pragma("unroll") for (int n = 0; n < 2; ++n) _Pragma("unroll") for (int k = 0; k < 2; ++k) \
;         acc[ai][bj][m][n] = __builtin_amdgcn_mfma_f32_16x16x32_bf16(Bt[n][k], At[m][k], acc[ai][bj][m][n], 0, 0, 0); __builtin_amdgcn_s_setprio(0); } while (0)
; #define PG8_WAIT_V(n) asm volatile("s_waitcnt vmcnt(" #n ")" ::: "memory")
; #define PG8_WAIT_L(n) asm volatile("s_waitcnt lgkmcnt(" #n ")" ::: "memory")
; #define PG8_BAR __builtin_amdgcn_s_barrier()
; #define PG8_SCHED __builtin_amdgcn_sched_barrier(0)
; template <class Epi, class Sched, bool ATILE = false>
; __device__ __forceinline__ void gemm_phase(LAS unsigned char* lds, const Gemm g, const Sched& S, const Epi& E) {
;     ...
;             PG8_BAR; PG8_WAIT_L(0); PG8_MMA(0, 1, At, B1); PG8_BAR;
;             PG8_LDA(At, 1, 1); PG8_STAGE(PG8_SA(1, 0), a3, voffA);
;             PG8_BAR; PG8_WAIT_L(0); PG8_MMA(1, 0, At, B0); PG8_BAR; PG8_SCHED;
;             PG8_STAGE(PG8_SB(1, 1), b3 + hstepB, voffB);
;             PG8_WAIT_V(6); PG8_BAR; PG8_MMA(1, 1, At, B1); PG8_BAR;
;         }
	s_waitcnt lgkmcnt(0)
	v_mfma_f32_16x16x32_bf16 v[124:127], v[224:227], v[192:195], v[124:127]
	v_mfma_f32_16x16x32_bf16 v[120:123], v[232:235], v[192:195], v[120:123]
	v_mfma_f32_16x16x32_bf16 v[108:111], v[224:227], v[200:203], v[108:111]
	v_mfma_f32_16x16x32_bf16 v[104:107], v[232:235], v[200:203], v[104:107]
	v_mfma_f32_16x16x32_bf16 v[92:95], v[224:227], v[208:211], v[92:95]
	v_mfma_f32_16x16x32_bf16 v[88:91], v[232:235], v[208:211], v[88:91]
	v_mfma_f32_16x16x32_bf16 v[76:79], v[224:227], v[216:219], v[76:79]
	v_mfma_f32_16x16x32_bf16 v[72:75], v[232:235], v[216:219], v[72:75]
	v_mfma_f32_16x16x32_bf16 v[124:127], v[228:231], v[196:199], v[124:127]
	v_mfma_f32_16x16x32_bf16 v[120:123], v[236:239], v[196:199], v[120:123]
	v_mfma_f32_16x16x32_bf16 v[108:111], v[228:231], v[204:207], v[108:111]
	v_mfma_f32_16x16x32_bf16 v[104:107], v[236:239], v[204:207], v[104:107]
	v_mfma_f32_16x16x32_bf16 v[92:95], v[228:231], v[212:215], v[92:95]
	v_mfma_f32_16x16x32_bf16 v[88:91], v[236:239], v[212:215], v[88:91]
	v_mfma_f32_16x16x32_bf16 v[76:79], v[228:231], v[220:223], v[76:79]
	v_mfma_f32_16x16x32_bf16 v[72:75], v[236:239], v[220:223], v[72:75]
	s_barrier
	s_setprio 0
	s_mov_b32 m0, s4
	ds_read_b128 v[192:195], v167 offset:49152
	ds_read_b128 v[196:199], v167 offset:50176
	ds_read_b128 v[200:203], v167 offset:51200
	ds_read_b128 v[204:207], v167 offset:52224
	ds_read_b128 v[208:211], v167 offset:53248
	ds_read_b128 v[212:215], v167 offset:54272
	ds_read_b128 v[216:219], v167 offset:55296
	ds_read_b128 v[220:223], v167 offset:56320
	global_load_lds_dwordx4 v136, s[100:101]
	s_mov_b32 m0, s5
	s_nop 0
	global_load_lds_dwordx4 v140, s[100:101]
	s_setprio 1
	s_barrier
	s_waitcnt lgkmcnt(0)
	v_mfma_f32_16x16x32_bf16 v[68:71], v[56:59], v[192:195], v[68:71]
	v_mfma_f32_16x16x32_bf16 v[64:67], v[178:181], v[192:195], v[64:67]
	v_mfma_f32_16x16x32_bf16 v[52:55], v[56:59], v[200:203], v[52:55]
	v_mfma_f32_16x16x32_bf16 v[48:51], v[178:181], v[200:203], v[48:51]
	v_mfma_f32_16x16x32_bf16 v[28:31], v[56:59], v[208:211], v[28:31]
	v_mfma_f32_16x16x32_bf16 v[24:27], v[178:181], v[208:211], v[24:27]
	v_mfma_f32_16x16x32_bf16 v[12:15], v[56:59], v[216:219], v[12:15]
	v_mfma_f32_16x16x32_bf16 v[8:11], v[178:181], v[216:219], v[8:11]
	v_mfma_f32_16x16x32_bf16 v[68:71], v[60:63], v[196:199], v[68:71]
	v_mfma_f32_16x16x32_bf16 v[64:67], v[182:185], v[196:199], v[64:67]
	v_mfma_f32_16x16x32_bf16 v[52:55], v[60:63], v[204:207], v[52:55]
	v_mfma_f32_16x16x32_bf16 v[48:51], v[182:185], v[204:207], v[48:51]
	v_mfma_f32_16x16x32_bf16 v[28:31], v[60:63], v[212:215], v[28:31]
	v_mfma_f32_16x16x32_bf16 v[24:27], v[182:185], v[212:215], v[24:27]
	v_mfma_f32_16x16x32_bf16 v[12:15], v[60:63], v[220:223], v[12:15]
	v_mfma_f32_16x16x32_bf16 v[8:11], v[182:185], v[220:223], v[8:11]
	s_barrier
	s_setprio 0
	s_add_u32 s84, s84, 0x80080
	s_addc_u32 s85, s85, 0
	s_add_i32 s73, s86, s31
	s_mov_b32 m0, s73
	s_nop 0
	global_load_lds_dwordx4 v138, s[84:85]
	s_add_i32 m0, s73, 0x2000
	s_nop 0
	global_load_lds_dwordx4 v142, s[84:85]
	s_waitcnt vmcnt(6)
	s_setprio 1
	s_barrier
	v_mfma_f32_16x16x32_bf16 v[32:35], v[224:227], v[192:195], v[32:35]
	v_mfma_f32_16x16x32_bf16 v[60:63], v[228:231], v[196:199], v[32:35]
	v_mfma_f32_16x16x32_bf16 v[32:35], v[232:235], v[192:195], v[36:39]
	v_mfma_f32_16x16x32_bf16 v[56:59], v[236:239], v[196:199], v[32:35]
	v_mfma_f32_16x16x32_bf16 v[32:35], v[224:227], v[200:203], v[44:47]
	v_mfma_f32_16x16x32_bf16 v[44:47], v[228:231], v[204:207], v[32:35]
	v_mfma_f32_16x16x32_bf16 v[32:35], v[232:235], v[200:203], v[40:43]
	s_add_u32 s12, s12, 0x100
	v_mfma_f32_16x16x32_bf16 v[20:23], v[224:227], v[208:211], v[20:23]
	s_addc_u32 s13, s13, 0
	v_mfma_f32_16x16x32_bf16 v[16:19], v[232:235], v[208:211], v[16:19]
	s_add_u32 s62, s62, 0x100
	v_mfma_f32_16x16x32_bf16 v[4:7], v[224:227], v[216:219], v[4:7]
	s_addc_u32 s63, s63, 0
	v_mfma_f32_16x16x32_bf16 v[0:3], v[232:235], v[216:219], v[0:3]
	s_cmp_ge_i32 s88, s1
	v_mfma_f32_16x16x32_bf16 v[40:43], v[236:239], v[204:207], v[32:35]
	s_mov_b32 s73, s88
	v_mfma_f32_16x16x32_bf16 v[20:23], v[228:231], v[212:215], v[20:23]
	v_mfma_f32_16x16x32_bf16 v[16:19], v[236:239], v[212:215], v[16:19]
	v_mfma_f32_16x16x32_bf16 v[4:7], v[228:231], v[220:223], v[4:7]
	v_mfma_f32_16x16x32_bf16 v[0:3], v[236:239], v[220:223], v[0:3]
	s_barrier
	s_setprio 0
	s_cbranch_scc0 .LBB0_895
	s_nop 5
	s_branch .LBB0_897

; #define PG8_STAGE(bufoff, gbase, voff) do { _Pragma("unroll") for (int _i = 0; _i < 2; ++_i) \
;         __builtin_amdgcn_global_load_lds((const unsigned*)((const char*)(gbase) + (voff)[_i]), (LAS unsigned*)(lds + (bufoff) + ldsw + _i * 8192), 16, 0, 0); } while (0)
; #define PG8_LDA(dst, b, h) do { _Pragma("unroll") for (int m = 0; m < 4; ++m) _Pragma("unroll") for (int k = 0; k < 2; ++k) dst[m][k] = *(const LAS bf16x8*)(lds + PG8_SA(b, h) + aoff + m * 2048 + k * 1024); } while (0)
; #define PG8_LDB(dst, b, h) do { _Pragma("unroll") for (int n = 0; n < 2; ++n) _Pragma("unroll") for (int k = 0; k < 2; ++k) dst[n][k] = *(const LAS bf16x8*)(lds + PG8_SB(b, h) + boff + n * 2048 + k * 1024); } while (0)
; #define PG8_MMA(ai, bj, At, Bt) do { __builtin_amdgcn_s_setprio(1); _Pragma("unroll") for (int m = 0; m < 4; ++m) _Pragma("unroll") for (int n = 0; n < 2; ++n) _Pragma("unroll") for (int k = 0; k < 2; ++k) \
;         acc[ai][bj][m][n] = __builtin_amdgcn_mfma_f32_16x16x32_bf16(Bt[n][k], At[m][k], acc[ai][bj][m][n], 0, 0, 0); __builtin_amdgcn_s_setprio(0); } while (0)
; #define PG8_WAIT_V(n) asm volatile("s_waitcnt vmcnt(" #n ")" ::: "memory")
; #define PG8_WAIT_L(n) asm volatile("s_waitcnt lgkmcnt(" #n ")" ::: "memory")
; template <class Epi, class Sched, bool ATILE = false>
; __device__ __forceinline__ void gemm_phase(LAS unsigned char* lds, const Gemm g, const Sched& S, const Epi& E) {
;     ...
;         for (int t = 0; t < nt; t += 2) {
;             const bool last = (t == nt - 2);
;             const char* a1 = cA + (size_t)(t + 1) * kstepA;
;             const char* a2 = last ? nA : cA + (size_t)(t + 2) * kstepA; const char* b2 = last ? nB : cB + (size_t)(t + 2) * kstep;
;             const char* a3 = a2 + kstepA; const char* b3 = b2 + kstep;
;             PG8_LDB(B0, 0, 0); PG8_SCHED; PG8_LDA(At, 0, 0); PG8_STAGE(PG8_SA(1, 1), a1 + hstepA, voffA);
;             PG8_WAIT_L(8); PG8_BAR; PG8_WAIT_L(0); PG8_MMA(0, 0, At, B0); PG8_BAR; PG8_SCHED;
;             PG8_LDB(B1, 0, 1); PG8_STAGE(PG8_SB(0, 0), b2, voffB);
;             PG8_BAR; PG8_WAIT_L(0); PG8_MMA(0, 1, At, B1); PG8_BAR;
;             PG8_LDA(At, 0, 1); PG8_STAGE(PG8_SA(0, 0), a2, voffA);
;             PG8_BAR; PG8_WAIT_L(0); PG8_MMA(1, 0, At, B0); PG8_BAR; PG8_SCHED;
;             PG8_STAGE(PG8_SB(0, 1), b2 + hstepB, voffB);
;             PG8_WAIT_V(6); PG8_BAR; PG8_MMA(1, 1, At, B1); PG8_BAR;
.LBB0_1426:
	ds_read_b128 v[162:165], v147
	ds_read_b128 v[166:169], v147 offset:1024
	ds_read_b128 v[170:173], v147 offset:2048
	ds_read_b128 v[174:177], v147 offset:3072
	s_add_i32 s58, s18, 2
	s_add_u32 s16, s12, 0x100
	s_addc_u32 s17, s13, 0
	s_cmp_eq_u32 s55, s18
	s_cselect_b32 s18, s10, s56
	s_cselect_b32 s21, s7, s17
	s_cselect_b32 s20, s6, s16
	s_cselect_b32 s19, s11, s57
	s_mov_b32 m0, s30
	v_lshl_add_u64 v[144:145], s[12:13], 0, v[140:141]
	ds_read_b128 v[178:181], v148
	ds_read_b128 v[182:185], v148 offset:1024
	ds_read_b128 v[186:189], v148 offset:2048
	ds_read_b128 v[190:193], v148 offset:3072
	ds_read_b128 v[194:197], v148 offset:4096
	ds_read_b128 v[198:201], v148 offset:5120
	ds_read_b128 v[202:205], v148 offset:6144
	ds_read_b128 v[206:209], v148 offset:7168
	global_load_lds_dwordx4 v[144:145], off
	v_lshl_add_u64 v[144:145], s[12:13], 0, v[142:143]
	s_mov_b32 m0, s31
	s_nop 0
	global_load_lds_dwordx4 v[144:145], off
	s_waitcnt lgkmcnt(8)
	s_setprio 1
	s_barrier
	s_waitcnt lgkmcnt(0)
	v_mfma_f32_16x16x32_bf16 v[124:127], v[162:165], v[178:181], v[124:127]
	v_mfma_f32_16x16x32_bf16 v[120:123], v[170:173], v[178:181], v[120:123]
	v_mfma_f32_16x16x32_bf16 v[108:111], v[162:165], v[186:189], v[108:111]
	v_mfma_f32_16x16x32_bf16 v[104:107], v[170:173], v[186:189], v[104:107]
	v_mfma_f32_16x16x32_bf16 v[92:95], v[162:165], v[194:197], v[92:95]
	v_mfma_f32_16x16x32_bf16 v[88:91], v[170:173], v[194:197], v[88:91]
	v_mfma_f32_16x16x32_bf16 v[76:79], v[162:165], v[202:205], v[76:79]
	v_mfma_f32_16x16x32_bf16 v[72:75], v[170:173], v[202:205], v[72:75]
	v_mfma_f32_16x16x32_bf16 v[124:127], v[166:169], v[182:185], v[124:127]
	v_mfma_f32_16x16x32_bf16 v[120:123], v[174:177], v[182:185], v[120:123]
	v_mfma_f32_16x16x32_bf16 v[108:111], v[166:169], v[190:193], v[108:111]
	v_mfma_f32_16x16x32_bf16 v[104:107], v[174:177], v[190:193], v[104:107]
	v_mfma_f32_16x16x32_bf16 v[92:95], v[166:169], v[198:201], v[92:95]
	v_mfma_f32_16x16x32_bf16 v[88:91], v[174:177], v[198:201], v[88:91]
	v_mfma_f32_16x16x32_bf16 v[76:79], v[166:169], v[206:209], v[76:79]
	v_mfma_f32_16x16x32_bf16 v[72:75], v[174:177], v[206:209], v[72:75]
	s_barrier
	s_setprio 0
	s_mov_b32 m0, s33
	v_lshl_add_u64 v[144:145], s[18:19], 0, v[132:133]
	ds_read_b128 v[210:213], v149
	ds_read_b128 v[214:217], v149 offset:1024
	ds_read_b128 v[218:221], v149 offset:2048
	ds_read_b128 v[222:225], v149 offset:3072
	global_load_lds_dwordx4 v[144:145], off
	v_lshl_add_u64 v[226:227], s[18:19], 0, v[128:129]
	s_mov_b32 m0, s34
	s_nop 0
	global_load_lds_dwordx4 v[226:227], off
	s_setprio 1
	s_barrier
	s_waitcnt lgkmcnt(0)
	v_mfma_f32_16x16x32_bf16 v[116:119], v[210:213], v[178:181], v[116:119]
	v_mfma_f32_16x16x32_bf16 v[112:115], v[218:221], v[178:181], v[112:115]
	v_mfma_f32_16x16x32_bf16 v[100:103], v[210:213], v[186:189], v[100:103]
	v_mfma_f32_16x16x32_bf16 v[96:99], v[218:221], v[186:189], v[96:99]
	v_mfma_f32_16x16x32_bf16 v[84:87], v[210:213], v[194:197], v[84:87]
	v_mfma_f32_16x16x32_bf16 v[80:83], v[218:221], v[194:197], v[80:83]
	v_mfma_f32_16x16x32_bf16 v[68:71], v[210:213], v[202:205], v[68:71]
	v_mfma_f32_16x16x32_bf16 v[64:67], v[218:221], v[202:205], v[64:67]
	v_mfma_f32_16x16x32_bf16 v[116:119], v[214:217], v[182:185], v[116:119]
	v_mfma_f32_16x16x32_bf16 v[112:115], v[222:225], v[182:185], v[112:115]
	v_mfma_f32_16x16x32_bf16 v[100:103], v[214:217], v[190:193], v[100:103]
	v_mfma_f32_16x16x32_bf16 v[96:99], v[222:225], v[190:193], v[96:99]
	v_mfma_f32_16x16x32_bf16 v[84:87], v[214:217], v[198:201], v[84:87]
	v_mfma_f32_16x16x32_bf16 v[80:83], v[222:225], v[198:201], v[80:83]
	v_mfma_f32_16x16x32_bf16 v[68:71], v[214:217], v[206:209], v[68:71]
	v_mfma_f32_16x16x32_bf16 v[64:67], v[222:225], v[206:209], v[64:67]
	s_barrier
	s_setprio 0
	s_mov_b32 m0, s22
	v_lshl_add_u64 v[228:229], s[20:21], 0, v[134:135]
	ds_read_b128 v[178:181], v148 offset:16384
	ds_read_b128 v[182:185], v148 offset:17408
	ds_read_b128 v[186:189], v148 offset:18432
	ds_read_b128 v[190:193], v148 offset:19456
	ds_read_b128 v[194:197], v148 offset:20480
	ds_read_b128 v[198:201], v148 offset:21504
	ds_read_b128 v[202:205], v148 offset:22528
	ds_read_b128 v[206:209], v148 offset:23552
	global_load_lds_dwordx4 v[228:229], off
	v_lshl_add_u64 v[230:231], s[20:21], 0, v[130:131]
	s_mov_b32 m0, s23
	s_nop 0
	global_load_lds_dwordx4 v[230:231], off
	s_setprio 1
	s_barrier
	s_waitcnt lgkmcnt(0)
	v_mfma_f32_16x16x32_bf16 v[60:63], v[162:165], v[178:181], v[60:63]
	v_mfma_f32_16x16x32_bf16 v[56:59], v[170:173], v[178:181], v[56:59]
	v_mfma_f32_16x16x32_bf16 v[44:47], v[162:165], v[186:189], v[44:47]
	v_mfma_f32_16x16x32_bf16 v[40:43], v[170:173], v[186:189], v[40:43]
	v_mfma_f32_16x16x32_bf16 v[28:31], v[162:165], v[194:197], v[28:31]
	v_mfma_f32_16x16x32_bf16 v[24:27], v[170:173], v[194:197], v[24:27]
	v_mfma_f32_16x16x32_bf16 v[12:15], v[162:165], v[202:205], v[12:15]
	v_mfma_f32_16x16x32_bf16 v[8:11], v[170:173], v[202:205], v[8:11]
	v_mfma_f32_16x16x32_bf16 v[60:63], v[166:169], v[182:185], v[60:63]
	v_mfma_f32_16x16x32_bf16 v[56:59], v[174:177], v[182:185], v[56:59]
	v_mfma_f32_16x16x32_bf16 v[44:47], v[166:169], v[190:193], v[44:47]
	v_mfma_f32_16x16x32_bf16 v[40:43], v[174:177], v[190:193], v[40:43]
	v_mfma_f32_16x16x32_bf16 v[28:31], v[166:169], v[198:201], v[28:31]
	v_mfma_f32_16x16x32_bf16 v[24:27], v[174:177], v[198:201], v[24:27]
	v_mfma_f32_16x16x32_bf16 v[12:15], v[166:169], v[206:209], v[12:15]
	v_mfma_f32_16x16x32_bf16 v[8:11], v[174:177], v[206:209], v[8:11]
	s_barrier
	s_setprio 0
	s_add_u32 s12, s18, 0x18000
	s_addc_u32 s13, s19, 0
	s_mov_b32 m0, s35
	s_nop 0
	global_load_lds_dwordx4 v132, s[12:13]
	s_mov_b32 m0, s36
	s_nop 0
	global_load_lds_dwordx4 v128, s[12:13]
	s_waitcnt vmcnt(6)
	s_setprio 1
	s_barrier
; #define PG8_STAGE(bufoff, gbase, voff) do { _Pragma("unroll") for (int _i = 0; _i < 2; ++_i) \
;         __builtin_amdgcn_global_load_lds((const unsigned*)((const char*)(gbase) + (voff)[_i]), (LAS unsigned*)(lds + (bufoff) + ldsw + _i * 8192), 16, 0, 0); } while (0)
; #define PG8_LDA(dst, b, h) do { _Pragma("unroll") for (int m = 0; m < 4; ++m) _Pragma("unroll") for (int k = 0; k < 2; ++k) dst[m][k] = *(const LAS bf16x8*)(lds + PG8_SA(b, h) + aoff + m * 2048 + k * 1024); } while (0)
; #define PG8_LDB(dst, b, h) do { _Pragma("unroll") for (int n = 0; n < 2; ++n) _Pragma("unroll") for (int k = 0; k < 2; ++k) dst[n][k] = *(const LAS bf16x8*)(lds + PG8_SB(b, h) + boff + n * 2048 + k * 1024); } while (0)
; #define PG8_MMA(ai, bj, At, Bt) do { __builtin_amdgcn_s_setprio(1); _Pragma("unroll") for (int m = 0; m < 4; ++m) _Pragma("unroll") for (int n = 0; n < 2; ++n) _Pragma("unroll") for (int k = 0; k < 2; ++k) \
;         acc[ai][bj][m][n] = __builtin_amdgcn_mfma_f32_16x16x32_bf16(Bt[n][k], At[m][k], acc[ai][bj][m][n], 0, 0, 0); __builtin_amdgcn_s_setprio(0); } while (0)
; #define PG8_WAIT_V(n) asm volatile("s_waitcnt vmcnt(" #n ")" ::: "memory")
; #define PG8_WAIT_L(n) asm volatile("s_waitcnt lgkmcnt(" #n ")" ::: "memory")
; #define PG8_BAR __builtin_amdgcn_s_barrier()
; #define PG8_SCHED __builtin_amdgcn_sched_barrier(0)
; template <class Epi, class Sched, bool ATILE = false>
; __device__ __forceinline__ void gemm_phase(LAS unsigned char* lds, const Gemm g, const Sched& S, const Epi& E) {
;     ...
;             PG8_WAIT_V(6); PG8_BAR; PG8_MMA(1, 1, At, B1); PG8_BAR;
;             PG8_LDB(B0, 1, 0); PG8_SCHED; PG8_LDA(At, 1, 0); PG8_STAGE(PG8_SA(0, 1), a2 + hstepA, voffA);
;             PG8_WAIT_L(8); PG8_BAR; PG8_WAIT_L(0); PG8_MMA(0, 0, At, B0); PG8_BAR; PG8_SCHED;
;             PG8_LDB(B1, 1, 1); PG8_STAGE(PG8_SB(1, 0), b3, voffB);
;             PG8_BAR; PG8_WAIT_L(0); PG8_MMA(0, 1, At, B1); PG8_BAR;
	v_mfma_f32_16x16x32_bf16 v[52:55], v[210:213], v[178:181], v[52:55]
	v_mfma_f32_16x16x32_bf16 v[48:51], v[218:221], v[178:181], v[48:51]
	v_mfma_f32_16x16x32_bf16 v[36:39], v[210:213], v[186:189], v[36:39]
	v_mfma_f32_16x16x32_bf16 v[32:35], v[218:221], v[186:189], v[32:35]
	v_mfma_f32_16x16x32_bf16 v[20:23], v[210:213], v[194:197], v[20:23]
	v_mfma_f32_16x16x32_bf16 v[16:19], v[218:221], v[194:197], v[16:19]
	v_mfma_f32_16x16x32_bf16 v[4:7], v[210:213], v[202:205], v[4:7]
	v_mfma_f32_16x16x32_bf16 v[0:3], v[218:221], v[202:205], v[0:3]
	v_mfma_f32_16x16x32_bf16 v[52:55], v[214:217], v[182:185], v[52:55]
	v_mfma_f32_16x16x32_bf16 v[48:51], v[222:225], v[182:185], v[48:51]
	v_mfma_f32_16x16x32_bf16 v[36:39], v[214:217], v[190:193], v[36:39]
	v_mfma_f32_16x16x32_bf16 v[32:35], v[222:225], v[190:193], v[32:35]
	v_mfma_f32_16x16x32_bf16 v[20:23], v[214:217], v[198:201], v[20:23]
	v_mfma_f32_16x16x32_bf16 v[16:19], v[222:225], v[198:201], v[16:19]
	v_mfma_f32_16x16x32_bf16 v[4:7], v[214:217], v[206:209], v[4:7]
	v_mfma_f32_16x16x32_bf16 v[0:3], v[222:225], v[206:209], v[0:3]
	s_barrier
	s_setprio 0
	ds_read_b128 v[162:165], v150
	ds_read_b128 v[166:169], v150 offset:1024
	ds_read_b128 v[170:173], v150 offset:2048
	ds_read_b128 v[174:177], v150 offset:3072
	s_add_u32 s12, s20, 0x18000
	s_addc_u32 s13, s21, 0
	s_mov_b32 m0, s24
	ds_read_b128 v[178:181], v148 offset:32768
	ds_read_b128 v[182:185], v148 offset:33792
	ds_read_b128 v[186:189], v148 offset:34816
	ds_read_b128 v[190:193], v148 offset:35840
	ds_read_b128 v[194:197], v148 offset:36864
	ds_read_b128 v[198:201], v148 offset:37888
	ds_read_b128 v[202:205], v148 offset:38912
	ds_read_b128 v[206:209], v148 offset:39936
	global_load_lds_dwordx4 v134, s[12:13]
	s_mov_b32 m0, s25
	s_nop 0
	global_load_lds_dwordx4 v130, s[12:13]
	s_waitcnt lgkmcnt(8)
	s_setprio 1
	s_barrier
	s_waitcnt lgkmcnt(0)
	v_mfma_f32_16x16x32_bf16 v[124:127], v[162:165], v[178:181], v[124:127]
	v_mfma_f32_16x16x32_bf16 v[120:123], v[170:173], v[178:181], v[120:123]
	v_mfma_f32_16x16x32_bf16 v[108:111], v[162:165], v[186:189], v[108:111]
	v_mfma_f32_16x16x32_bf16 v[104:107], v[170:173], v[186:189], v[104:107]
	v_mfma_f32_16x16x32_bf16 v[92:95], v[162:165], v[194:197], v[92:95]
	v_mfma_f32_16x16x32_bf16 v[88:91], v[170:173], v[194:197], v[88:91]
	v_mfma_f32_16x16x32_bf16 v[76:79], v[162:165], v[202:205], v[76:79]
	v_mfma_f32_16x16x32_bf16 v[72:75], v[170:173], v[202:205], v[72:75]
	v_mfma_f32_16x16x32_bf16 v[124:127], v[166:169], v[182:185], v[124:127]
	v_mfma_f32_16x16x32_bf16 v[120:123], v[174:177], v[182:185], v[120:123]
	v_mfma_f32_16x16x32_bf16 v[108:111], v[166:169], v[190:193], v[108:111]
	v_mfma_f32_16x16x32_bf16 v[104:107], v[174:177], v[190:193], v[104:107]
	v_mfma_f32_16x16x32_bf16 v[92:95], v[166:169], v[198:201], v[92:95]
	v_mfma_f32_16x16x32_bf16 v[88:91], v[174:177], v[198:201], v[88:91]
	v_mfma_f32_16x16x32_bf16 v[76:79], v[166:169], v[206:209], v[76:79]
	v_mfma_f32_16x16x32_bf16 v[72:75], v[174:177], v[206:209], v[72:75]
	s_barrier
	s_setprio 0
	s_mov_b32 m0, s40
	v_lshl_add_u64 v[144:145], v[144:145], 0, s[0:1]
	ds_read_b128 v[210:213], v157
	ds_read_b128 v[214:217], v157 offset:1024
	ds_read_b128 v[218:221], v157 offset:2048
	ds_read_b128 v[222:225], v157 offset:3072
	global_load_lds_dwordx4 v[144:145], off
	v_lshl_add_u64 v[144:145], v[226:227], 0, s[0:1]
	s_mov_b32 m0, s41
	s_nop 0
	global_load_lds_dwordx4 v[144:145], off
	s_setprio 1
	s_barrier
; #define PG8_STAGE(bufoff, gbase, voff) do { _Pragma("unroll") for (int _i = 0; _i < 2; ++_i) \
;         __builtin_amdgcn_global_load_lds((const unsigned*)((const char*)(gbase) + (voff)[_i]), (LAS unsigned*)(lds + (bufoff) + ldsw + _i * 8192), 16, 0, 0); } while (0)
; #define PG8_LDA(dst, b, h) do { _Pragma("unroll") for (int m = 0; m < 4; ++m) _Pragma("unroll") for (int k = 0; k < 2; ++k) dst[m][k] = *(const LAS bf16x8*)(lds + PG8_SA(b, h) + aoff + m * 2048 + k * 1024); } while (0)
; #define PG8_MMA(ai, bj, At, Bt) do { __builtin_amdgcn_s_setprio(1); _Pragma("unroll") for (int m = 0; m < 4; ++m) _Pragma("unroll") for (int n = 0; n < 2; ++n) _Pragma("unroll") for (int k = 0; k < 2; ++k) \
;         acc[ai][bj][m][n] = __builtin_amdgcn_mfma_f32_16x16x32_bf16(Bt[n][k], At[m][k], acc[ai][bj][m][n], 0, 0, 0); __builtin_amdgcn_s_setprio(0); } while (0)
; #define PG8_WAIT_V(n) asm volatile("s_waitcnt vmcnt(" #n ")" ::: "memory")
; #define PG8_WAIT_L(n) asm volatile("s_waitcnt lgkmcnt(" #n ")" ::: "memory")
; #define PG8_BAR __builtin_amdgcn_s_barrier()
; #define PG8_SCHED __builtin_amdgcn_sched_barrier(0)
; template <class Epi, class Sched, bool ATILE = false>
; __device__ __forceinline__ void gemm_phase(LAS unsigned char* lds, const Gemm g, const Sched& S, const Epi& E) {
;     ...
;             PG8_BAR; PG8_WAIT_L(0); PG8_MMA(0, 1, At, B1); PG8_BAR;
;             PG8_LDA(At, 1, 1); PG8_STAGE(PG8_SA(1, 0), a3, voffA);
;             PG8_BAR; PG8_WAIT_L(0); PG8_MMA(1, 0, At, B0); PG8_BAR; PG8_SCHED;
;             PG8_STAGE(PG8_SB(1, 1), b3 + hstepB, voffB);
;             PG8_WAIT_V(6); PG8_BAR; PG8_MMA(1, 1, At, B1); PG8_BAR;
;         }
	s_waitcnt lgkmcnt(0)
	v_mfma_f32_16x16x32_bf16 v[116:119], v[210:213], v[178:181], v[116:119]
	v_mfma_f32_16x16x32_bf16 v[112:115], v[218:221], v[178:181], v[112:115]
	v_mfma_f32_16x16x32_bf16 v[100:103], v[210:213], v[186:189], v[100:103]
	v_mfma_f32_16x16x32_bf16 v[96:99], v[218:221], v[186:189], v[96:99]
	v_mfma_f32_16x16x32_bf16 v[84:87], v[210:213], v[194:197], v[84:87]
	v_mfma_f32_16x16x32_bf16 v[80:83], v[218:221], v[194:197], v[80:83]
	v_mfma_f32_16x16x32_bf16 v[68:71], v[210:213], v[202:205], v[68:71]
	v_mfma_f32_16x16x32_bf16 v[64:67], v[218:221], v[202:205], v[64:67]
	v_mfma_f32_16x16x32_bf16 v[116:119], v[214:217], v[182:185], v[116:119]
	v_mfma_f32_16x16x32_bf16 v[112:115], v[222:225], v[182:185], v[112:115]
	v_mfma_f32_16x16x32_bf16 v[100:103], v[214:217], v[190:193], v[100:103]
	v_mfma_f32_16x16x32_bf16 v[96:99], v[222:225], v[190:193], v[96:99]
	v_mfma_f32_16x16x32_bf16 v[84:87], v[214:217], v[198:201], v[84:87]
	v_mfma_f32_16x16x32_bf16 v[80:83], v[222:225], v[198:201], v[80:83]
	v_mfma_f32_16x16x32_bf16 v[68:71], v[214:217], v[206:209], v[68:71]
	v_mfma_f32_16x16x32_bf16 v[64:67], v[222:225], v[206:209], v[64:67]
	s_barrier
	s_setprio 0
	s_mov_b32 m0, s28
	v_lshl_add_u64 v[144:145], v[228:229], 0, s[0:1]
	ds_read_b128 v[178:181], v148 offset:49152
	ds_read_b128 v[182:185], v148 offset:50176
	ds_read_b128 v[186:189], v148 offset:51200
	ds_read_b128 v[190:193], v148 offset:52224
	ds_read_b128 v[194:197], v148 offset:53248
	ds_read_b128 v[198:201], v148 offset:54272
	ds_read_b128 v[202:205], v148 offset:55296
	ds_read_b128 v[206:209], v148 offset:56320
	global_load_lds_dwordx4 v[144:145], off
	v_lshl_add_u64 v[144:145], v[230:231], 0, s[0:1]
	s_mov_b32 m0, s29
	s_nop 0
	global_load_lds_dwordx4 v[144:145], off
	s_setprio 1
	s_barrier
	s_waitcnt lgkmcnt(0)
	v_mfma_f32_16x16x32_bf16 v[60:63], v[162:165], v[178:181], v[60:63]
	v_mfma_f32_16x16x32_bf16 v[56:59], v[170:173], v[178:181], v[56:59]
	v_mfma_f32_16x16x32_bf16 v[44:47], v[162:165], v[186:189], v[44:47]
	v_mfma_f32_16x16x32_bf16 v[40:43], v[170:173], v[186:189], v[40:43]
	v_mfma_f32_16x16x32_bf16 v[28:31], v[162:165], v[194:197], v[28:31]
	v_mfma_f32_16x16x32_bf16 v[24:27], v[170:173], v[194:197], v[24:27]
	v_mfma_f32_16x16x32_bf16 v[12:15], v[162:165], v[202:205], v[12:15]
	v_mfma_f32_16x16x32_bf16 v[8:11], v[170:173], v[202:205], v[8:11]
	v_mfma_f32_16x16x32_bf16 v[60:63], v[166:169], v[182:185], v[60:63]
	v_mfma_f32_16x16x32_bf16 v[56:59], v[174:177], v[182:185], v[56:59]
	v_mfma_f32_16x16x32_bf16 v[44:47], v[166:169], v[190:193], v[44:47]
	v_mfma_f32_16x16x32_bf16 v[40:43], v[174:177], v[190:193], v[40:43]
	v_mfma_f32_16x16x32_bf16 v[28:31], v[166:169], v[198:201], v[28:31]
	v_mfma_f32_16x16x32_bf16 v[24:27], v[174:177], v[198:201], v[24:27]
	v_mfma_f32_16x16x32_bf16 v[12:15], v[166:169], v[206:209], v[12:15]
	v_mfma_f32_16x16x32_bf16 v[8:11], v[174:177], v[206:209], v[8:11]
	s_barrier
	s_setprio 0
	s_add_u32 s12, s18, 0x18080
	s_addc_u32 s13, s19, 0
	s_mov_b32 m0, s42
	s_nop 0
	global_load_lds_dwordx4 v132, s[12:13]
	s_mov_b32 m0, s43
	s_nop 0
	global_load_lds_dwordx4 v128, s[12:13]
	s_waitcnt vmcnt(6)
	s_setprio 1
	s_barrier
	v_mfma_f32_16x16x32_bf16 v[52:55], v[210:213], v[178:181], v[52:55]
	v_mfma_f32_16x16x32_bf16 v[48:51], v[218:221], v[178:181], v[48:51]
	v_mfma_f32_16x16x32_bf16 v[36:39], v[210:213], v[186:189], v[36:39]
	v_mfma_f32_16x16x32_bf16 v[32:35], v[218:221], v[186:189], v[32:35]
	v_mfma_f32_16x16x32_bf16 v[20:23], v[210:213], v[194:197], v[20:23]
	v_mfma_f32_16x16x32_bf16 v[16:19], v[218:221], v[194:197], v[16:19]
	v_mfma_f32_16x16x32_bf16 v[4:7], v[210:213], v[202:205], v[4:7]
	s_add_u32 s56, s56, 0x100
	v_mfma_f32_16x16x32_bf16 v[0:3], v[218:221], v[202:205], v[0:3]
	s_addc_u32 s57, s57, 0
	v_mfma_f32_16x16x32_bf16 v[52:55], v[214:217], v[182:185], v[52:55]
	s_cmp_ge_i32 s58, s54
	v_mfma_f32_16x16x32_bf16 v[48:51], v[222:225], v[182:185], v[48:51]
	s_mov_b64 s[12:13], s[16:17]
	v_mfma_f32_16x16x32_bf16 v[36:39], v[214:217], v[190:193], v[36:39]
	s_mov_b32 s18, s58
	v_mfma_f32_16x16x32_bf16 v[32:35], v[222:225], v[190:193], v[32:35]
	v_mfma_f32_16x16x32_bf16 v[20:23], v[214:217], v[198:201], v[20:23]
	v_mfma_f32_16x16x32_bf16 v[16:19], v[222:225], v[198:201], v[16:19]
	v_mfma_f32_16x16x32_bf16 v[4:7], v[214:217], v[206:209], v[4:7]
	v_mfma_f32_16x16x32_bf16 v[0:3], v[222:225], v[206:209], v[0:3]
	s_barrier
	s_setprio 0
	s_cbranch_scc0 .LBB0_1426
	s_nop 5
	s_branch .LBB0_1428

; #define PG8_STAGE(bufoff, gbase, voff) do { _Pragma("unroll") for (int _i = 0; _i < 2; ++_i) \
;         __builtin_amdgcn_global_load_lds((const unsigned*)((const char*)(gbase) + (voff)[_i]), (LAS unsigned*)(lds + (bufoff) + ldsw + _i * 8192), 16, 0, 0); } while (0)
; #define PG8_LDA(dst, b, h) do { _Pragma("unroll") for (int m = 0; m < 4; ++m) _Pragma("unroll") for (int k = 0; k < 2; ++k) dst[m][k] = *(const LAS bf16x8*)(lds + PG8_SA(b, h) + aoff + m * 2048 + k * 1024); } while (0)
; #define PG8_LDB(dst, b, h) do { _Pragma("unroll") for (int n = 0; n < 2; ++n) _Pragma("unroll") for (int k = 0; k < 2; ++k) dst[n][k] = *(const LAS bf16x8*)(lds + PG8_SB(b, h) + boff + n * 2048 + k * 1024); } while (0)
; #define PG8_MMA(ai, bj, At, Bt) do { __builtin_amdgcn_s_setprio(1); _Pragma("unroll") for (int m = 0; m < 4; ++m) _Pragma("unroll") for (int n = 0; n < 2; ++n) _Pragma("unroll") for (int k = 0; k < 2; ++k) \
;         acc[ai][bj][m][n] = __builtin_amdgcn_mfma_f32_16x16x32_bf16(Bt[n][k], At[m][k], acc[ai][bj][m][n], 0, 0, 0); __builtin_amdgcn_s_setprio(0); } while (0)
; #define PG8_WAIT_V(n) asm volatile("s_waitcnt vmcnt(" #n ")" ::: "memory")
; #define PG8_WAIT_L(n) asm volatile("s_waitcnt lgkmcnt(" #n ")" ::: "memory")
; template <class Epi, class Sched, bool ATILE = false>
; __device__ __forceinline__ void gemm_phase(LAS unsigned char* lds, const Gemm g, const Sched& S, const Epi& E) {
;     ...
;         for (int t = 0; t < nt; t += 2) {
;             const bool last = (t == nt - 2);
;             const char* a1 = cA + (size_t)(t + 1) * kstepA;
;             const char* a2 = last ? nA : cA + (size_t)(t + 2) * kstepA; const char* b2 = last ? nB : cB + (size_t)(t + 2) * kstep;
;             const char* a3 = a2 + kstepA; const char* b3 = b2 + kstep;
;             PG8_LDB(B0, 0, 0); PG8_SCHED; PG8_LDA(At, 0, 0); PG8_STAGE(PG8_SA(1, 1), a1 + hstepA, voffA);
;             PG8_WAIT_L(8); PG8_BAR; PG8_WAIT_L(0); PG8_MMA(0, 0, At, B0); PG8_BAR; PG8_SCHED;
;             PG8_LDB(B1, 0, 1); PG8_STAGE(PG8_SB(0, 0), b2, voffB);
;             PG8_BAR; PG8_WAIT_L(0); PG8_MMA(0, 1, At, B1); PG8_BAR;
;             PG8_LDA(At, 0, 1); PG8_STAGE(PG8_SA(0, 0), a2, voffA);
;             PG8_BAR; PG8_WAIT_L(0); PG8_MMA(1, 0, At, B0); PG8_BAR; PG8_SCHED;
;             PG8_STAGE(PG8_SB(0, 1), b2 + hstepB, voffB);
;             PG8_WAIT_V(6); PG8_BAR; PG8_MMA(1, 1, At, B1); PG8_BAR;
.LBB0_1517:
	ds_read_b128 v[96:99], v182
	ds_read_b128 v[100:103], v182 offset:1024
	ds_read_b128 v[112:115], v182 offset:2048
	ds_read_b128 v[116:119], v182 offset:3072
	s_add_i32 s54, s26, 2
	s_add_u32 s27, s24, 0xfffc0080
	s_addc_u32 s28, s25, -1
	s_cmp_eq_u32 s45, s26
	s_cselect_b32 s26, s44, s52
	s_cselect_b32 s29, s17, s28
	s_cselect_b32 s28, s42, s27
	s_cselect_b32 s27, s43, s53
	s_add_i32 m0, s23, 0xc000
	ds_read_b128 v[144:147], v183
	ds_read_b128 v[174:177], v183 offset:1024
	ds_read_b128 v[178:181], v183 offset:2048
	ds_read_b128 v[186:189], v183 offset:3072
	ds_read_b128 v[190:193], v183 offset:4096
	ds_read_b128 v[194:197], v183 offset:5120
	ds_read_b128 v[198:201], v183 offset:6144
	ds_read_b128 v[202:205], v183 offset:7168
	global_load_lds_dwordx4 v166, s[24:25]
	s_add_i32 m0, s23, 0xe000
	s_nop 0
	global_load_lds_dwordx4 v168, s[24:25]
	s_waitcnt lgkmcnt(8)
	s_setprio 1
	s_barrier
	s_waitcnt lgkmcnt(0)
	v_mfma_f32_16x16x32_bf16 v[140:143], v[96:99], v[144:147], v[140:143]
	v_mfma_f32_16x16x32_bf16 v[136:139], v[112:115], v[144:147], v[136:139]
	v_mfma_f32_16x16x32_bf16 v[124:127], v[96:99], v[178:181], v[124:127]
	v_mfma_f32_16x16x32_bf16 v[120:123], v[112:115], v[178:181], v[120:123]
	v_mfma_f32_16x16x32_bf16 v[92:95], v[96:99], v[190:193], v[92:95]
	v_mfma_f32_16x16x32_bf16 v[88:91], v[112:115], v[190:193], v[88:91]
	v_mfma_f32_16x16x32_bf16 v[76:79], v[96:99], v[198:201], v[76:79]
	v_mfma_f32_16x16x32_bf16 v[72:75], v[112:115], v[198:201], v[72:75]
	v_mfma_f32_16x16x32_bf16 v[140:143], v[100:103], v[174:177], v[140:143]
	v_mfma_f32_16x16x32_bf16 v[136:139], v[116:119], v[174:177], v[136:139]
	v_mfma_f32_16x16x32_bf16 v[124:127], v[100:103], v[186:189], v[124:127]
	v_mfma_f32_16x16x32_bf16 v[120:123], v[116:119], v[186:189], v[120:123]
	v_mfma_f32_16x16x32_bf16 v[92:95], v[100:103], v[194:197], v[92:95]
	v_mfma_f32_16x16x32_bf16 v[88:91], v[116:119], v[194:197], v[88:91]
	v_mfma_f32_16x16x32_bf16 v[76:79], v[100:103], v[202:205], v[76:79]
	v_mfma_f32_16x16x32_bf16 v[72:75], v[116:119], v[202:205], v[72:75]
	s_barrier
	s_setprio 0
	s_add_i32 s55, s39, s5
	s_add_u32 s98, s26, s10
	s_addc_u32 s99, s27, s11
	s_mov_b32 m0, s55
	ds_read_b128 v[206:209], v184
	ds_read_b128 v[210:213], v184 offset:1024
	ds_read_b128 v[214:217], v184 offset:2048
	ds_read_b128 v[218:221], v184 offset:3072
	global_load_lds_dwordx4 v150, s[26:27]
	s_add_i32 m0, s55, 0x2000
	s_nop 0
	global_load_lds_dwordx4 v164, s[26:27]
	s_setprio 1
	s_barrier
	s_waitcnt lgkmcnt(0)
	v_mfma_f32_16x16x32_bf16 v[132:135], v[206:209], v[144:147], v[132:135]
	v_mfma_f32_16x16x32_bf16 v[128:131], v[214:217], v[144:147], v[128:131]
	v_mfma_f32_16x16x32_bf16 v[108:111], v[206:209], v[178:181], v[108:111]
	v_mfma_f32_16x16x32_bf16 v[104:107], v[214:217], v[178:181], v[104:107]
	v_mfma_f32_16x16x32_bf16 v[84:87], v[206:209], v[190:193], v[84:87]
	v_mfma_f32_16x16x32_bf16 v[80:83], v[214:217], v[190:193], v[80:83]
	v_mfma_f32_16x16x32_bf16 v[68:71], v[206:209], v[198:201], v[68:71]
	v_mfma_f32_16x16x32_bf16 v[64:67], v[214:217], v[198:201], v[64:67]
	v_mfma_f32_16x16x32_bf16 v[132:135], v[210:213], v[174:177], v[132:135]
	v_mfma_f32_16x16x32_bf16 v[128:131], v[218:221], v[174:177], v[128:131]
	v_mfma_f32_16x16x32_bf16 v[108:111], v[210:213], v[186:189], v[108:111]
	v_mfma_f32_16x16x32_bf16 v[104:107], v[218:221], v[186:189], v[104:107]
	v_mfma_f32_16x16x32_bf16 v[84:87], v[210:213], v[194:197], v[84:87]
	v_mfma_f32_16x16x32_bf16 v[80:83], v[218:221], v[194:197], v[80:83]
	v_mfma_f32_16x16x32_bf16 v[68:71], v[210:213], v[202:205], v[68:71]
	v_mfma_f32_16x16x32_bf16 v[64:67], v[218:221], v[202:205], v[64:67]
	s_barrier
	s_setprio 0
	s_mov_b32 m0, s23
	s_add_u32 s100, s28, s10
	s_addc_u32 s101, s29, s11
	ds_read_b128 v[144:147], v183 offset:16384
	ds_read_b128 v[174:177], v183 offset:17408
	ds_read_b128 v[178:181], v183 offset:18432
	ds_read_b128 v[186:189], v183 offset:19456
	ds_read_b128 v[190:193], v183 offset:20480
	ds_read_b128 v[194:197], v183 offset:21504
	ds_read_b128 v[198:201], v183 offset:22528
	ds_read_b128 v[202:205], v183 offset:23552
	global_load_lds_dwordx4 v148, s[28:29]
	s_mov_b32 m0, s30
	s_nop 0
	global_load_lds_dwordx4 v162, s[28:29]
	s_setprio 1
	s_barrier
	s_waitcnt lgkmcnt(0)
	v_mfma_f32_16x16x32_bf16 v[60:63], v[96:99], v[144:147], v[60:63]
	v_mfma_f32_16x16x32_bf16 v[56:59], v[112:115], v[144:147], v[56:59]
	v_mfma_f32_16x16x32_bf16 v[44:47], v[96:99], v[178:181], v[44:47]
	v_mfma_f32_16x16x32_bf16 v[40:43], v[112:115], v[178:181], v[40:43]
	v_mfma_f32_16x16x32_bf16 v[28:31], v[96:99], v[190:193], v[28:31]
	v_mfma_f32_16x16x32_bf16 v[24:27], v[112:115], v[190:193], v[24:27]
	v_mfma_f32_16x16x32_bf16 v[12:15], v[96:99], v[198:201], v[12:15]
	v_mfma_f32_16x16x32_bf16 v[8:11], v[112:115], v[198:201], v[8:11]
	v_mfma_f32_16x16x32_bf16 v[60:63], v[100:103], v[174:177], v[60:63]
	v_mfma_f32_16x16x32_bf16 v[56:59], v[116:119], v[174:177], v[56:59]
	v_mfma_f32_16x16x32_bf16 v[44:47], v[100:103], v[186:189], v[44:47]
	v_mfma_f32_16x16x32_bf16 v[40:43], v[116:119], v[186:189], v[40:43]
	v_mfma_f32_16x16x32_bf16 v[28:31], v[100:103], v[194:197], v[28:31]
	v_mfma_f32_16x16x32_bf16 v[24:27], v[116:119], v[194:197], v[24:27]
	v_mfma_f32_16x16x32_bf16 v[12:15], v[100:103], v[202:205], v[12:15]
	v_mfma_f32_16x16x32_bf16 v[8:11], v[116:119], v[202:205], v[8:11]
	s_barrier
	s_setprio 0
	s_add_u32 s56, s26, 0x40000
	s_addc_u32 s57, s27, 0
	s_add_i32 s55, s40, s5
	s_mov_b32 m0, s55
	s_nop 0
	global_load_lds_dwordx4 v150, s[56:57]
	s_add_i32 m0, s55, 0x2000
	s_nop 0
	global_load_lds_dwordx4 v164, s[56:57]
	s_waitcnt vmcnt(6)
	s_setprio 1
	s_barrier
; #define PG8_STAGE(bufoff, gbase, voff) do { _Pragma("unroll") for (int _i = 0; _i < 2; ++_i) \
;         __builtin_amdgcn_global_load_lds((const unsigned*)((const char*)(gbase) + (voff)[_i]), (LAS unsigned*)(lds + (bufoff) + ldsw + _i * 8192), 16, 0, 0); } while (0)
; #define PG8_LDA(dst, b, h) do { _Pragma("unroll") for (int m = 0; m < 4; ++m) _Pragma("unroll") for (int k = 0; k < 2; ++k) dst[m][k] = *(const LAS bf16x8*)(lds + PG8_SA(b, h) + aoff + m * 2048 + k * 1024); } while (0)
; #define PG8_LDB(dst, b, h) do { _Pragma("unroll") for (int n = 0; n < 2; ++n) _Pragma("unroll") for (int k = 0; k < 2; ++k) dst[n][k] = *(const LAS bf16x8*)(lds + PG8_SB(b, h) + boff + n * 2048 + k * 1024); } while (0)
; #define PG8_MMA(ai, bj, At, Bt) do { __builtin_amdgcn_s_setprio(1); _Pragma("unroll") for (int m = 0; m < 4; ++m) _Pragma("unroll") for (int n = 0; n < 2; ++n) _Pragma("unroll") for (int k = 0; k < 2; ++k) \
;         acc[ai][bj][m][n] = __builtin_amdgcn_mfma_f32_16x16x32_bf16(Bt[n][k], At[m][k], acc[ai][bj][m][n], 0, 0, 0); __builtin_amdgcn_s_setprio(0); } while (0)
; #define PG8_WAIT_V(n) asm volatile("s_waitcnt vmcnt(" #n ")" ::: "memory")
; #define PG8_WAIT_L(n) asm volatile("s_waitcnt lgkmcnt(" #n ")" ::: "memory")
; #define PG8_BAR __builtin_amdgcn_s_barrier()
; #define PG8_SCHED __builtin_amdgcn_sched_barrier(0)
; template <class Epi, class Sched, bool ATILE = false>
; __device__ __forceinline__ void gemm_phase(LAS unsigned char* lds, const Gemm g, const Sched& S, const Epi& E) {
;     ...
;             PG8_WAIT_V(6); PG8_BAR; PG8_MMA(1, 1, At, B1); PG8_BAR;
;             PG8_LDB(B0, 1, 0); PG8_SCHED; PG8_LDA(At, 1, 0); PG8_STAGE(PG8_SA(0, 1), a2 + hstepA, voffA);
;             PG8_WAIT_L(8); PG8_BAR; PG8_WAIT_L(0); PG8_MMA(0, 0, At, B0); PG8_BAR; PG8_SCHED;
;             PG8_LDB(B1, 1, 1); PG8_STAGE(PG8_SB(1, 0), b3, voffB);
;             PG8_BAR; PG8_WAIT_L(0); PG8_MMA(0, 1, At, B1); PG8_BAR;
	v_mfma_f32_16x16x32_bf16 v[52:55], v[206:209], v[144:147], v[52:55]
	v_mfma_f32_16x16x32_bf16 v[48:51], v[214:217], v[144:147], v[48:51]
	v_mfma_f32_16x16x32_bf16 v[36:39], v[206:209], v[178:181], v[36:39]
	v_mfma_f32_16x16x32_bf16 v[32:35], v[214:217], v[178:181], v[32:35]
	v_mfma_f32_16x16x32_bf16 v[20:23], v[206:209], v[190:193], v[20:23]
	v_mfma_f32_16x16x32_bf16 v[16:19], v[214:217], v[190:193], v[16:19]
	v_mfma_f32_16x16x32_bf16 v[4:7], v[206:209], v[198:201], v[4:7]
	v_mfma_f32_16x16x32_bf16 v[0:3], v[214:217], v[198:201], v[0:3]
	v_mfma_f32_16x16x32_bf16 v[52:55], v[210:213], v[174:177], v[52:55]
	v_mfma_f32_16x16x32_bf16 v[48:51], v[218:221], v[174:177], v[48:51]
	v_mfma_f32_16x16x32_bf16 v[36:39], v[210:213], v[186:189], v[36:39]
	v_mfma_f32_16x16x32_bf16 v[32:35], v[218:221], v[186:189], v[32:35]
	v_mfma_f32_16x16x32_bf16 v[20:23], v[210:213], v[194:197], v[20:23]
	v_mfma_f32_16x16x32_bf16 v[16:19], v[218:221], v[194:197], v[16:19]
	v_mfma_f32_16x16x32_bf16 v[4:7], v[210:213], v[202:205], v[4:7]
	v_mfma_f32_16x16x32_bf16 v[0:3], v[218:221], v[202:205], v[0:3]
	s_barrier
	s_setprio 0
	s_add_i32 s55, 0, 0x18000
	v_add_u32_e32 v116, s55, v159
	ds_read_b128 v[96:99], v116
	ds_read_b128 v[100:103], v116 offset:1024
	ds_read_b128 v[112:115], v116 offset:2048
	ds_read_b128 v[116:119], v116 offset:3072
	s_add_u32 s28, s28, 0x40000
	s_addc_u32 s29, s29, 0
	s_mov_b32 m0, s31
	ds_read_b128 v[144:147], v183 offset:32768
	ds_read_b128 v[174:177], v183 offset:33792
	ds_read_b128 v[178:181], v183 offset:34816
	ds_read_b128 v[186:189], v183 offset:35840
	ds_read_b128 v[190:193], v183 offset:36864
	ds_read_b128 v[194:197], v183 offset:37888
	ds_read_b128 v[198:201], v183 offset:38912
	ds_read_b128 v[202:205], v183 offset:39936
	global_load_lds_dwordx4 v148, s[28:29]
	s_mov_b32 m0, s33
	s_nop 0
	global_load_lds_dwordx4 v162, s[28:29]
	s_waitcnt lgkmcnt(8)
	s_setprio 1
	s_barrier
	s_waitcnt lgkmcnt(0)
	v_mfma_f32_16x16x32_bf16 v[140:143], v[96:99], v[144:147], v[140:143]
	v_mfma_f32_16x16x32_bf16 v[136:139], v[112:115], v[144:147], v[136:139]
	v_mfma_f32_16x16x32_bf16 v[124:127], v[96:99], v[178:181], v[124:127]
	v_mfma_f32_16x16x32_bf16 v[120:123], v[112:115], v[178:181], v[120:123]
	v_mfma_f32_16x16x32_bf16 v[92:95], v[96:99], v[190:193], v[92:95]
	v_mfma_f32_16x16x32_bf16 v[88:91], v[112:115], v[190:193], v[88:91]
	v_mfma_f32_16x16x32_bf16 v[76:79], v[96:99], v[198:201], v[76:79]
	v_mfma_f32_16x16x32_bf16 v[72:75], v[112:115], v[198:201], v[72:75]
	v_mfma_f32_16x16x32_bf16 v[140:143], v[100:103], v[174:177], v[140:143]
	v_mfma_f32_16x16x32_bf16 v[136:139], v[116:119], v[174:177], v[136:139]
	v_mfma_f32_16x16x32_bf16 v[124:127], v[100:103], v[186:189], v[124:127]
	v_mfma_f32_16x16x32_bf16 v[120:123], v[116:119], v[186:189], v[120:123]
	v_mfma_f32_16x16x32_bf16 v[92:95], v[100:103], v[194:197], v[92:95]
	v_mfma_f32_16x16x32_bf16 v[88:91], v[116:119], v[194:197], v[88:91]
	v_mfma_f32_16x16x32_bf16 v[76:79], v[100:103], v[202:205], v[76:79]
	v_mfma_f32_16x16x32_bf16 v[72:75], v[116:119], v[202:205], v[72:75]
	s_barrier
	s_setprio 0
	s_add_i32 s28, 0, 0x1c000
	s_add_i32 s29, s55, s5
	v_add_u32_e32 v185, s28, v159
	s_mov_b32 m0, s29
	ds_read_b128 v[206:209], v185
	ds_read_b128 v[210:213], v185 offset:1024
	ds_read_b128 v[214:217], v185 offset:2048
	ds_read_b128 v[218:221], v185 offset:3072
	global_load_lds_dwordx4 v150, s[98:99]
	s_add_i32 m0, s29, 0x2000
	s_nop 0
	global_load_lds_dwordx4 v164, s[98:99]
	s_setprio 1
	s_barrier
; #define PG8_STAGE(bufoff, gbase, voff) do { _Pragma("unroll") for (int _i = 0; _i < 2; ++_i) \
;         __builtin_amdgcn_global_load_lds((const unsigned*)((const char*)(gbase) + (voff)[_i]), (LAS unsigned*)(lds + (bufoff) + ldsw + _i * 8192), 16, 0, 0); } while (0)
; #define PG8_LDA(dst, b, h) do { _Pragma("unroll") for (int m = 0; m < 4; ++m) _Pragma("unroll") for (int k = 0; k < 2; ++k) dst[m][k] = *(const LAS bf16x8*)(lds + PG8_SA(b, h) + aoff + m * 2048 + k * 1024); } while (0)
; #define PG8_MMA(ai, bj, At, Bt) do { __builtin_amdgcn_s_setprio(1); _Pragma("unroll") for (int m = 0; m < 4; ++m) _Pragma("unroll") for (int n = 0; n < 2; ++n) _Pragma("unroll") for (int k = 0; k < 2; ++k) \
;         acc[ai][bj][m][n] = __builtin_amdgcn_mfma_f32_16x16x32_bf16(Bt[n][k], At[m][k], acc[ai][bj][m][n], 0, 0, 0); __builtin_amdgcn_s_setprio(0); } while (0)
; #define PG8_WAIT_V(n) asm volatile("s_waitcnt vmcnt(" #n ")" ::: "memory")
; #define PG8_WAIT_L(n) asm volatile("s_waitcnt lgkmcnt(" #n ")" ::: "memory")
; #define PG8_BAR __builtin_amdgcn_s_barrier()
; #define PG8_SCHED __builtin_amdgcn_sched_barrier(0)
; template <class Epi, class Sched, bool ATILE = false>
; __device__ __forceinline__ void gemm_phase(LAS unsigned char* lds, const Gemm g, const Sched& S, const Epi& E) {
;     ...
;             PG8_BAR; PG8_WAIT_L(0); PG8_MMA(0, 1, At, B1); PG8_BAR;
;             PG8_LDA(At, 1, 1); PG8_STAGE(PG8_SA(1, 0), a3, voffA);
;             PG8_BAR; PG8_WAIT_L(0); PG8_MMA(1, 0, At, B0); PG8_BAR; PG8_SCHED;
;             PG8_STAGE(PG8_SB(1, 1), b3 + hstepB, voffB);
;             PG8_WAIT_V(6); PG8_BAR; PG8_MMA(1, 1, At, B1); PG8_BAR;
;         }
	s_waitcnt lgkmcnt(0)
	v_mfma_f32_16x16x32_bf16 v[132:135], v[206:209], v[144:147], v[132:135]
	v_mfma_f32_16x16x32_bf16 v[128:131], v[214:217], v[144:147], v[128:131]
	v_mfma_f32_16x16x32_bf16 v[108:111], v[206:209], v[178:181], v[108:111]
	v_mfma_f32_16x16x32_bf16 v[104:107], v[214:217], v[178:181], v[104:107]
	v_mfma_f32_16x16x32_bf16 v[84:87], v[206:209], v[190:193], v[84:87]
	v_mfma_f32_16x16x32_bf16 v[80:83], v[214:217], v[190:193], v[80:83]
	v_mfma_f32_16x16x32_bf16 v[68:71], v[206:209], v[198:201], v[68:71]
	v_mfma_f32_16x16x32_bf16 v[64:67], v[214:217], v[198:201], v[64:67]
	v_mfma_f32_16x16x32_bf16 v[132:135], v[210:213], v[174:177], v[132:135]
	v_mfma_f32_16x16x32_bf16 v[128:131], v[218:221], v[174:177], v[128:131]
	v_mfma_f32_16x16x32_bf16 v[108:111], v[210:213], v[186:189], v[108:111]
	v_mfma_f32_16x16x32_bf16 v[104:107], v[218:221], v[186:189], v[104:107]
	v_mfma_f32_16x16x32_bf16 v[84:87], v[210:213], v[194:197], v[84:87]
	v_mfma_f32_16x16x32_bf16 v[80:83], v[218:221], v[194:197], v[80:83]
	v_mfma_f32_16x16x32_bf16 v[68:71], v[210:213], v[202:205], v[68:71]
	v_mfma_f32_16x16x32_bf16 v[64:67], v[218:221], v[202:205], v[64:67]
	s_barrier
	s_setprio 0
	s_mov_b32 m0, s35
	ds_read_b128 v[144:147], v183 offset:49152
	ds_read_b128 v[174:177], v183 offset:50176
	ds_read_b128 v[178:181], v183 offset:51200
	ds_read_b128 v[186:189], v183 offset:52224
	ds_read_b128 v[190:193], v183 offset:53248
	ds_read_b128 v[194:197], v183 offset:54272
	ds_read_b128 v[198:201], v183 offset:55296
	ds_read_b128 v[202:205], v183 offset:56320
	global_load_lds_dwordx4 v148, s[100:101]
	s_mov_b32 m0, s36
	s_nop 0
	global_load_lds_dwordx4 v162, s[100:101]
	s_setprio 1
	s_barrier
	s_waitcnt lgkmcnt(0)
	v_mfma_f32_16x16x32_bf16 v[60:63], v[96:99], v[144:147], v[60:63]
	v_mfma_f32_16x16x32_bf16 v[56:59], v[112:115], v[144:147], v[56:59]
	v_mfma_f32_16x16x32_bf16 v[44:47], v[96:99], v[178:181], v[44:47]
	v_mfma_f32_16x16x32_bf16 v[40:43], v[112:115], v[178:181], v[40:43]
	v_mfma_f32_16x16x32_bf16 v[28:31], v[96:99], v[190:193], v[28:31]
	v_mfma_f32_16x16x32_bf16 v[24:27], v[112:115], v[190:193], v[24:27]
	v_mfma_f32_16x16x32_bf16 v[12:15], v[96:99], v[198:201], v[12:15]
	v_mfma_f32_16x16x32_bf16 v[8:11], v[112:115], v[198:201], v[8:11]
	v_mfma_f32_16x16x32_bf16 v[60:63], v[100:103], v[174:177], v[60:63]
	v_mfma_f32_16x16x32_bf16 v[56:59], v[116:119], v[174:177], v[56:59]
	v_mfma_f32_16x16x32_bf16 v[44:47], v[100:103], v[186:189], v[44:47]
	v_mfma_f32_16x16x32_bf16 v[40:43], v[116:119], v[186:189], v[40:43]
	v_mfma_f32_16x16x32_bf16 v[28:31], v[100:103], v[194:197], v[28:31]
	v_mfma_f32_16x16x32_bf16 v[24:27], v[116:119], v[194:197], v[24:27]
	v_mfma_f32_16x16x32_bf16 v[12:15], v[100:103], v[202:205], v[12:15]
	v_mfma_f32_16x16x32_bf16 v[8:11], v[116:119], v[202:205], v[8:11]
	s_barrier
	s_setprio 0
	s_add_u32 s26, s26, 0x40080
	s_addc_u32 s27, s27, 0
	s_add_i32 s28, s28, s5
	s_mov_b32 m0, s28
	s_nop 0
	global_load_lds_dwordx4 v150, s[26:27]
	s_add_i32 m0, s28, 0x2000
	s_nop 0
	global_load_lds_dwordx4 v164, s[26:27]
	s_waitcnt vmcnt(6)
	s_setprio 1
	s_barrier
	v_mfma_f32_16x16x32_bf16 v[52:55], v[206:209], v[144:147], v[52:55]
	v_mfma_f32_16x16x32_bf16 v[48:51], v[214:217], v[144:147], v[48:51]
	v_mfma_f32_16x16x32_bf16 v[36:39], v[206:209], v[178:181], v[36:39]
	v_mfma_f32_16x16x32_bf16 v[32:35], v[214:217], v[178:181], v[32:35]
	v_mfma_f32_16x16x32_bf16 v[20:23], v[206:209], v[190:193], v[20:23]
	v_mfma_f32_16x16x32_bf16 v[16:19], v[214:217], v[190:193], v[16:19]
	v_mfma_f32_16x16x32_bf16 v[4:7], v[206:209], v[198:201], v[4:7]
	s_add_u32 s24, s24, 0x100
	v_mfma_f32_16x16x32_bf16 v[0:3], v[214:217], v[198:201], v[0:3]
	s_addc_u32 s25, s25, 0
	v_mfma_f32_16x16x32_bf16 v[52:55], v[210:213], v[174:177], v[52:55]
	s_add_u32 s52, s52, 0x100
	v_mfma_f32_16x16x32_bf16 v[48:51], v[218:221], v[174:177], v[48:51]
	s_addc_u32 s53, s53, 0
	v_mfma_f32_16x16x32_bf16 v[36:39], v[210:213], v[186:189], v[36:39]
	s_cmp_ge_i32 s54, s13
	v_mfma_f32_16x16x32_bf16 v[32:35], v[218:221], v[186:189], v[32:35]
	s_mov_b32 s26, s54
	v_mfma_f32_16x16x32_bf16 v[20:23], v[210:213], v[194:197], v[20:23]
	v_mfma_f32_16x16x32_bf16 v[16:19], v[218:221], v[194:197], v[16:19]
	v_mfma_f32_16x16x32_bf16 v[4:7], v[210:213], v[202:205], v[4:7]
	v_mfma_f32_16x16x32_bf16 v[0:3], v[218:221], v[202:205], v[0:3]
	s_barrier
	s_setprio 0
	s_cbranch_scc0 .LBB0_1517
	s_nop 5
	s_branch .LBB0_1508

; #define PG8_STAGE(bufoff, gbase, voff) do { _Pragma("unroll") for (int _i = 0; _i < 2; ++_i) \
;         __builtin_amdgcn_global_load_lds((const unsigned*)((const char*)(gbase) + (voff)[_i]), (LAS unsigned*)(lds + (bufoff) + ldsw + _i * 8192), 16, 0, 0); } while (0)
; #define PG8_LDA(dst, b, h) do { _Pragma("unroll") for (int m = 0; m < 4; ++m) _Pragma("unroll") for (int k = 0; k < 2; ++k) dst[m][k] = *(const LAS bf16x8*)(lds + PG8_SA(b, h) + aoff + m * 2048 + k * 1024); } while (0)
; #define PG8_LDB(dst, b, h) do { _Pragma("unroll") for (int n = 0; n < 2; ++n) _Pragma("unroll") for (int k = 0; k < 2; ++k) dst[n][k] = *(const LAS bf16x8*)(lds + PG8_SB(b, h) + boff + n * 2048 + k * 1024); } while (0)
; #define PG8_MMA(ai, bj, At, Bt) do { __builtin_amdgcn_s_setprio(1); _Pragma("unroll") for (int m = 0; m < 4; ++m) _Pragma("unroll") for (int n = 0; n < 2; ++n) _Pragma("unroll") for (int k = 0; k < 2; ++k) \
;         acc[ai][bj][m][n] = __builtin_amdgcn_mfma_f32_16x16x32_bf16(Bt[n][k], At[m][k], acc[ai][bj][m][n], 0, 0, 0); __builtin_amdgcn_s_setprio(0); } while (0)
; #define PG8_WAIT_V(n) asm volatile("s_waitcnt vmcnt(" #n ")" ::: "memory")
; #define PG8_WAIT_L(n) asm volatile("s_waitcnt lgkmcnt(" #n ")" ::: "memory")
; template <class Epi, class Sched, bool ATILE = false>
; __device__ __forceinline__ void gemm_phase(LAS unsigned char* lds, const Gemm g, const Sched& S, const Epi& E) {
;     ...
;         for (int t = 0; t < nt; t += 2) {
;             const bool last = (t == nt - 2);
;             const char* a1 = cA + (size_t)(t + 1) * kstepA;
;             const char* a2 = last ? nA : cA + (size_t)(t + 2) * kstepA; const char* b2 = last ? nB : cB + (size_t)(t + 2) * kstep;
;             const char* a3 = a2 + kstepA; const char* b3 = b2 + kstep;
;             PG8_LDB(B0, 0, 0); PG8_SCHED; PG8_LDA(At, 0, 0); PG8_STAGE(PG8_SA(1, 1), a1 + hstepA, voffA);
;             PG8_WAIT_L(8); PG8_BAR; PG8_WAIT_L(0); PG8_MMA(0, 0, At, B0); PG8_BAR; PG8_SCHED;
;             PG8_LDB(B1, 0, 1); PG8_STAGE(PG8_SB(0, 0), b2, voffB);
;             PG8_BAR; PG8_WAIT_L(0); PG8_MMA(0, 1, At, B1); PG8_BAR;
;             PG8_LDA(At, 0, 1); PG8_STAGE(PG8_SA(0, 0), a2, voffA);
;             PG8_BAR; PG8_WAIT_L(0); PG8_MMA(1, 0, At, B0); PG8_BAR; PG8_SCHED;
;             PG8_STAGE(PG8_SB(0, 1), b2 + hstepB, voffB);
;             PG8_WAIT_V(6); PG8_BAR; PG8_MMA(1, 1, At, B1); PG8_BAR;
.LBB0_1658:
	s_waitcnt lgkmcnt(0)
	ds_read_b128 v[128:131], v169
	ds_read_b128 v[132:135], v169 offset:1024
	ds_read_b128 v[136:139], v169 offset:2048
	ds_read_b128 v[140:143], v169 offset:3072
	s_add_i32 s29, s27, 2
	s_add_u32 s34, s30, 0x4000
	s_addc_u32 s35, s31, 0
	s_cmp_eq_u32 s11, s27
	s_cselect_b32 s38, s22, s34
	s_cselect_b32 s39, s23, s35
	s_cselect_b32 s34, s24, s13
	s_cselect_b32 s35, s25, s17
	s_add_u32 s36, s38, 0x8000
	s_addc_u32 s37, s39, 0
	s_add_i32 m0, s5, 0xc000
	ds_read_b128 v[144:147], v210
	ds_read_b128 v[148:151], v210 offset:1024
	ds_read_b128 v[192:195], v210 offset:2048
	ds_read_b128 v[196:199], v210 offset:3072
	ds_read_b128 v[200:203], v210 offset:4096
	ds_read_b128 v[204:207], v210 offset:5120
	ds_read_b128 v[214:217], v210 offset:6144
	ds_read_b128 v[218:221], v210 offset:7168
	global_load_lds_dwordx4 v186, s[30:31]
	s_add_i32 m0, s5, 0xe000
	s_nop 0
	global_load_lds_dwordx4 v188, s[30:31]
	s_waitcnt lgkmcnt(8)
	s_setprio 1
	s_barrier
	s_waitcnt lgkmcnt(0)
	v_mfma_f32_16x16x32_bf16 v[120:123], v[128:131], v[144:147], v[120:123]
	v_mfma_f32_16x16x32_bf16 v[116:119], v[136:139], v[144:147], v[116:119]
	v_mfma_f32_16x16x32_bf16 v[108:111], v[128:131], v[192:195], v[108:111]
	v_mfma_f32_16x16x32_bf16 v[100:103], v[136:139], v[192:195], v[100:103]
	v_mfma_f32_16x16x32_bf16 v[92:95], v[128:131], v[200:203], v[92:95]
	v_mfma_f32_16x16x32_bf16 v[84:87], v[136:139], v[200:203], v[84:87]
	v_mfma_f32_16x16x32_bf16 v[76:79], v[128:131], v[214:217], v[76:79]
	v_mfma_f32_16x16x32_bf16 v[68:71], v[136:139], v[214:217], v[68:71]
	v_mfma_f32_16x16x32_bf16 v[120:123], v[132:135], v[148:151], v[120:123]
	v_mfma_f32_16x16x32_bf16 v[116:119], v[140:143], v[148:151], v[116:119]
	v_mfma_f32_16x16x32_bf16 v[108:111], v[132:135], v[196:199], v[108:111]
	v_mfma_f32_16x16x32_bf16 v[100:103], v[140:143], v[196:199], v[100:103]
	v_mfma_f32_16x16x32_bf16 v[92:95], v[132:135], v[204:207], v[92:95]
	v_mfma_f32_16x16x32_bf16 v[84:87], v[140:143], v[204:207], v[84:87]
	v_mfma_f32_16x16x32_bf16 v[76:79], v[132:135], v[218:221], v[76:79]
	v_mfma_f32_16x16x32_bf16 v[68:71], v[140:143], v[218:221], v[68:71]
	s_barrier
	s_setprio 0
	s_add_i32 s27, s52, s4
	s_add_u32 s98, s34, s8
	s_addc_u32 s99, s35, s9
	s_mov_b32 m0, s27
	ds_read_b128 v[222:225], v211
	ds_read_b128 v[226:229], v211 offset:1024
	ds_read_b128 v[230:233], v211 offset:2048
	ds_read_b128 v[234:237], v211 offset:3072
	global_load_lds_dwordx4 v162, s[34:35]
	s_add_i32 m0, s27, 0x2000
	s_nop 0
	global_load_lds_dwordx4 v166, s[34:35]
	s_setprio 1
	s_barrier
	s_waitcnt lgkmcnt(0)
	v_mfma_f32_16x16x32_bf16 v[124:127], v[222:225], v[144:147], v[124:127]
	v_mfma_f32_16x16x32_bf16 v[112:115], v[230:233], v[144:147], v[112:115]
	v_mfma_f32_16x16x32_bf16 v[104:107], v[222:225], v[192:195], v[104:107]
	v_mfma_f32_16x16x32_bf16 v[96:99], v[230:233], v[192:195], v[96:99]
	v_mfma_f32_16x16x32_bf16 v[88:91], v[222:225], v[200:203], v[88:91]
	v_mfma_f32_16x16x32_bf16 v[80:83], v[230:233], v[200:203], v[80:83]
	v_mfma_f32_16x16x32_bf16 v[72:75], v[222:225], v[214:217], v[72:75]
	v_mfma_f32_16x16x32_bf16 v[64:67], v[230:233], v[214:217], v[64:67]
	v_mfma_f32_16x16x32_bf16 v[124:127], v[226:229], v[148:151], v[124:127]
	v_mfma_f32_16x16x32_bf16 v[112:115], v[234:237], v[148:151], v[112:115]
	v_mfma_f32_16x16x32_bf16 v[104:107], v[226:229], v[196:199], v[104:107]
	v_mfma_f32_16x16x32_bf16 v[96:99], v[234:237], v[196:199], v[96:99]
	v_mfma_f32_16x16x32_bf16 v[88:91], v[226:229], v[204:207], v[88:91]
	v_mfma_f32_16x16x32_bf16 v[80:83], v[234:237], v[204:207], v[80:83]
	v_mfma_f32_16x16x32_bf16 v[72:75], v[226:229], v[218:221], v[72:75]
	v_mfma_f32_16x16x32_bf16 v[64:67], v[234:237], v[218:221], v[64:67]
	s_barrier
	s_setprio 0
	s_mov_b32 m0, s5
	ds_read_b128 v[144:147], v210 offset:16384
	ds_read_b128 v[148:151], v210 offset:17408
	ds_read_b128 v[192:195], v210 offset:18432
	ds_read_b128 v[196:199], v210 offset:19456
	ds_read_b128 v[200:203], v210 offset:20480
	ds_read_b128 v[204:207], v210 offset:21504
	ds_read_b128 v[214:217], v210 offset:22528
	ds_read_b128 v[218:221], v210 offset:23552
	global_load_lds_dwordx4 v160, s[38:39]
	s_mov_b32 m0, s33
	s_nop 0
	global_load_lds_dwordx4 v164, s[38:39]
	s_setprio 1
	s_barrier
	s_waitcnt lgkmcnt(0)
	v_mfma_f32_16x16x32_bf16 v[60:63], v[128:131], v[144:147], v[60:63]
	v_mfma_f32_16x16x32_bf16 v[56:59], v[136:139], v[144:147], v[56:59]
	v_mfma_f32_16x16x32_bf16 v[44:47], v[128:131], v[192:195], v[44:47]
	v_mfma_f32_16x16x32_bf16 v[40:43], v[136:139], v[192:195], v[40:43]
	v_mfma_f32_16x16x32_bf16 v[28:31], v[128:131], v[200:203], v[28:31]
	v_mfma_f32_16x16x32_bf16 v[24:27], v[136:139], v[200:203], v[24:27]
	v_mfma_f32_16x16x32_bf16 v[12:15], v[128:131], v[214:217], v[12:15]
	v_mfma_f32_16x16x32_bf16 v[8:11], v[136:139], v[214:217], v[8:11]
	v_mfma_f32_16x16x32_bf16 v[60:63], v[132:135], v[148:151], v[60:63]
	v_mfma_f32_16x16x32_bf16 v[56:59], v[140:143], v[148:151], v[56:59]
	v_mfma_f32_16x16x32_bf16 v[44:47], v[132:135], v[196:199], v[44:47]
	v_mfma_f32_16x16x32_bf16 v[40:43], v[140:143], v[196:199], v[40:43]
	v_mfma_f32_16x16x32_bf16 v[28:31], v[132:135], v[204:207], v[28:31]
	v_mfma_f32_16x16x32_bf16 v[24:27], v[140:143], v[204:207], v[24:27]
	v_mfma_f32_16x16x32_bf16 v[12:15], v[132:135], v[218:221], v[12:15]
	v_mfma_f32_16x16x32_bf16 v[8:11], v[140:143], v[218:221], v[8:11]
	s_barrier
	s_setprio 0
	s_add_u32 s56, s34, 0x80000
	s_addc_u32 s57, s35, 0
	s_add_i32 s27, s53, s4
	s_mov_b32 m0, s27
	s_nop 0
	global_load_lds_dwordx4 v162, s[56:57]
	s_add_i32 m0, s27, 0x2000
	s_nop 0
	global_load_lds_dwordx4 v166, s[56:57]
	s_waitcnt vmcnt(6)
	s_setprio 1
	s_barrier
; #define PG8_STAGE(bufoff, gbase, voff) do { _Pragma("unroll") for (int _i = 0; _i < 2; ++_i) \
;         __builtin_amdgcn_global_load_lds((const unsigned*)((const char*)(gbase) + (voff)[_i]), (LAS unsigned*)(lds + (bufoff) + ldsw + _i * 8192), 16, 0, 0); } while (0)
; #define PG8_LDA(dst, b, h) do { _Pragma("unroll") for (int m = 0; m < 4; ++m) _Pragma("unroll") for (int k = 0; k < 2; ++k) dst[m][k] = *(const LAS bf16x8*)(lds + PG8_SA(b, h) + aoff + m * 2048 + k * 1024); } while (0)
; #define PG8_LDB(dst, b, h) do { _Pragma("unroll") for (int n = 0; n < 2; ++n) _Pragma("unroll") for (int k = 0; k < 2; ++k) dst[n][k] = *(const LAS bf16x8*)(lds + PG8_SB(b, h) + boff + n * 2048 + k * 1024); } while (0)
; #define PG8_MMA(ai, bj, At, Bt) do { __builtin_amdgcn_s_setprio(1); _Pragma("unroll") for (int m = 0; m < 4; ++m) _Pragma("unroll") for (int n = 0; n < 2; ++n) _Pragma("unroll") for (int k = 0; k < 2; ++k) \
;         acc[ai][bj][m][n] = __builtin_amdgcn_mfma_f32_16x16x32_bf16(Bt[n][k], At[m][k], acc[ai][bj][m][n], 0, 0, 0); __builtin_amdgcn_s_setprio(0); } while (0)
; #define PG8_WAIT_V(n) asm volatile("s_waitcnt vmcnt(" #n ")" ::: "memory")
; #define PG8_WAIT_L(n) asm volatile("s_waitcnt lgkmcnt(" #n ")" ::: "memory")
; #define PG8_BAR __builtin_amdgcn_s_barrier()
; #define PG8_SCHED __builtin_amdgcn_sched_barrier(0)
; template <class Epi, class Sched, bool ATILE = false>
; __device__ __forceinline__ void gemm_phase(LAS unsigned char* lds, const Gemm g, const Sched& S, const Epi& E) {
;     ...
;             PG8_WAIT_V(6); PG8_BAR; PG8_MMA(1, 1, At, B1); PG8_BAR;
;             PG8_LDB(B0, 1, 0); PG8_SCHED; PG8_LDA(At, 1, 0); PG8_STAGE(PG8_SA(0, 1), a2 + hstepA, voffA);
;             PG8_WAIT_L(8); PG8_BAR; PG8_WAIT_L(0); PG8_MMA(0, 0, At, B0); PG8_BAR; PG8_SCHED;
;             PG8_LDB(B1, 1, 1); PG8_STAGE(PG8_SB(1, 0), b3, voffB);
;             PG8_BAR; PG8_WAIT_L(0); PG8_MMA(0, 1, At, B1); PG8_BAR;
	v_mfma_f32_16x16x32_bf16 v[52:55], v[222:225], v[144:147], v[52:55]
	v_mfma_f32_16x16x32_bf16 v[48:51], v[230:233], v[144:147], v[48:51]
	v_mfma_f32_16x16x32_bf16 v[36:39], v[222:225], v[192:195], v[36:39]
	v_mfma_f32_16x16x32_bf16 v[32:35], v[230:233], v[192:195], v[32:35]
	v_mfma_f32_16x16x32_bf16 v[20:23], v[222:225], v[200:203], v[20:23]
	v_mfma_f32_16x16x32_bf16 v[16:19], v[230:233], v[200:203], v[16:19]
	v_mfma_f32_16x16x32_bf16 v[4:7], v[222:225], v[214:217], v[4:7]
	v_mfma_f32_16x16x32_bf16 v[0:3], v[230:233], v[214:217], v[0:3]
	v_mfma_f32_16x16x32_bf16 v[52:55], v[226:229], v[148:151], v[52:55]
	v_mfma_f32_16x16x32_bf16 v[48:51], v[234:237], v[148:151], v[48:51]
	v_mfma_f32_16x16x32_bf16 v[36:39], v[226:229], v[196:199], v[36:39]
	v_mfma_f32_16x16x32_bf16 v[32:35], v[234:237], v[196:199], v[32:35]
	v_mfma_f32_16x16x32_bf16 v[20:23], v[226:229], v[204:207], v[20:23]
	v_mfma_f32_16x16x32_bf16 v[16:19], v[234:237], v[204:207], v[16:19]
	v_mfma_f32_16x16x32_bf16 v[4:7], v[226:229], v[218:221], v[4:7]
	v_mfma_f32_16x16x32_bf16 v[0:3], v[234:237], v[218:221], v[0:3]
	s_barrier
	s_setprio 0
	s_add_i32 s27, 0, 0x18000
	v_add_u32_e32 v140, s27, v157
	ds_read_b128 v[128:131], v140
	ds_read_b128 v[132:135], v140 offset:1024
	ds_read_b128 v[136:139], v140 offset:2048
	ds_read_b128 v[140:143], v140 offset:3072
	s_add_u32 s38, s38, 0x4000
	s_addc_u32 s39, s39, 0
	s_mov_b32 m0, s40
	ds_read_b128 v[144:147], v210 offset:32768
	ds_read_b128 v[148:151], v210 offset:33792
	ds_read_b128 v[192:195], v210 offset:34816
	ds_read_b128 v[196:199], v210 offset:35840
	ds_read_b128 v[200:203], v210 offset:36864
	ds_read_b128 v[204:207], v210 offset:37888
	ds_read_b128 v[214:217], v210 offset:38912
	ds_read_b128 v[218:221], v210 offset:39936
	global_load_lds_dwordx4 v160, s[38:39]
	s_mov_b32 m0, s41
	s_nop 0
	global_load_lds_dwordx4 v164, s[38:39]
	s_waitcnt lgkmcnt(8)
	s_setprio 1
	s_barrier
	s_waitcnt lgkmcnt(0)
	v_mfma_f32_16x16x32_bf16 v[120:123], v[128:131], v[144:147], v[120:123]
	v_mfma_f32_16x16x32_bf16 v[116:119], v[136:139], v[144:147], v[116:119]
	v_mfma_f32_16x16x32_bf16 v[108:111], v[128:131], v[192:195], v[108:111]
	v_mfma_f32_16x16x32_bf16 v[100:103], v[136:139], v[192:195], v[100:103]
	v_mfma_f32_16x16x32_bf16 v[92:95], v[128:131], v[200:203], v[92:95]
	v_mfma_f32_16x16x32_bf16 v[84:87], v[136:139], v[200:203], v[84:87]
	v_mfma_f32_16x16x32_bf16 v[76:79], v[128:131], v[214:217], v[76:79]
	v_mfma_f32_16x16x32_bf16 v[68:71], v[136:139], v[214:217], v[68:71]
	v_mfma_f32_16x16x32_bf16 v[120:123], v[132:135], v[148:151], v[120:123]
	v_mfma_f32_16x16x32_bf16 v[116:119], v[140:143], v[148:151], v[116:119]
	v_mfma_f32_16x16x32_bf16 v[108:111], v[132:135], v[196:199], v[108:111]
	v_mfma_f32_16x16x32_bf16 v[100:103], v[140:143], v[196:199], v[100:103]
	v_mfma_f32_16x16x32_bf16 v[92:95], v[132:135], v[204:207], v[92:95]
	v_mfma_f32_16x16x32_bf16 v[84:87], v[140:143], v[204:207], v[84:87]
	v_mfma_f32_16x16x32_bf16 v[76:79], v[132:135], v[218:221], v[76:79]
	v_mfma_f32_16x16x32_bf16 v[68:71], v[140:143], v[218:221], v[68:71]
	s_barrier
	s_setprio 0
	s_add_i32 s38, 0, 0x1c000
	s_add_i32 s27, s27, s4
	v_add_u32_e32 v213, s38, v157
	s_mov_b32 m0, s27
	ds_read_b128 v[222:225], v213
	ds_read_b128 v[226:229], v213 offset:1024
	ds_read_b128 v[230:233], v213 offset:2048
	ds_read_b128 v[234:237], v213 offset:3072
	global_load_lds_dwordx4 v162, s[98:99]
	s_add_i32 m0, s27, 0x2000
	s_nop 0
	global_load_lds_dwordx4 v166, s[98:99]
	s_setprio 1
	s_barrier
; #define PG8_STAGE(bufoff, gbase, voff) do { _Pragma("unroll") for (int _i = 0; _i < 2; ++_i) \
;         __builtin_amdgcn_global_load_lds((const unsigned*)((const char*)(gbase) + (voff)[_i]), (LAS unsigned*)(lds + (bufoff) + ldsw + _i * 8192), 16, 0, 0); } while (0)
; #define PG8_LDA(dst, b, h) do { _Pragma("unroll") for (int m = 0; m < 4; ++m) _Pragma("unroll") for (int k = 0; k < 2; ++k) dst[m][k] = *(const LAS bf16x8*)(lds + PG8_SA(b, h) + aoff + m * 2048 + k * 1024); } while (0)
; #define PG8_MMA(ai, bj, At, Bt) do { __builtin_amdgcn_s_setprio(1); _Pragma("unroll") for (int m = 0; m < 4; ++m) _Pragma("unroll") for (int n = 0; n < 2; ++n) _Pragma("unroll") for (int k = 0; k < 2; ++k) \
;         acc[ai][bj][m][n] = __builtin_amdgcn_mfma_f32_16x16x32_bf16(Bt[n][k], At[m][k], acc[ai][bj][m][n], 0, 0, 0); __builtin_amdgcn_s_setprio(0); } while (0)
; #define PG8_WAIT_V(n) asm volatile("s_waitcnt vmcnt(" #n ")" ::: "memory")
; #define PG8_WAIT_L(n) asm volatile("s_waitcnt lgkmcnt(" #n ")" ::: "memory")
; #define PG8_BAR __builtin_amdgcn_s_barrier()
; #define PG8_SCHED __builtin_amdgcn_sched_barrier(0)
; template <class Epi, class Sched, bool ATILE = false>
; __device__ __forceinline__ void gemm_phase(LAS unsigned char* lds, const Gemm g, const Sched& S, const Epi& E) {
;     ...
;             PG8_BAR; PG8_WAIT_L(0); PG8_MMA(0, 1, At, B1); PG8_BAR;
;             PG8_LDA(At, 1, 1); PG8_STAGE(PG8_SA(1, 0), a3, voffA);
;             PG8_BAR; PG8_WAIT_L(0); PG8_MMA(1, 0, At, B0); PG8_BAR; PG8_SCHED;
;             PG8_STAGE(PG8_SB(1, 1), b3 + hstepB, voffB);
;             PG8_WAIT_V(6); PG8_BAR; PG8_MMA(1, 1, At, B1); PG8_BAR;
;         }
	s_waitcnt lgkmcnt(0)
	v_mfma_f32_16x16x32_bf16 v[124:127], v[222:225], v[144:147], v[124:127]
	v_mfma_f32_16x16x32_bf16 v[112:115], v[230:233], v[144:147], v[112:115]
	v_mfma_f32_16x16x32_bf16 v[104:107], v[222:225], v[192:195], v[104:107]
	v_mfma_f32_16x16x32_bf16 v[96:99], v[230:233], v[192:195], v[96:99]
	v_mfma_f32_16x16x32_bf16 v[88:91], v[222:225], v[200:203], v[88:91]
	v_mfma_f32_16x16x32_bf16 v[80:83], v[230:233], v[200:203], v[80:83]
	v_mfma_f32_16x16x32_bf16 v[72:75], v[222:225], v[214:217], v[72:75]
	v_mfma_f32_16x16x32_bf16 v[64:67], v[230:233], v[214:217], v[64:67]
	v_mfma_f32_16x16x32_bf16 v[124:127], v[226:229], v[148:151], v[124:127]
	v_mfma_f32_16x16x32_bf16 v[112:115], v[234:237], v[148:151], v[112:115]
	v_mfma_f32_16x16x32_bf16 v[104:107], v[226:229], v[196:199], v[104:107]
	v_mfma_f32_16x16x32_bf16 v[96:99], v[234:237], v[196:199], v[96:99]
	v_mfma_f32_16x16x32_bf16 v[88:91], v[226:229], v[204:207], v[88:91]
	v_mfma_f32_16x16x32_bf16 v[80:83], v[234:237], v[204:207], v[80:83]
	v_mfma_f32_16x16x32_bf16 v[72:75], v[226:229], v[218:221], v[72:75]
	v_mfma_f32_16x16x32_bf16 v[64:67], v[234:237], v[218:221], v[64:67]
	s_barrier
	s_setprio 0
	s_mov_b32 m0, s43
	ds_read_b128 v[144:147], v210 offset:49152
	ds_read_b128 v[148:151], v210 offset:50176
	ds_read_b128 v[192:195], v210 offset:51200
	ds_read_b128 v[196:199], v210 offset:52224
	ds_read_b128 v[200:203], v210 offset:53248
	ds_read_b128 v[204:207], v210 offset:54272
	ds_read_b128 v[214:217], v210 offset:55296
	ds_read_b128 v[218:221], v210 offset:56320
	global_load_lds_dwordx4 v160, s[36:37]
	s_mov_b32 m0, s44
	s_nop 0
	global_load_lds_dwordx4 v164, s[36:37]
	s_setprio 1
	s_barrier
	s_waitcnt lgkmcnt(0)
	v_mfma_f32_16x16x32_bf16 v[60:63], v[128:131], v[144:147], v[60:63]
	v_mfma_f32_16x16x32_bf16 v[56:59], v[136:139], v[144:147], v[56:59]
	v_mfma_f32_16x16x32_bf16 v[44:47], v[128:131], v[192:195], v[44:47]
	v_mfma_f32_16x16x32_bf16 v[40:43], v[136:139], v[192:195], v[40:43]
	v_mfma_f32_16x16x32_bf16 v[28:31], v[128:131], v[200:203], v[28:31]
	v_mfma_f32_16x16x32_bf16 v[24:27], v[136:139], v[200:203], v[24:27]
	v_mfma_f32_16x16x32_bf16 v[12:15], v[128:131], v[214:217], v[12:15]
	v_mfma_f32_16x16x32_bf16 v[8:11], v[136:139], v[214:217], v[8:11]
	v_mfma_f32_16x16x32_bf16 v[60:63], v[132:135], v[148:151], v[60:63]
	v_mfma_f32_16x16x32_bf16 v[56:59], v[140:143], v[148:151], v[56:59]
	v_mfma_f32_16x16x32_bf16 v[44:47], v[132:135], v[196:199], v[44:47]
	v_mfma_f32_16x16x32_bf16 v[40:43], v[140:143], v[196:199], v[40:43]
	v_mfma_f32_16x16x32_bf16 v[28:31], v[132:135], v[204:207], v[28:31]
	v_mfma_f32_16x16x32_bf16 v[24:27], v[140:143], v[204:207], v[24:27]
	v_mfma_f32_16x16x32_bf16 v[12:15], v[132:135], v[218:221], v[12:15]
	v_mfma_f32_16x16x32_bf16 v[8:11], v[140:143], v[218:221], v[8:11]
	s_barrier
	s_setprio 0
	s_add_u32 s34, s34, 0x80080
	s_addc_u32 s35, s35, 0
	s_add_i32 s27, s38, s4
	s_mov_b32 m0, s27
	s_nop 0
	global_load_lds_dwordx4 v162, s[34:35]
	s_add_i32 m0, s27, 0x2000
	s_nop 0
	global_load_lds_dwordx4 v166, s[34:35]
	s_waitcnt vmcnt(6)
	s_setprio 1
	s_barrier
	v_mfma_f32_16x16x32_bf16 v[52:55], v[222:225], v[144:147], v[52:55]
	v_mfma_f32_16x16x32_bf16 v[48:51], v[230:233], v[144:147], v[48:51]
	v_mfma_f32_16x16x32_bf16 v[36:39], v[222:225], v[192:195], v[36:39]
	v_mfma_f32_16x16x32_bf16 v[32:35], v[230:233], v[192:195], v[32:35]
	v_mfma_f32_16x16x32_bf16 v[20:23], v[222:225], v[200:203], v[20:23]
	v_mfma_f32_16x16x32_bf16 v[16:19], v[230:233], v[200:203], v[16:19]
	v_mfma_f32_16x16x32_bf16 v[4:7], v[222:225], v[214:217], v[4:7]
	s_add_u32 s13, s13, 0x100
	v_mfma_f32_16x16x32_bf16 v[0:3], v[230:233], v[214:217], v[0:3]
	s_addc_u32 s17, s17, 0
	v_mfma_f32_16x16x32_bf16 v[52:55], v[226:229], v[148:151], v[52:55]
	s_add_u32 s30, s30, 0x10000
	v_mfma_f32_16x16x32_bf16 v[48:51], v[234:237], v[148:151], v[48:51]
	s_addc_u32 s31, s31, 0
	v_mfma_f32_16x16x32_bf16 v[36:39], v[226:229], v[196:199], v[36:39]
	s_cmp_ge_i32 s29, s1
	v_mfma_f32_16x16x32_bf16 v[32:35], v[234:237], v[196:199], v[32:35]
	s_mov_b32 s27, s29
	v_mfma_f32_16x16x32_bf16 v[20:23], v[226:229], v[204:207], v[20:23]
	v_mfma_f32_16x16x32_bf16 v[16:19], v[234:237], v[204:207], v[16:19]
	v_mfma_f32_16x16x32_bf16 v[4:7], v[226:229], v[218:221], v[4:7]
	v_mfma_f32_16x16x32_bf16 v[0:3], v[234:237], v[218:221], v[0:3]
	s_barrier
	s_setprio 0
	s_cbranch_scc0 .LBB0_1658
	s_nop 5
	s_branch .LBB0_1662

; #define PG8_STAGE(bufoff, gbase, voff) do { _Pragma("unroll") for (int _i = 0; _i < 2; ++_i) \
;         __builtin_amdgcn_global_load_lds((const unsigned*)((const char*)(gbase) + (voff)[_i]), (LAS unsigned*)(lds + (bufoff) + ldsw + _i * 8192), 16, 0, 0); } while (0)
; #define PG8_LDA(dst, b, h) do { _Pragma("unroll") for (int m = 0; m < 4; ++m) _Pragma("unroll") for (int k = 0; k < 2; ++k) dst[m][k] = *(const LAS bf16x8*)(lds + PG8_SA(b, h) + aoff + m * 2048 + k * 1024); } while (0)
; #define PG8_LDB(dst, b, h) do { _Pragma("unroll") for (int n = 0; n < 2; ++n) _Pragma("unroll") for (int k = 0; k < 2; ++k) dst[n][k] = *(const LAS bf16x8*)(lds + PG8_SB(b, h) + boff + n * 2048 + k * 1024); } while (0)
; #define PG8_MMA(ai, bj, At, Bt) do { __builtin_amdgcn_s_setprio(1); _Pragma("unroll") for (int m = 0; m < 4; ++m) _Pragma("unroll") for (int n = 0; n < 2; ++n) _Pragma("unroll") for (int k = 0; k < 2; ++k) \
;         acc[ai][bj][m][n] = __builtin_amdgcn_mfma_f32_16x16x32_bf16(Bt[n][k], At[m][k], acc[ai][bj][m][n], 0, 0, 0); __builtin_amdgcn_s_setprio(0); } while (0)
; #define PG8_WAIT_V(n) asm volatile("s_waitcnt vmcnt(" #n ")" ::: "memory")
; #define PG8_WAIT_L(n) asm volatile("s_waitcnt lgkmcnt(" #n ")" ::: "memory")
; template <class Epi, class Sched, bool ATILE = false>
; __device__ __forceinline__ void gemm_phase(LAS unsigned char* lds, const Gemm g, const Sched& S, const Epi& E) {
;     ...
;         for (int t = 0; t < nt; t += 2) {
;             const bool last = (t == nt - 2);
;             const char* a1 = cA + (size_t)(t + 1) * kstepA;
;             const char* a2 = last ? nA : cA + (size_t)(t + 2) * kstepA; const char* b2 = last ? nB : cB + (size_t)(t + 2) * kstep;
;             const char* a3 = a2 + kstepA; const char* b3 = b2 + kstep;
;             PG8_LDB(B0, 0, 0); PG8_SCHED; PG8_LDA(At, 0, 0); PG8_STAGE(PG8_SA(1, 1), a1 + hstepA, voffA);
;             PG8_WAIT_L(8); PG8_BAR; PG8_WAIT_L(0); PG8_MMA(0, 0, At, B0); PG8_BAR; PG8_SCHED;
;             PG8_LDB(B1, 0, 1); PG8_STAGE(PG8_SB(0, 0), b2, voffB);
;             PG8_BAR; PG8_WAIT_L(0); PG8_MMA(0, 1, At, B1); PG8_BAR;
;             PG8_LDA(At, 0, 1); PG8_STAGE(PG8_SA(0, 0), a2, voffA);
;             PG8_BAR; PG8_WAIT_L(0); PG8_MMA(1, 0, At, B0); PG8_BAR; PG8_SCHED;
;             PG8_STAGE(PG8_SB(0, 1), b2 + hstepB, voffB);
;             PG8_WAIT_V(6); PG8_BAR; PG8_MMA(1, 1, At, B1); PG8_BAR;
.LBB0_1812:
	ds_read_b128 v[176:179], v139
	ds_read_b128 v[180:183], v139 offset:1024
	ds_read_b128 v[184:187], v139 offset:2048
	ds_read_b128 v[188:191], v139 offset:3072
	s_add_i32 s34, s8, 2
	s_add_u32 s9, s6, 0xfff80080
	s_addc_u32 s10, s7, -1
	s_cmp_eq_u32 s19, s8
	s_cselect_b32 s8, s18, s25
	s_cselect_b32 s11, s13, s10
	s_cselect_b32 s10, s16, s9
	s_cselect_b32 s9, s17, s27
	s_add_i32 m0, s37, 0xc000
	ds_read_b128 v[192:195], v159
	ds_read_b128 v[196:199], v159 offset:1024
	ds_read_b128 v[200:203], v159 offset:2048
	ds_read_b128 v[204:207], v159 offset:3072
	ds_read_b128 v[208:211], v159 offset:4096
	ds_read_b128 v[212:215], v159 offset:5120
	ds_read_b128 v[216:219], v159 offset:6144
	ds_read_b128 v[220:223], v159 offset:7168
	global_load_lds_dwordx4 v164, s[6:7]
	s_add_i32 m0, s37, 0xe000
	s_nop 0
	global_load_lds_dwordx4 v166, s[6:7]
	s_waitcnt lgkmcnt(8)
	s_setprio 1
	s_barrier
	s_waitcnt lgkmcnt(0)
	v_mfma_f32_16x16x32_bf16 v[120:123], v[176:179], v[192:195], v[120:123]
	v_mfma_f32_16x16x32_bf16 v[112:115], v[184:187], v[192:195], v[112:115]
	v_mfma_f32_16x16x32_bf16 v[104:107], v[176:179], v[200:203], v[104:107]
	v_mfma_f32_16x16x32_bf16 v[96:99], v[184:187], v[200:203], v[96:99]
	v_mfma_f32_16x16x32_bf16 v[88:91], v[176:179], v[208:211], v[88:91]
	v_mfma_f32_16x16x32_bf16 v[80:83], v[184:187], v[208:211], v[80:83]
	v_mfma_f32_16x16x32_bf16 v[72:75], v[176:179], v[216:219], v[72:75]
	v_mfma_f32_16x16x32_bf16 v[64:67], v[184:187], v[216:219], v[64:67]
	v_mfma_f32_16x16x32_bf16 v[120:123], v[180:183], v[196:199], v[120:123]
	v_mfma_f32_16x16x32_bf16 v[112:115], v[188:191], v[196:199], v[112:115]
	v_mfma_f32_16x16x32_bf16 v[104:107], v[180:183], v[204:207], v[104:107]
	v_mfma_f32_16x16x32_bf16 v[96:99], v[188:191], v[204:207], v[96:99]
	v_mfma_f32_16x16x32_bf16 v[88:91], v[180:183], v[212:215], v[88:91]
	v_mfma_f32_16x16x32_bf16 v[80:83], v[188:191], v[212:215], v[80:83]
	v_mfma_f32_16x16x32_bf16 v[72:75], v[180:183], v[220:223], v[72:75]
	v_mfma_f32_16x16x32_bf16 v[64:67], v[188:191], v[220:223], v[64:67]
	s_barrier
	s_setprio 0
	s_add_i32 s35, s51, s36
	s_add_u32 s98, s8, s22
	s_addc_u32 s99, s9, s23
	s_mov_b32 m0, s35
	ds_read_b128 v[224:227], v173
	ds_read_b128 v[228:231], v173 offset:1024
	ds_read_b128 v[232:235], v173 offset:2048
	ds_read_b128 v[236:239], v173 offset:3072
	global_load_lds_dwordx4 v130, s[8:9]
	s_add_i32 m0, s35, 0x2000
	s_nop 0
	global_load_lds_dwordx4 v134, s[8:9]
	s_setprio 1
	s_barrier
	s_waitcnt lgkmcnt(0)
	v_mfma_f32_16x16x32_bf16 v[124:127], v[224:227], v[192:195], v[124:127]
	v_mfma_f32_16x16x32_bf16 v[116:119], v[232:235], v[192:195], v[116:119]
	v_mfma_f32_16x16x32_bf16 v[108:111], v[224:227], v[200:203], v[108:111]
	v_mfma_f32_16x16x32_bf16 v[100:103], v[232:235], v[200:203], v[100:103]
	v_mfma_f32_16x16x32_bf16 v[92:95], v[224:227], v[208:211], v[92:95]
	v_mfma_f32_16x16x32_bf16 v[84:87], v[232:235], v[208:211], v[84:87]
	v_mfma_f32_16x16x32_bf16 v[76:79], v[224:227], v[216:219], v[76:79]
	v_mfma_f32_16x16x32_bf16 v[68:71], v[232:235], v[216:219], v[68:71]
	v_mfma_f32_16x16x32_bf16 v[124:127], v[228:231], v[196:199], v[124:127]
	v_mfma_f32_16x16x32_bf16 v[116:119], v[236:239], v[196:199], v[116:119]
	v_mfma_f32_16x16x32_bf16 v[108:111], v[228:231], v[204:207], v[108:111]
	v_mfma_f32_16x16x32_bf16 v[100:103], v[236:239], v[204:207], v[100:103]
	v_mfma_f32_16x16x32_bf16 v[92:95], v[228:231], v[212:215], v[92:95]
	v_mfma_f32_16x16x32_bf16 v[84:87], v[236:239], v[212:215], v[84:87]
	v_mfma_f32_16x16x32_bf16 v[76:79], v[228:231], v[220:223], v[76:79]
	v_mfma_f32_16x16x32_bf16 v[68:71], v[236:239], v[220:223], v[68:71]
	s_barrier
	s_setprio 0
	s_mov_b32 m0, s37
	s_add_u32 s100, s10, s22
	s_addc_u32 s101, s11, s23
	ds_read_b128 v[192:195], v159 offset:16384
	ds_read_b128 v[196:199], v159 offset:17408
	ds_read_b128 v[200:203], v159 offset:18432
	ds_read_b128 v[204:207], v159 offset:19456
	ds_read_b128 v[208:211], v159 offset:20480
	ds_read_b128 v[212:215], v159 offset:21504
	ds_read_b128 v[216:219], v159 offset:22528
	ds_read_b128 v[220:223], v159 offset:23552
	global_load_lds_dwordx4 v128, s[10:11]
	s_mov_b32 m0, s38
	s_nop 0
	global_load_lds_dwordx4 v132, s[10:11]
	s_setprio 1
	s_barrier
	s_waitcnt lgkmcnt(0)
	v_mfma_f32_16x16x32_bf16 v[56:59], v[176:179], v[192:195], v[56:59]
	v_mfma_f32_16x16x32_bf16 v[48:51], v[184:187], v[192:195], v[48:51]
	v_mfma_f32_16x16x32_bf16 v[40:43], v[176:179], v[200:203], v[40:43]
	v_mfma_f32_16x16x32_bf16 v[32:35], v[184:187], v[200:203], v[32:35]
	v_mfma_f32_16x16x32_bf16 v[24:27], v[176:179], v[208:211], v[24:27]
	v_mfma_f32_16x16x32_bf16 v[16:19], v[184:187], v[208:211], v[16:19]
	v_mfma_f32_16x16x32_bf16 v[8:11], v[176:179], v[216:219], v[8:11]
	v_mfma_f32_16x16x32_bf16 v[4:7], v[184:187], v[216:219], v[4:7]
	v_mfma_f32_16x16x32_bf16 v[56:59], v[180:183], v[196:199], v[56:59]
	v_mfma_f32_16x16x32_bf16 v[48:51], v[188:191], v[196:199], v[48:51]
	v_mfma_f32_16x16x32_bf16 v[40:43], v[180:183], v[204:207], v[40:43]
	v_mfma_f32_16x16x32_bf16 v[32:35], v[188:191], v[204:207], v[32:35]
	v_mfma_f32_16x16x32_bf16 v[24:27], v[180:183], v[212:215], v[24:27]
	v_mfma_f32_16x16x32_bf16 v[16:19], v[188:191], v[212:215], v[16:19]
	v_mfma_f32_16x16x32_bf16 v[8:11], v[180:183], v[220:223], v[8:11]
	v_mfma_f32_16x16x32_bf16 v[4:7], v[188:191], v[220:223], v[4:7]
	s_barrier
	s_setprio 0
	s_add_u32 s54, s8, 0x80000
	s_addc_u32 s55, s9, 0
	s_add_i32 s35, s52, s36
	s_mov_b32 m0, s35
	s_nop 0
	global_load_lds_dwordx4 v130, s[54:55]
	s_add_i32 m0, s35, 0x2000
	s_nop 0
	global_load_lds_dwordx4 v134, s[54:55]
	s_waitcnt vmcnt(6)
	s_setprio 1
	s_barrier
; #define PG8_STAGE(bufoff, gbase, voff) do { _Pragma("unroll") for (int _i = 0; _i < 2; ++_i) \
;         __builtin_amdgcn_global_load_lds((const unsigned*)((const char*)(gbase) + (voff)[_i]), (LAS unsigned*)(lds + (bufoff) + ldsw + _i * 8192), 16, 0, 0); } while (0)
; #define PG8_LDA(dst, b, h) do { _Pragma("unroll") for (int m = 0; m < 4; ++m) _Pragma("unroll") for (int k = 0; k < 2; ++k) dst[m][k] = *(const LAS bf16x8*)(lds + PG8_SA(b, h) + aoff + m * 2048 + k * 1024); } while (0)
; #define PG8_LDB(dst, b, h) do { _Pragma("unroll") for (int n = 0; n < 2; ++n) _Pragma("unroll") for (int k = 0; k < 2; ++k) dst[n][k] = *(const LAS bf16x8*)(lds + PG8_SB(b, h) + boff + n * 2048 + k * 1024); } while (0)
; #define PG8_MMA(ai, bj, At, Bt) do { __builtin_amdgcn_s_setprio(1); _Pragma("unroll") for (int m = 0; m < 4; ++m) _Pragma("unroll") for (int n = 0; n < 2; ++n) _Pragma("unroll") for (int k = 0; k < 2; ++k) \
;         acc[ai][bj][m][n] = __builtin_amdgcn_mfma_f32_16x16x32_bf16(Bt[n][k], At[m][k], acc[ai][bj][m][n], 0, 0, 0); __builtin_amdgcn_s_setprio(0); } while (0)
; #define PG8_WAIT_V(n) asm volatile("s_waitcnt vmcnt(" #n ")" ::: "memory")
; #define PG8_WAIT_L(n) asm volatile("s_waitcnt lgkmcnt(" #n ")" ::: "memory")
; #define PG8_BAR __builtin_amdgcn_s_barrier()
; #define PG8_SCHED __builtin_amdgcn_sched_barrier(0)
; template <class Epi, class Sched, bool ATILE = false>
; __device__ __forceinline__ void gemm_phase(LAS unsigned char* lds, const Gemm g, const Sched& S, const Epi& E) {
;     ...
;             PG8_WAIT_V(6); PG8_BAR; PG8_MMA(1, 1, At, B1); PG8_BAR;
;             PG8_LDB(B0, 1, 0); PG8_SCHED; PG8_LDA(At, 1, 0); PG8_STAGE(PG8_SA(0, 1), a2 + hstepA, voffA);
;             PG8_WAIT_L(8); PG8_BAR; PG8_WAIT_L(0); PG8_MMA(0, 0, At, B0); PG8_BAR; PG8_SCHED;
;             PG8_LDB(B1, 1, 1); PG8_STAGE(PG8_SB(1, 0), b3, voffB);
;             PG8_BAR; PG8_WAIT_L(0); PG8_MMA(0, 1, At, B1); PG8_BAR;
	v_mfma_f32_16x16x32_bf16 v[60:63], v[224:227], v[192:195], v[60:63]
	v_mfma_f32_16x16x32_bf16 v[52:55], v[232:235], v[192:195], v[52:55]
	v_mfma_f32_16x16x32_bf16 v[44:47], v[224:227], v[200:203], v[44:47]
	v_mfma_f32_16x16x32_bf16 v[36:39], v[232:235], v[200:203], v[36:39]
	v_mfma_f32_16x16x32_bf16 v[28:31], v[224:227], v[208:211], v[28:31]
	v_mfma_f32_16x16x32_bf16 v[20:23], v[232:235], v[208:211], v[20:23]
	v_mfma_f32_16x16x32_bf16 v[12:15], v[224:227], v[216:219], v[12:15]
	v_mfma_f32_16x16x32_bf16 v[0:3], v[232:235], v[216:219], v[0:3]
	v_mfma_f32_16x16x32_bf16 v[60:63], v[228:231], v[196:199], v[60:63]
	v_mfma_f32_16x16x32_bf16 v[52:55], v[236:239], v[196:199], v[52:55]
	v_mfma_f32_16x16x32_bf16 v[44:47], v[228:231], v[204:207], v[44:47]
	v_mfma_f32_16x16x32_bf16 v[36:39], v[236:239], v[204:207], v[36:39]
	v_mfma_f32_16x16x32_bf16 v[28:31], v[228:231], v[212:215], v[28:31]
	v_mfma_f32_16x16x32_bf16 v[20:23], v[236:239], v[212:215], v[20:23]
	v_mfma_f32_16x16x32_bf16 v[12:15], v[228:231], v[220:223], v[12:15]
	v_mfma_f32_16x16x32_bf16 v[0:3], v[236:239], v[220:223], v[0:3]
	s_barrier
	s_setprio 0
	s_add_i32 s35, 0, 0x18000
	v_add_u32_e32 v172, s35, v157
	ds_read_b128 v[176:179], v172
	ds_read_b128 v[180:183], v172 offset:1024
	ds_read_b128 v[184:187], v172 offset:2048
	ds_read_b128 v[188:191], v172 offset:3072
	s_add_u32 s10, s10, 0x80000
	s_addc_u32 s11, s11, 0
	s_mov_b32 m0, s39
	ds_read_b128 v[192:195], v159 offset:32768
	ds_read_b128 v[196:199], v159 offset:33792
	ds_read_b128 v[200:203], v159 offset:34816
	ds_read_b128 v[204:207], v159 offset:35840
	ds_read_b128 v[208:211], v159 offset:36864
	ds_read_b128 v[212:215], v159 offset:37888
	ds_read_b128 v[216:219], v159 offset:38912
	ds_read_b128 v[220:223], v159 offset:39936
	global_load_lds_dwordx4 v128, s[10:11]
	s_mov_b32 m0, s40
	s_nop 0
	global_load_lds_dwordx4 v132, s[10:11]
	s_waitcnt lgkmcnt(8)
	s_setprio 1
	s_barrier
	s_waitcnt lgkmcnt(0)
	v_mfma_f32_16x16x32_bf16 v[120:123], v[176:179], v[192:195], v[120:123]
	v_mfma_f32_16x16x32_bf16 v[112:115], v[184:187], v[192:195], v[112:115]
	v_mfma_f32_16x16x32_bf16 v[104:107], v[176:179], v[200:203], v[104:107]
	v_mfma_f32_16x16x32_bf16 v[96:99], v[184:187], v[200:203], v[96:99]
	v_mfma_f32_16x16x32_bf16 v[88:91], v[176:179], v[208:211], v[88:91]
	v_mfma_f32_16x16x32_bf16 v[80:83], v[184:187], v[208:211], v[80:83]
	v_mfma_f32_16x16x32_bf16 v[72:75], v[176:179], v[216:219], v[72:75]
	v_mfma_f32_16x16x32_bf16 v[64:67], v[184:187], v[216:219], v[64:67]
	v_mfma_f32_16x16x32_bf16 v[120:123], v[180:183], v[196:199], v[120:123]
	v_mfma_f32_16x16x32_bf16 v[112:115], v[188:191], v[196:199], v[112:115]
	v_mfma_f32_16x16x32_bf16 v[104:107], v[180:183], v[204:207], v[104:107]
	v_mfma_f32_16x16x32_bf16 v[96:99], v[188:191], v[204:207], v[96:99]
	v_mfma_f32_16x16x32_bf16 v[88:91], v[180:183], v[212:215], v[88:91]
	v_mfma_f32_16x16x32_bf16 v[80:83], v[188:191], v[212:215], v[80:83]
	v_mfma_f32_16x16x32_bf16 v[72:75], v[180:183], v[220:223], v[72:75]
	v_mfma_f32_16x16x32_bf16 v[64:67], v[188:191], v[220:223], v[64:67]
	s_barrier
	s_setprio 0
	s_add_i32 s10, 0, 0x1c000
	s_add_i32 s11, s35, s36
	v_add_u32_e32 v172, s10, v157
	s_mov_b32 m0, s11
	ds_read_b128 v[224:227], v172
	ds_read_b128 v[228:231], v172 offset:1024
	ds_read_b128 v[232:235], v172 offset:2048
	ds_read_b128 v[236:239], v172 offset:3072
	global_load_lds_dwordx4 v130, s[98:99]
	s_add_i32 m0, s11, 0x2000
	s_nop 0
	global_load_lds_dwordx4 v134, s[98:99]
	s_setprio 1
	s_barrier
; #define PG8_STAGE(bufoff, gbase, voff) do { _Pragma("unroll") for (int _i = 0; _i < 2; ++_i) \
;         __builtin_amdgcn_global_load_lds((const unsigned*)((const char*)(gbase) + (voff)[_i]), (LAS unsigned*)(lds + (bufoff) + ldsw + _i * 8192), 16, 0, 0); } while (0)
; #define PG8_LDA(dst, b, h) do { _Pragma("unroll") for (int m = 0; m < 4; ++m) _Pragma("unroll") for (int k = 0; k < 2; ++k) dst[m][k] = *(const LAS bf16x8*)(lds + PG8_SA(b, h) + aoff + m * 2048 + k * 1024); } while (0)
; #define PG8_LDB(dst, b, h) do { _Pragma("unroll") for (int n = 0; n < 2; ++n) _Pragma("unroll") for (int k = 0; k < 2; ++k) dst[n][k] = *(const LAS bf16x8*)(lds + PG8_SB(b, h) + boff + n * 2048 + k * 1024); } while (0)
; #define PG8_MMA(ai, bj, At, Bt) do { __builtin_amdgcn_s_setprio(1); _Pragma("unroll") for (int m = 0; m < 4; ++m) _Pragma("unroll") for (int n = 0; n < 2; ++n) _Pragma("unroll") for (int k = 0; k < 2; ++k) \
;         acc[ai][bj][m][n] = __builtin_amdgcn_mfma_f32_16x16x32_bf16(Bt[n][k], At[m][k], acc[ai][bj][m][n], 0, 0, 0); __builtin_amdgcn_s_setprio(0); } while (0)
; #define PG8_WAIT_V(n) asm volatile("s_waitcnt vmcnt(" #n ")" ::: "memory")
; #define PG8_WAIT_L(n) asm volatile("s_waitcnt lgkmcnt(" #n ")" ::: "memory")
; #define PG8_BAR __builtin_amdgcn_s_barrier()
; #define PG8_SCHED __builtin_amdgcn_sched_barrier(0)
; template <class Epi, class Sched, bool ATILE = false>
; __device__ __forceinline__ void gemm_phase(LAS unsigned char* lds, const Gemm g, const Sched& S, const Epi& E) {
;     ...
;             PG8_LDB(B1, 1, 1); PG8_STAGE(PG8_SB(1, 0), b3, voffB);
;             PG8_BAR; PG8_WAIT_L(0); PG8_MMA(0, 1, At, B1); PG8_BAR;
;             PG8_LDA(At, 1, 1); PG8_STAGE(PG8_SA(1, 0), a3, voffA);
;             PG8_BAR; PG8_WAIT_L(0); PG8_MMA(1, 0, At, B0); PG8_BAR; PG8_SCHED;
;             PG8_STAGE(PG8_SB(1, 1), b3 + hstepB, voffB);
;             PG8_WAIT_V(6); PG8_BAR; PG8_MMA(1, 1, At, B1); PG8_BAR;
;         }
	s_waitcnt lgkmcnt(0)
	v_mfma_f32_16x16x32_bf16 v[124:127], v[224:227], v[192:195], v[124:127]
	v_mfma_f32_16x16x32_bf16 v[116:119], v[232:235], v[192:195], v[116:119]
	v_mfma_f32_16x16x32_bf16 v[108:111], v[224:227], v[200:203], v[108:111]
	v_mfma_f32_16x16x32_bf16 v[100:103], v[232:235], v[200:203], v[100:103]
	v_mfma_f32_16x16x32_bf16 v[92:95], v[224:227], v[208:211], v[92:95]
	v_mfma_f32_16x16x32_bf16 v[84:87], v[232:235], v[208:211], v[84:87]
	v_mfma_f32_16x16x32_bf16 v[76:79], v[224:227], v[216:219], v[76:79]
	v_mfma_f32_16x16x32_bf16 v[68:71], v[232:235], v[216:219], v[68:71]
	v_mfma_f32_16x16x32_bf16 v[124:127], v[228:231], v[196:199], v[124:127]
	v_mfma_f32_16x16x32_bf16 v[116:119], v[236:239], v[196:199], v[116:119]
	v_mfma_f32_16x16x32_bf16 v[108:111], v[228:231], v[204:207], v[108:111]
	v_mfma_f32_16x16x32_bf16 v[100:103], v[236:239], v[204:207], v[100:103]
	v_mfma_f32_16x16x32_bf16 v[92:95], v[228:231], v[212:215], v[92:95]
	v_mfma_f32_16x16x32_bf16 v[84:87], v[236:239], v[212:215], v[84:87]
	v_mfma_f32_16x16x32_bf16 v[76:79], v[228:231], v[220:223], v[76:79]
	v_mfma_f32_16x16x32_bf16 v[68:71], v[236:239], v[220:223], v[68:71]
	s_barrier
	s_setprio 0
	s_mov_b32 m0, s43
	ds_read_b128 v[192:195], v159 offset:49152
	ds_read_b128 v[196:199], v159 offset:50176
	ds_read_b128 v[200:203], v159 offset:51200
	ds_read_b128 v[204:207], v159 offset:52224
	ds_read_b128 v[208:211], v159 offset:53248
	ds_read_b128 v[212:215], v159 offset:54272
	ds_read_b128 v[216:219], v159 offset:55296
	ds_read_b128 v[220:223], v159 offset:56320
	global_load_lds_dwordx4 v128, s[100:101]
	s_mov_b32 m0, s44
	s_nop 0
	global_load_lds_dwordx4 v132, s[100:101]
	s_setprio 1
	s_barrier
	s_waitcnt lgkmcnt(0)
	v_mfma_f32_16x16x32_bf16 v[56:59], v[176:179], v[192:195], v[56:59]
	v_mfma_f32_16x16x32_bf16 v[48:51], v[184:187], v[192:195], v[48:51]
	v_mfma_f32_16x16x32_bf16 v[40:43], v[176:179], v[200:203], v[40:43]
	v_mfma_f32_16x16x32_bf16 v[32:35], v[184:187], v[200:203], v[32:35]
	v_mfma_f32_16x16x32_bf16 v[24:27], v[176:179], v[208:211], v[24:27]
	v_mfma_f32_16x16x32_bf16 v[16:19], v[184:187], v[208:211], v[16:19]
	v_mfma_f32_16x16x32_bf16 v[8:11], v[176:179], v[216:219], v[8:11]
	v_mfma_f32_16x16x32_bf16 v[4:7], v[184:187], v[216:219], v[4:7]
	v_mfma_f32_16x16x32_bf16 v[56:59], v[180:183], v[196:199], v[56:59]
	v_mfma_f32_16x16x32_bf16 v[48:51], v[188:191], v[196:199], v[48:51]
	v_mfma_f32_16x16x32_bf16 v[40:43], v[180:183], v[204:207], v[40:43]
	v_mfma_f32_16x16x32_bf16 v[32:35], v[188:191], v[204:207], v[32:35]
	v_mfma_f32_16x16x32_bf16 v[24:27], v[180:183], v[212:215], v[24:27]
	v_mfma_f32_16x16x32_bf16 v[16:19], v[188:191], v[212:215], v[16:19]
	v_mfma_f32_16x16x32_bf16 v[8:11], v[180:183], v[220:223], v[8:11]
	v_mfma_f32_16x16x32_bf16 v[4:7], v[188:191], v[220:223], v[4:7]
	s_barrier
	s_setprio 0
	s_add_u32 s8, s8, 0x80080
	s_addc_u32 s9, s9, 0
	s_add_i32 s10, s10, s36
	s_mov_b32 m0, s10
	s_nop 0
	global_load_lds_dwordx4 v130, s[8:9]
	s_add_i32 m0, s10, 0x2000
	s_nop 0
	global_load_lds_dwordx4 v134, s[8:9]
	s_waitcnt vmcnt(6)
	s_setprio 1
	s_barrier
	v_mfma_f32_16x16x32_bf16 v[60:63], v[224:227], v[192:195], v[60:63]
	v_mfma_f32_16x16x32_bf16 v[52:55], v[232:235], v[192:195], v[52:55]
	v_mfma_f32_16x16x32_bf16 v[44:47], v[224:227], v[200:203], v[44:47]
	v_mfma_f32_16x16x32_bf16 v[36:39], v[232:235], v[200:203], v[36:39]
	v_mfma_f32_16x16x32_bf16 v[28:31], v[224:227], v[208:211], v[28:31]
	v_mfma_f32_16x16x32_bf16 v[20:23], v[232:235], v[208:211], v[20:23]
	v_mfma_f32_16x16x32_bf16 v[12:15], v[224:227], v[216:219], v[12:15]
	s_add_u32 s6, s6, 0x100
	v_mfma_f32_16x16x32_bf16 v[0:3], v[232:235], v[216:219], v[0:3]
	s_addc_u32 s7, s7, 0
	v_mfma_f32_16x16x32_bf16 v[60:63], v[228:231], v[196:199], v[60:63]
	s_add_u32 s25, s25, 0x100
	v_mfma_f32_16x16x32_bf16 v[52:55], v[236:239], v[196:199], v[52:55]
	s_addc_u32 s27, s27, 0
	v_mfma_f32_16x16x32_bf16 v[44:47], v[228:231], v[204:207], v[44:47]
	s_cmp_ge_i32 s34, s12
	v_mfma_f32_16x16x32_bf16 v[36:39], v[236:239], v[204:207], v[36:39]
	s_mov_b32 s8, s34
	v_mfma_f32_16x16x32_bf16 v[28:31], v[228:231], v[212:215], v[28:31]
	v_mfma_f32_16x16x32_bf16 v[20:23], v[236:239], v[212:215], v[20:23]
	v_mfma_f32_16x16x32_bf16 v[12:15], v[228:231], v[220:223], v[12:15]
	v_mfma_f32_16x16x32_bf16 v[0:3], v[236:239], v[220:223], v[0:3]
	s_barrier
	s_setprio 0
	s_cbranch_scc0 .LBB0_1812
	s_nop 5
	s_branch .LBB0_1803

; #define PG8_STAGE(bufoff, gbase, voff) do { _Pragma("unroll") for (int _i = 0; _i < 2; ++_i) \
;         __builtin_amdgcn_global_load_lds((const unsigned*)((const char*)(gbase) + (voff)[_i]), (LAS unsigned*)(lds + (bufoff) + ldsw + _i * 8192), 16, 0, 0); } while (0)
; #define PG8_LDA(dst, b, h) do { _Pragma("unroll") for (int m = 0; m < 4; ++m) _Pragma("unroll") for (int k = 0; k < 2; ++k) dst[m][k] = *(const LAS bf16x8*)(lds + PG8_SA(b, h) + aoff + m * 2048 + k * 1024); } while (0)
; #define PG8_LDB(dst, b, h) do { _Pragma("unroll") for (int n = 0; n < 2; ++n) _Pragma("unroll") for (int k = 0; k < 2; ++k) dst[n][k] = *(const LAS bf16x8*)(lds + PG8_SB(b, h) + boff + n * 2048 + k * 1024); } while (0)
; #define PG8_MMA(ai, bj, At, Bt) do { __builtin_amdgcn_s_setprio(1); _Pragma("unroll") for (int m = 0; m < 4; ++m) _Pragma("unroll") for (int n = 0; n < 2; ++n) _Pragma("unroll") for (int k = 0; k < 2; ++k) \
;         acc[ai][bj][m][n] = __builtin_amdgcn_mfma_f32_16x16x32_bf16(Bt[n][k], At[m][k], acc[ai][bj][m][n], 0, 0, 0); __builtin_amdgcn_s_setprio(0); } while (0)
; #define PG8_WAIT_V(n) asm volatile("s_waitcnt vmcnt(" #n ")" ::: "memory")
; #define PG8_WAIT_L(n) asm volatile("s_waitcnt lgkmcnt(" #n ")" ::: "memory")
; template <class Epi, class Sched, bool ATILE = false>
; __device__ __forceinline__ void gemm_phase(LAS unsigned char* lds, const Gemm g, const Sched& S, const Epi& E) {
;     ...
;         for (int t = 0; t < nt; t += 2) {
;             const bool last = (t == nt - 2);
;             const char* a1 = cA + (size_t)(t + 1) * kstepA;
;             const char* a2 = last ? nA : cA + (size_t)(t + 2) * kstepA; const char* b2 = last ? nB : cB + (size_t)(t + 2) * kstep;
;             const char* a3 = a2 + kstepA; const char* b3 = b2 + kstep;
;             PG8_LDB(B0, 0, 0); PG8_SCHED; PG8_LDA(At, 0, 0); PG8_STAGE(PG8_SA(1, 1), a1 + hstepA, voffA);
;             PG8_WAIT_L(8); PG8_BAR; PG8_WAIT_L(0); PG8_MMA(0, 0, At, B0); PG8_BAR; PG8_SCHED;
;             PG8_LDB(B1, 0, 1); PG8_STAGE(PG8_SB(0, 0), b2, voffB);
;             PG8_BAR; PG8_WAIT_L(0); PG8_MMA(0, 1, At, B1); PG8_BAR;
;             PG8_LDA(At, 0, 1); PG8_STAGE(PG8_SA(0, 0), a2, voffA);
;             PG8_BAR; PG8_WAIT_L(0); PG8_MMA(1, 0, At, B0); PG8_BAR; PG8_SCHED;
;             PG8_STAGE(PG8_SB(0, 1), b2 + hstepB, voffB);
;             PG8_WAIT_V(6); PG8_BAR; PG8_MMA(1, 1, At, B1); PG8_BAR;
.LBB0_1898:
	ds_read_b128 v[20:23], v180
	ds_read_b128 v[28:31], v180 offset:1024
	ds_read_b128 v[174:177], v180 offset:2048
	ds_read_b128 v[184:187], v180 offset:3072
	s_add_i32 s58, s26, 2
	s_add_u32 s27, s24, 0x4000
	s_addc_u32 s28, s25, 0
	s_cmp_eq_u32 s17, s26
	s_cselect_b32 s30, s20, s27
	s_cselect_b32 s31, s21, s28
	s_cselect_b32 s26, s22, s56
	s_cselect_b32 s27, s23, s57
	s_add_u32 s28, s30, 0x8000
	s_addc_u32 s29, s31, 0
	s_add_i32 m0, s34, 0xc000
	ds_read_b128 v[188:191], v181
	ds_read_b128 v[192:195], v181 offset:1024
	ds_read_b128 v[196:199], v181 offset:2048
	ds_read_b128 v[200:203], v181 offset:3072
	ds_read_b128 v[204:207], v181 offset:4096
	ds_read_b128 v[208:211], v181 offset:5120
	ds_read_b128 v[212:215], v181 offset:6144
	ds_read_b128 v[216:219], v181 offset:7168
	global_load_lds_dwordx4 v168, s[24:25]
	s_add_i32 m0, s34, 0xe000
	s_nop 0
	global_load_lds_dwordx4 v170, s[24:25]
	s_waitcnt lgkmcnt(8)
	s_setprio 1
	s_barrier
	s_waitcnt lgkmcnt(0)
	v_mfma_f32_16x16x32_bf16 v[0:3], v[20:23], v[188:191], v[0:3]
	v_mfma_f32_16x16x32_bf16 v[4:7], v[174:177], v[188:191], v[4:7]
	v_mfma_f32_16x16x32_bf16 v[44:47], v[20:23], v[196:199], v[44:47]
	v_mfma_f32_16x16x32_bf16 v[36:39], v[174:177], v[196:199], v[36:39]
	v_mfma_f32_16x16x32_bf16 v[52:55], v[20:23], v[204:207], v[52:55]
	v_mfma_f32_16x16x32_bf16 v[48:51], v[174:177], v[204:207], v[48:51]
	v_mfma_f32_16x16x32_bf16 v[92:95], v[20:23], v[212:215], v[92:95]
	v_mfma_f32_16x16x32_bf16 v[84:87], v[174:177], v[212:215], v[84:87]
	v_mfma_f32_16x16x32_bf16 v[0:3], v[28:31], v[192:195], v[0:3]
	v_mfma_f32_16x16x32_bf16 v[4:7], v[184:187], v[192:195], v[4:7]
	v_mfma_f32_16x16x32_bf16 v[44:47], v[28:31], v[200:203], v[44:47]
	v_mfma_f32_16x16x32_bf16 v[36:39], v[184:187], v[200:203], v[36:39]
	v_mfma_f32_16x16x32_bf16 v[52:55], v[28:31], v[208:211], v[52:55]
	v_mfma_f32_16x16x32_bf16 v[48:51], v[184:187], v[208:211], v[48:51]
	v_mfma_f32_16x16x32_bf16 v[92:95], v[28:31], v[216:219], v[92:95]
	v_mfma_f32_16x16x32_bf16 v[84:87], v[184:187], v[216:219], v[84:87]
	s_barrier
	s_setprio 0
	s_add_i32 s59, s44, s33
	s_add_u32 s98, s26, s4
	s_addc_u32 s99, s27, s5
	s_mov_b32 m0, s59
	ds_read_b128 v[220:223], v182
	ds_read_b128 v[224:227], v182 offset:1024
	ds_read_b128 v[228:231], v182 offset:2048
	ds_read_b128 v[232:235], v182 offset:3072
	global_load_lds_dwordx4 v138, s[26:27]
	s_add_i32 m0, s59, 0x2000
	s_nop 0
	global_load_lds_dwordx4 v142, s[26:27]
	s_setprio 1
	s_barrier
	s_waitcnt lgkmcnt(0)
	v_mfma_f32_16x16x32_bf16 v[12:15], v[220:223], v[188:191], v[12:15]
	v_mfma_f32_16x16x32_bf16 v[8:11], v[228:231], v[188:191], v[8:11]
	v_mfma_f32_16x16x32_bf16 v[24:27], v[220:223], v[196:199], v[24:27]
	v_mfma_f32_16x16x32_bf16 v[16:19], v[228:231], v[196:199], v[16:19]
	v_mfma_f32_16x16x32_bf16 v[40:43], v[220:223], v[204:207], v[40:43]
	v_mfma_f32_16x16x32_bf16 v[32:35], v[228:231], v[204:207], v[32:35]
	v_mfma_f32_16x16x32_bf16 v[56:59], v[220:223], v[212:215], v[56:59]
	v_mfma_f32_16x16x32_bf16 v[60:63], v[228:231], v[212:215], v[60:63]
	v_mfma_f32_16x16x32_bf16 v[12:15], v[224:227], v[192:195], v[12:15]
	v_mfma_f32_16x16x32_bf16 v[8:11], v[232:235], v[192:195], v[8:11]
	v_mfma_f32_16x16x32_bf16 v[24:27], v[224:227], v[200:203], v[24:27]
	v_mfma_f32_16x16x32_bf16 v[16:19], v[232:235], v[200:203], v[16:19]
	v_mfma_f32_16x16x32_bf16 v[40:43], v[224:227], v[208:211], v[40:43]
	v_mfma_f32_16x16x32_bf16 v[32:35], v[232:235], v[208:211], v[32:35]
	v_mfma_f32_16x16x32_bf16 v[56:59], v[224:227], v[216:219], v[56:59]
	v_mfma_f32_16x16x32_bf16 v[60:63], v[232:235], v[216:219], v[60:63]
	s_barrier
	s_setprio 0
	s_mov_b32 m0, s34
	ds_read_b128 v[188:191], v181 offset:16384
	ds_read_b128 v[192:195], v181 offset:17408
	ds_read_b128 v[196:199], v181 offset:18432
	ds_read_b128 v[200:203], v181 offset:19456
	ds_read_b128 v[204:207], v181 offset:20480
	ds_read_b128 v[208:211], v181 offset:21504
	ds_read_b128 v[212:215], v181 offset:22528
	ds_read_b128 v[216:219], v181 offset:23552
	global_load_lds_dwordx4 v136, s[30:31]
	s_mov_b32 m0, s35
	s_nop 0
	global_load_lds_dwordx4 v140, s[30:31]
	s_setprio 1
	s_barrier
	s_waitcnt lgkmcnt(0)
	v_mfma_f32_16x16x32_bf16 v[64:67], v[20:23], v[188:191], v[64:67]
	v_mfma_f32_16x16x32_bf16 v[68:71], v[174:177], v[188:191], v[68:71]
	v_mfma_f32_16x16x32_bf16 v[108:111], v[20:23], v[196:199], v[108:111]
	v_mfma_f32_16x16x32_bf16 v[100:103], v[174:177], v[196:199], v[100:103]
	v_mfma_f32_16x16x32_bf16 v[116:119], v[20:23], v[204:207], v[116:119]
	v_mfma_f32_16x16x32_bf16 v[112:115], v[174:177], v[204:207], v[112:115]
	v_mfma_f32_16x16x32_bf16 v[20:23], v[20:23], v[212:215], v[132:135]
	v_mfma_f32_16x16x32_bf16 v[64:67], v[28:31], v[192:195], v[64:67]
	v_mfma_f32_16x16x32_bf16 v[68:71], v[184:187], v[192:195], v[68:71]
	v_mfma_f32_16x16x32_bf16 v[108:111], v[28:31], v[200:203], v[108:111]
	v_mfma_f32_16x16x32_bf16 v[100:103], v[184:187], v[200:203], v[100:103]
	v_mfma_f32_16x16x32_bf16 v[116:119], v[28:31], v[208:211], v[116:119]
	v_mfma_f32_16x16x32_bf16 v[112:115], v[184:187], v[208:211], v[112:115]
	v_mfma_f32_16x16x32_bf16 v[20:23], v[28:31], v[216:219], v[20:23]
	v_mfma_f32_16x16x32_bf16 v[28:31], v[174:177], v[212:215], v[128:131]
	v_mfma_f32_16x16x32_bf16 v[28:31], v[184:187], v[216:219], v[28:31]
	s_barrier
	s_setprio 0
	s_add_u32 s60, s26, 0x158000
	s_addc_u32 s61, s27, 0
	s_add_i32 s59, s45, s33
	s_mov_b32 m0, s59
	s_nop 0
	global_load_lds_dwordx4 v138, s[60:61]
	s_add_i32 m0, s59, 0x2000
	s_nop 0
	global_load_lds_dwordx4 v142, s[60:61]
	s_waitcnt vmcnt(6)
	s_setprio 1
	s_barrier
; #define PG8_STAGE(bufoff, gbase, voff) do { _Pragma("unroll") for (int _i = 0; _i < 2; ++_i) \
;         __builtin_amdgcn_global_load_lds((const unsigned*)((const char*)(gbase) + (voff)[_i]), (LAS unsigned*)(lds + (bufoff) + ldsw + _i * 8192), 16, 0, 0); } while (0)
; #define PG8_LDA(dst, b, h) do { _Pragma("unroll") for (int m = 0; m < 4; ++m) _Pragma("unroll") for (int k = 0; k < 2; ++k) dst[m][k] = *(const LAS bf16x8*)(lds + PG8_SA(b, h) + aoff + m * 2048 + k * 1024); } while (0)
; #define PG8_LDB(dst, b, h) do { _Pragma("unroll") for (int n = 0; n < 2; ++n) _Pragma("unroll") for (int k = 0; k < 2; ++k) dst[n][k] = *(const LAS bf16x8*)(lds + PG8_SB(b, h) + boff + n * 2048 + k * 1024); } while (0)
; #define PG8_MMA(ai, bj, At, Bt) do { __builtin_amdgcn_s_setprio(1); _Pragma("unroll") for (int m = 0; m < 4; ++m) _Pragma("unroll") for (int n = 0; n < 2; ++n) _Pragma("unroll") for (int k = 0; k < 2; ++k) \
;         acc[ai][bj][m][n] = __builtin_amdgcn_mfma_f32_16x16x32_bf16(Bt[n][k], At[m][k], acc[ai][bj][m][n], 0, 0, 0); __builtin_amdgcn_s_setprio(0); } while (0)
; #define PG8_WAIT_V(n) asm volatile("s_waitcnt vmcnt(" #n ")" ::: "memory")
; #define PG8_WAIT_L(n) asm volatile("s_waitcnt lgkmcnt(" #n ")" ::: "memory")
; #define PG8_BAR __builtin_amdgcn_s_barrier()
; #define PG8_SCHED __builtin_amdgcn_sched_barrier(0)
; template <class Epi, class Sched, bool ATILE = false>
; __device__ __forceinline__ void gemm_phase(LAS unsigned char* lds, const Gemm g, const Sched& S, const Epi& E) {
;     ...
;             PG8_WAIT_V(6); PG8_BAR; PG8_MMA(1, 1, At, B1); PG8_BAR;
;             PG8_LDB(B0, 1, 0); PG8_SCHED; PG8_LDA(At, 1, 0); PG8_STAGE(PG8_SA(0, 1), a2 + hstepA, voffA);
;             PG8_WAIT_L(8); PG8_BAR; PG8_WAIT_L(0); PG8_MMA(0, 0, At, B0); PG8_BAR; PG8_SCHED;
;             PG8_LDB(B1, 1, 1); PG8_STAGE(PG8_SB(1, 0), b3, voffB);
;             PG8_BAR; PG8_WAIT_L(0); PG8_MMA(0, 1, At, B1); PG8_BAR;
;             PG8_LDA(At, 1, 1); PG8_STAGE(PG8_SA(1, 0), a3, voffA);
	v_mfma_f32_16x16x32_bf16 v[76:79], v[220:223], v[188:191], v[76:79]
	v_mfma_f32_16x16x32_bf16 v[72:75], v[228:231], v[188:191], v[72:75]
	v_mfma_f32_16x16x32_bf16 v[88:91], v[220:223], v[196:199], v[88:91]
	v_mfma_f32_16x16x32_bf16 v[80:83], v[228:231], v[196:199], v[80:83]
	v_mfma_f32_16x16x32_bf16 v[104:107], v[220:223], v[204:207], v[104:107]
	v_mfma_f32_16x16x32_bf16 v[96:99], v[228:231], v[204:207], v[96:99]
	v_mfma_f32_16x16x32_bf16 v[120:123], v[220:223], v[212:215], v[120:123]
	v_mfma_f32_16x16x32_bf16 v[124:127], v[228:231], v[212:215], v[124:127]
	v_mfma_f32_16x16x32_bf16 v[76:79], v[224:227], v[192:195], v[76:79]
	v_mfma_f32_16x16x32_bf16 v[72:75], v[232:235], v[192:195], v[72:75]
	v_mfma_f32_16x16x32_bf16 v[88:91], v[224:227], v[200:203], v[88:91]
	v_mfma_f32_16x16x32_bf16 v[80:83], v[232:235], v[200:203], v[80:83]
	v_mfma_f32_16x16x32_bf16 v[104:107], v[224:227], v[208:211], v[104:107]
	v_mfma_f32_16x16x32_bf16 v[96:99], v[232:235], v[208:211], v[96:99]
	v_mfma_f32_16x16x32_bf16 v[120:123], v[224:227], v[216:219], v[120:123]
	v_mfma_f32_16x16x32_bf16 v[124:127], v[232:235], v[216:219], v[124:127]
	s_barrier
	s_setprio 0
	s_add_i32 s59, 0, 0x18000
	v_add_u32_e32 v183, s59, v157
	ds_read_b128 v[128:131], v183
	ds_read_b128 v[132:135], v183 offset:1024
	ds_read_b128 v[174:177], v183 offset:2048
	ds_read_b128 v[184:187], v183 offset:3072
	s_add_u32 s30, s30, 0x4000
	s_addc_u32 s31, s31, 0
	s_mov_b32 m0, s36
	ds_read_b128 v[188:191], v181 offset:32768
	ds_read_b128 v[192:195], v181 offset:33792
	ds_read_b128 v[196:199], v181 offset:34816
	ds_read_b128 v[200:203], v181 offset:35840
	ds_read_b128 v[204:207], v181 offset:36864
	ds_read_b128 v[208:211], v181 offset:37888
	ds_read_b128 v[212:215], v181 offset:38912
	ds_read_b128 v[216:219], v181 offset:39936
	global_load_lds_dwordx4 v136, s[30:31]
	s_mov_b32 m0, s37
	s_nop 0
	global_load_lds_dwordx4 v140, s[30:31]
	s_waitcnt lgkmcnt(8)
	s_setprio 1
	s_barrier
	s_waitcnt lgkmcnt(0)
	v_mfma_f32_16x16x32_bf16 v[0:3], v[128:131], v[188:191], v[0:3]
	v_mfma_f32_16x16x32_bf16 v[4:7], v[174:177], v[188:191], v[4:7]
	v_mfma_f32_16x16x32_bf16 v[44:47], v[128:131], v[196:199], v[44:47]
	v_mfma_f32_16x16x32_bf16 v[36:39], v[174:177], v[196:199], v[36:39]
	v_mfma_f32_16x16x32_bf16 v[52:55], v[128:131], v[204:207], v[52:55]
	v_mfma_f32_16x16x32_bf16 v[48:51], v[174:177], v[204:207], v[48:51]
	v_mfma_f32_16x16x32_bf16 v[92:95], v[128:131], v[212:215], v[92:95]
	v_mfma_f32_16x16x32_bf16 v[84:87], v[174:177], v[212:215], v[84:87]
	v_mfma_f32_16x16x32_bf16 v[0:3], v[132:135], v[192:195], v[0:3]
	v_mfma_f32_16x16x32_bf16 v[4:7], v[184:187], v[192:195], v[4:7]
	v_mfma_f32_16x16x32_bf16 v[44:47], v[132:135], v[200:203], v[44:47]
	v_mfma_f32_16x16x32_bf16 v[36:39], v[184:187], v[200:203], v[36:39]
	v_mfma_f32_16x16x32_bf16 v[52:55], v[132:135], v[208:211], v[52:55]
	v_mfma_f32_16x16x32_bf16 v[48:51], v[184:187], v[208:211], v[48:51]
	v_mfma_f32_16x16x32_bf16 v[92:95], v[132:135], v[216:219], v[92:95]
	v_mfma_f32_16x16x32_bf16 v[84:87], v[184:187], v[216:219], v[84:87]
	s_barrier
	s_setprio 0
	s_add_i32 s30, 0, 0x1c000
	s_add_i32 s31, s59, s33
	v_add_u32_e32 v183, s30, v157
	s_mov_b32 m0, s31
	ds_read_b128 v[220:223], v183
	ds_read_b128 v[224:227], v183 offset:1024
	ds_read_b128 v[228:231], v183 offset:2048
	ds_read_b128 v[232:235], v183 offset:3072
	global_load_lds_dwordx4 v138, s[98:99]
	s_add_i32 m0, s31, 0x2000
	s_nop 0
	global_load_lds_dwordx4 v142, s[98:99]
	s_setprio 1
	s_barrier
	s_waitcnt lgkmcnt(0)
	v_mfma_f32_16x16x32_bf16 v[12:15], v[220:223], v[188:191], v[12:15]
	v_mfma_f32_16x16x32_bf16 v[8:11], v[228:231], v[188:191], v[8:11]
	v_mfma_f32_16x16x32_bf16 v[24:27], v[220:223], v[196:199], v[24:27]
	v_mfma_f32_16x16x32_bf16 v[16:19], v[228:231], v[196:199], v[16:19]
	v_mfma_f32_16x16x32_bf16 v[40:43], v[220:223], v[204:207], v[40:43]
	v_mfma_f32_16x16x32_bf16 v[32:35], v[228:231], v[204:207], v[32:35]
	v_mfma_f32_16x16x32_bf16 v[56:59], v[220:223], v[212:215], v[56:59]
	v_mfma_f32_16x16x32_bf16 v[60:63], v[228:231], v[212:215], v[60:63]
	v_mfma_f32_16x16x32_bf16 v[12:15], v[224:227], v[192:195], v[12:15]
	v_mfma_f32_16x16x32_bf16 v[8:11], v[232:235], v[192:195], v[8:11]
	v_mfma_f32_16x16x32_bf16 v[24:27], v[224:227], v[200:203], v[24:27]
	v_mfma_f32_16x16x32_bf16 v[16:19], v[232:235], v[200:203], v[16:19]
	v_mfma_f32_16x16x32_bf16 v[40:43], v[224:227], v[208:211], v[40:43]
	v_mfma_f32_16x16x32_bf16 v[32:35], v[232:235], v[208:211], v[32:35]
	v_mfma_f32_16x16x32_bf16 v[56:59], v[224:227], v[216:219], v[56:59]
	v_mfma_f32_16x16x32_bf16 v[60:63], v[232:235], v[216:219], v[60:63]
	s_barrier
	s_setprio 0
	s_mov_b32 m0, s39
	ds_read_b128 v[188:191], v181 offset:49152
	ds_read_b128 v[192:195], v181 offset:50176
	ds_read_b128 v[196:199], v181 offset:51200
	ds_read_b128 v[200:203], v181 offset:52224
	ds_read_b128 v[204:207], v181 offset:53248
	ds_read_b128 v[208:211], v181 offset:54272
	ds_read_b128 v[212:215], v181 offset:55296
	ds_read_b128 v[216:219], v181 offset:56320
	global_load_lds_dwordx4 v136, s[28:29]
	s_mov_b32 m0, s40
	s_nop 0
	global_load_lds_dwordx4 v140, s[28:29]
	s_setprio 1
	s_barrier
; __device__ __forceinline__ float bflo(unsigned w) { return __uint_as_float(w << 16); }
; __device__ __forceinline__ float bfhi(unsigned w) { return __uint_as_float(w & 0xffff0000u); }
; #define PG8_STAGE(bufoff, gbase, voff) do { _Pragma("unroll") for (int _i = 0; _i < 2; ++_i) \
;         __builtin_amdgcn_global_load_lds((const unsigned*)((const char*)(gbase) + (voff)[_i]), (LAS unsigned*)(lds + (bufoff) + ldsw + _i * 8192), 16, 0, 0); } while (0)
; #define PG8_LDA(dst, b, h) do { _Pragma("unroll") for (int m = 0; m < 4; ++m) _Pragma("unroll") for (int k = 0; k < 2; ++k) dst[m][k] = *(const LAS bf16x8*)(lds + PG8_SA(b, h) + aoff + m * 2048 + k * 1024); } while (0)
; #define PG8_MMA(ai, bj, At, Bt) do { __builtin_amdgcn_s_setprio(1); _Pragma("unroll") for (int m = 0; m < 4; ++m) _Pragma("unroll") for (int n = 0; n < 2; ++n) _Pragma("unroll") for (int k = 0; k < 2; ++k) \
;         acc[ai][bj][m][n] = __builtin_amdgcn_mfma_f32_16x16x32_bf16(Bt[n][k], At[m][k], acc[ai][bj][m][n], 0, 0, 0); __builtin_amdgcn_s_setprio(0); } while (0)
; #define PG8_WAIT_V(n) asm volatile("s_waitcnt vmcnt(" #n ")" ::: "memory")
; #define PG8_WAIT_L(n) asm volatile("s_waitcnt lgkmcnt(" #n ")" ::: "memory")
; #define PG8_BAR __builtin_amdgcn_s_barrier()
; #define PG8_SCHED __builtin_amdgcn_sched_barrier(0)
; template <class Epi, class Sched, bool ATILE = false>
; __device__ __forceinline__ void gemm_phase(LAS unsigned char* lds, const Gemm g, const Sched& S, const Epi& E) {
;     ...
;             PG8_LDA(At, 1, 1); PG8_STAGE(PG8_SA(1, 0), a3, voffA);
;             PG8_BAR; PG8_WAIT_L(0); PG8_MMA(1, 0, At, B0); PG8_BAR; PG8_SCHED;
;             PG8_STAGE(PG8_SB(1, 1), b3 + hstepB, voffB);
;             PG8_WAIT_V(6); PG8_BAR; PG8_MMA(1, 1, At, B1); PG8_BAR;
;         }
;     __device__ __forceinline__ void operator()(const f32x4 (&acc)[2][2][4][2], const Unit& u, int wr, int wc, int fr, int fq) const {
;     ...
;                     const f32x4 v0 = (f32x4){bflo(x.x), bfhi(x.x), bflo(x.y), bfhi(x.y)} + alpha * acc[ai][bj][m][0];
;                     const f32x4 v1 = (f32x4){bflo(x.z), bfhi(x.z), bflo(x.w), bfhi(x.w)} + alpha * acc[ai][bj][m][1];
	s_waitcnt lgkmcnt(0)
	v_mfma_f32_16x16x32_bf16 v[64:67], v[128:131], v[188:191], v[64:67]
	v_mfma_f32_16x16x32_bf16 v[108:111], v[128:131], v[196:199], v[108:111]
	v_mfma_f32_16x16x32_bf16 v[116:119], v[128:131], v[204:207], v[116:119]
	v_mfma_f32_16x16x32_bf16 v[20:23], v[128:131], v[212:215], v[20:23]
	v_mfma_f32_16x16x32_bf16 v[64:67], v[132:135], v[192:195], v[64:67]
	v_mfma_f32_16x16x32_bf16 v[68:71], v[174:177], v[188:191], v[68:71]
	v_mfma_f32_16x16x32_bf16 v[108:111], v[132:135], v[200:203], v[108:111]
	v_mfma_f32_16x16x32_bf16 v[100:103], v[174:177], v[196:199], v[100:103]
	v_mfma_f32_16x16x32_bf16 v[116:119], v[132:135], v[208:211], v[116:119]
	v_mfma_f32_16x16x32_bf16 v[112:115], v[174:177], v[204:207], v[112:115]
	v_mfma_f32_16x16x32_bf16 v[132:135], v[132:135], v[216:219], v[20:23]
	v_mfma_f32_16x16x32_bf16 v[20:23], v[174:177], v[212:215], v[28:31]
	v_mfma_f32_16x16x32_bf16 v[68:71], v[184:187], v[192:195], v[68:71]
	v_mfma_f32_16x16x32_bf16 v[100:103], v[184:187], v[200:203], v[100:103]
	v_mfma_f32_16x16x32_bf16 v[112:115], v[184:187], v[208:211], v[112:115]
	v_mfma_f32_16x16x32_bf16 v[128:131], v[184:187], v[216:219], v[20:23]
	s_barrier
	s_setprio 0
	s_add_u32 s26, s26, 0x158080
	s_addc_u32 s27, s27, 0
	s_add_i32 s28, s30, s33
	s_mov_b32 m0, s28
	s_nop 0
	global_load_lds_dwordx4 v138, s[26:27]
	s_add_i32 m0, s28, 0x2000
	s_nop 0
	global_load_lds_dwordx4 v142, s[26:27]
	s_waitcnt vmcnt(6)
	s_setprio 1
	s_barrier
	v_mfma_f32_16x16x32_bf16 v[20:23], v[220:223], v[188:191], v[76:79]
	v_mfma_f32_16x16x32_bf16 v[76:79], v[224:227], v[192:195], v[20:23]
	v_mfma_f32_16x16x32_bf16 v[20:23], v[228:231], v[188:191], v[72:75]
	v_mfma_f32_16x16x32_bf16 v[72:75], v[232:235], v[192:195], v[20:23]
	v_mfma_f32_16x16x32_bf16 v[20:23], v[220:223], v[196:199], v[88:91]
	v_mfma_f32_16x16x32_bf16 v[88:91], v[224:227], v[200:203], v[20:23]
	v_mfma_f32_16x16x32_bf16 v[20:23], v[228:231], v[196:199], v[80:83]
	s_add_u32 s56, s56, 0x100
	v_mfma_f32_16x16x32_bf16 v[80:83], v[232:235], v[200:203], v[20:23]
	s_addc_u32 s57, s57, 0
	v_mfma_f32_16x16x32_bf16 v[20:23], v[220:223], v[204:207], v[104:107]
	s_add_u32 s24, s24, 0x10000
	v_mfma_f32_16x16x32_bf16 v[104:107], v[224:227], v[208:211], v[20:23]
	s_addc_u32 s25, s25, 0
	v_mfma_f32_16x16x32_bf16 v[20:23], v[228:231], v[204:207], v[96:99]
	s_cmp_ge_i32 s58, s55
	v_mfma_f32_16x16x32_bf16 v[96:99], v[232:235], v[208:211], v[20:23]
	s_mov_b32 s26, s58
	v_mfma_f32_16x16x32_bf16 v[20:23], v[220:223], v[212:215], v[120:123]
	v_mfma_f32_16x16x32_bf16 v[120:123], v[224:227], v[216:219], v[20:23]
	v_mfma_f32_16x16x32_bf16 v[20:23], v[228:231], v[212:215], v[124:127]
	v_mfma_f32_16x16x32_bf16 v[124:127], v[232:235], v[216:219], v[20:23]
	s_barrier
	s_setprio 0
	s_cbranch_scc0 .LBB0_1898
	s_nop 5
	v_pk_mul_f32 v[2:3], v[2:3], 0.5 op_sel_hi:[1,0]
	v_pk_mul_f32 v[0:1], v[0:1], 0.5 op_sel_hi:[1,0]
	v_pk_mul_f32 v[6:7], v[6:7], 0.5 op_sel_hi:[1,0]
	v_pk_mul_f32 v[4:5], v[4:5], 0.5 op_sel_hi:[1,0]
	v_pk_mul_f32 v[22:23], v[14:15], 0.5 op_sel_hi:[1,0]
	v_pk_mul_f32 v[20:21], v[12:13], 0.5 op_sel_hi:[1,0]
	v_pk_mul_f32 v[30:31], v[10:11], 0.5 op_sel_hi:[1,0]
	v_pk_mul_f32 v[28:29], v[8:9], 0.5 op_sel_hi:[1,0]
	v_pk_mul_f32 v[10:11], v[46:47], 0.5 op_sel_hi:[1,0]
	v_pk_mul_f32 v[8:9], v[44:45], 0.5 op_sel_hi:[1,0]
	v_pk_mul_f32 v[14:15], v[38:39], 0.5 op_sel_hi:[1,0]
	v_pk_mul_f32 v[12:13], v[36:37], 0.5 op_sel_hi:[1,0]
	v_pk_mul_f32 v[38:39], v[26:27], 0.5 op_sel_hi:[1,0]
	v_pk_mul_f32 v[36:37], v[24:25], 0.5 op_sel_hi:[1,0]
	v_pk_mul_f32 v[46:47], v[18:19], 0.5 op_sel_hi:[1,0]
	v_pk_mul_f32 v[44:45], v[16:17], 0.5 op_sel_hi:[1,0]
	v_pk_mul_f32 v[18:19], v[54:55], 0.5 op_sel_hi:[1,0]
	v_pk_mul_f32 v[16:17], v[52:53], 0.5 op_sel_hi:[1,0]
	v_pk_mul_f32 v[26:27], v[50:51], 0.5 op_sel_hi:[1,0]
	v_pk_mul_f32 v[24:25], v[48:49], 0.5 op_sel_hi:[1,0]
	v_pk_mul_f32 v[50:51], v[42:43], 0.5 op_sel_hi:[1,0]
	v_pk_mul_f32 v[48:49], v[40:41], 0.5 op_sel_hi:[1,0]
	v_pk_mul_f32 v[54:55], v[34:35], 0.5 op_sel_hi:[1,0]
	v_pk_mul_f32 v[52:53], v[32:33], 0.5 op_sel_hi:[1,0]
	v_pk_mul_f32 v[34:35], v[94:95], 0.5 op_sel_hi:[1,0]
	v_pk_mul_f32 v[32:33], v[92:93], 0.5 op_sel_hi:[1,0]
	v_pk_mul_f32 v[42:43], v[86:87], 0.5 op_sel_hi:[1,0]
	v_pk_mul_f32 v[40:41], v[84:85], 0.5 op_sel_hi:[1,0]
	v_pk_mul_f32 v[58:59], v[58:59], 0.5 op_sel_hi:[1,0]
	v_pk_mul_f32 v[56:57], v[56:57], 0.5 op_sel_hi:[1,0]
	v_pk_mul_f32 v[62:63], v[62:63], 0.5 op_sel_hi:[1,0]
	v_pk_mul_f32 v[60:61], v[60:61], 0.5 op_sel_hi:[1,0]
	v_pk_mul_f32 v[66:67], v[66:67], 0.5 op_sel_hi:[1,0]
	v_pk_mul_f32 v[64:65], v[64:65], 0.5 op_sel_hi:[1,0]
	v_pk_mul_f32 v[70:71], v[70:71], 0.5 op_sel_hi:[1,0]
	v_pk_mul_f32 v[68:69], v[68:69], 0.5 op_sel_hi:[1,0]
	v_pk_mul_f32 v[86:87], v[78:79], 0.5 op_sel_hi:[1,0]
	v_pk_mul_f32 v[84:85], v[76:77], 0.5 op_sel_hi:[1,0]
	v_pk_mul_f32 v[94:95], v[74:75], 0.5 op_sel_hi:[1,0]
	v_pk_mul_f32 v[92:93], v[72:73], 0.5 op_sel_hi:[1,0]
	v_pk_mul_f32 v[74:75], v[110:111], 0.5 op_sel_hi:[1,0]
	v_pk_mul_f32 v[72:73], v[108:109], 0.5 op_sel_hi:[1,0]
	v_pk_mul_f32 v[78:79], v[102:103], 0.5 op_sel_hi:[1,0]
	v_pk_mul_f32 v[76:77], v[100:101], 0.5 op_sel_hi:[1,0]
	v_pk_mul_f32 v[102:103], v[90:91], 0.5 op_sel_hi:[1,0]
	v_pk_mul_f32 v[100:101], v[88:89], 0.5 op_sel_hi:[1,0]
	v_pk_mul_f32 v[110:111], v[82:83], 0.5 op_sel_hi:[1,0]
	v_pk_mul_f32 v[108:109], v[80:81], 0.5 op_sel_hi:[1,0]
	v_pk_mul_f32 v[82:83], v[118:119], 0.5 op_sel_hi:[1,0]
	v_pk_mul_f32 v[80:81], v[116:117], 0.5 op_sel_hi:[1,0]
	v_pk_mul_f32 v[90:91], v[114:115], 0.5 op_sel_hi:[1,0]
	v_pk_mul_f32 v[88:89], v[112:113], 0.5 op_sel_hi:[1,0]
	v_pk_mul_f32 v[114:115], v[106:107], 0.5 op_sel_hi:[1,0]
	v_pk_mul_f32 v[112:113], v[104:105], 0.5 op_sel_hi:[1,0]
	v_pk_mul_f32 v[118:119], v[98:99], 0.5 op_sel_hi:[1,0]
	v_pk_mul_f32 v[116:117], v[96:97], 0.5 op_sel_hi:[1,0]
	v_pk_mul_f32 v[98:99], v[134:135], 0.5 op_sel_hi:[1,0]
	v_pk_mul_f32 v[96:97], v[132:133], 0.5 op_sel_hi:[1,0]
	v_pk_mul_f32 v[106:107], v[130:131], 0.5 op_sel_hi:[1,0]
	v_pk_mul_f32 v[104:105], v[128:129], 0.5 op_sel_hi:[1,0]
	v_pk_mul_f32 v[122:123], v[122:123], 0.5 op_sel_hi:[1,0]
	v_pk_mul_f32 v[120:121], v[120:121], 0.5 op_sel_hi:[1,0]
	v_pk_mul_f32 v[126:127], v[126:127], 0.5 op_sel_hi:[1,0]
	v_pk_mul_f32 v[124:125], v[124:125], 0.5 op_sel_hi:[1,0]
	s_branch .LBB0_1903
